# GEMM1 main loop and GEMM3: operand staging through LDS-DMA (global_load_lds_dwordx4, depth 1) instead of register staging + ds_write
# speedup vs baseline: 1.0024x; 1.0008x over previous
; template <int MODE>
; __device__ __forceinline__ void gemm_tile(const Params& P, int tm, int tn, unsigned char* smem) {
;     ...
;     unsigned aoff, boff; int soff0;
;     {
;         int ar = m0 + srow;
;         if (MODE == 2) { const int b = ar >> 11, t = ar & 2047; ar = b * L + NMETA + t; }
;         aoff = (unsigned)ar * LDA + (unsigned)sc * 16u;
;         boff = (unsigned)(n0 + srow) * 2048u + (unsigned)sc * 16u;
;         soff0 = srow * 128 + ((sc ^ (srow & 7)) << 4);
;     }
;     const unsigned char* Ab = (const unsigned char*)A; const unsigned char* Bb = (const unsigned char*)Bt;
;     float4 ssp0, ssp1, ssp2, ssp3;
;     if (MODE == 3) {
;         const float* ssq = (const float*)(P.ws + WS_SSQ) + (size_t)(m0 + wr * 64 + lr) * 16 + 4 * g;
;         ssp0 = *(const float4*)(ssq); ssp1 = *(const float4*)(ssq + 16 * 16); ssp2 = *(const float4*)(ssq + 32 * 16); ssp3 = *(const float4*)(ssq + 48 * 16);
;     }
;     f32x4 acc[4][4];
; #pragma unroll
;     for (int i = 0; i < 4; ++i)
; #pragma unroll
;         for (int j = 0; j < 4; ++j) acc[i][j] = (f32x4){0.f, 0.f, 0.f, 0.f};
;     uint4 ra0, ra1, ra2, ra3, rb0, rb1, rb2, rb3;
;     ...
;     unsigned char* sA0 = smem; unsigned char* sB0 = smem + 16384; unsigned char* sA1 = smem + 32768; unsigned char* sB1 = smem + 49152;
;     G_LOAD(0)
;     G_WRITE(sA0, sB0)
;     __syncthreads();
;     const int arow_off = (wr * 64 + lr) * 128, brow_off = (wc * 64 + lr) * 128, sw = lr & 7;
;     G_LOAD(1)
;     for (int kt = 0; kt < 16; ++kt) {
;         unsigned char* sA = (kt & 1) ? sA1 : sA0; unsigned char* sB = (kt & 1) ? sB1 : sB0;
;         unsigned char* nA = (kt & 1) ? sA0 : sA1; unsigned char* nB = (kt & 1) ? sB0 : sB1;
;         bf16x8 fa[4], fb[4], ga[4], gb[4];
;         const int ch0 = ((g ^ sw) << 4), ch1 = (((4 + g) ^ sw) << 4);
;         const unsigned ko = (unsigned)(kt + 2) * 128u;
;         const unsigned koa = ko + ((MODE == 2 && kt + 2 >= 8) ? (unsigned)(ZC_FQ - 512) * 2u : 0u);
;         const bool wr_ok = kt < 15, ld_ok = kt < 14;
; #pragma unroll
;         for (int i = 0; i < 4; ++i) { fa[i] = *(const bf16x8*)(sA + arow_off + i * 2048 + ch0); fb[i] = *(const bf16x8*)(sB + brow_off + i * 2048 + ch0); }
;         __builtin_amdgcn_sched_barrier(0);
;         __builtin_amdgcn_s_setprio(2);
;         if (wr_ok) *(uint4*)(nA + soff0) = ra0;
;         if (ld_ok) ra0 = *(const uint4*)(Ab + (aoff + 0u * LDA + koa));
.LBB0_182:
	s_mul_hi_i32 s0, s35, 0x92492493
	s_add_i32 s0, s0, s35
	s_lshr_b32 s1, s0, 31
	s_ashr_i32 s0, s0, 7
	s_add_i32 s1, s0, s1
	s_mul_i32 s0, s1, 0xffffff20
	s_lshl_b32 s10, s1, 3
	s_add_i32 s0, s35, s0
	s_sub_i32 s10, 0x81, s10
	s_cmpk_gt_i32 s35, 0xdff
	s_cselect_b32 s10, s10, 8
	s_abs_i32 s11, s10
	v_cvt_f32_u32_e32 v2, s11
	s_ashr_i32 s0, s0, 31
	s_mul_i32 s13, s1, 0xe0
	s_sub_i32 s13, s0, s13
	v_rcp_iflag_f32_e32 v2, v2
	s_ashr_i32 s12, s10, 31
	s_add_i32 s13, s35, s13
	s_xor_b32 s12, s0, s12
	v_mul_f32_e32 v2, 0x4f7ffffe, v2
	v_cvt_u32_f32_e32 v2, v2
	s_xor_b32 s0, s13, s0
	s_sub_i32 s13, 0, s11
	s_mulk_i32 s1, 0xd8
	v_readfirstlane_b32 s42, v2
	s_mul_i32 s13, s13, s42
	s_mul_hi_u32 s13, s42, s13
	s_add_i32 s42, s42, s13
	s_mul_hi_u32 s13, s0, s42
	s_mul_i32 s42, s13, s11
	s_sub_i32 s0, s0, s42
	s_add_i32 s42, s13, 1
	s_sub_i32 s43, s0, s11
	s_cmp_ge_u32 s0, s11
	s_cselect_b32 s13, s42, s13
	s_cselect_b32 s0, s43, s0
	s_add_i32 s42, s13, 1
	s_cmp_ge_u32 s0, s11
	s_cselect_b32 s0, s42, s13
	s_xor_b32 s0, s0, s12
	s_sub_i32 s0, s0, s12
	s_mul_i32 s10, s10, s0
	s_add_i32 s10, s10, s1
	s_sub_i32 s1, s35, s10
	v_mov_b32_e32 v79, v0
	s_lshl_b32 s42, s1, 7
	v_ashrrev_i32_e32 v2, 3, v79
	v_lshlrev_b32_e32 v4, 4, v79
	s_lshl_b32 s10, s0, 7
	v_add_u32_e32 v3, s42, v2
	v_and_b32_e32 v4, 0x70, v4
	v_add_u32_e32 v5, s10, v2
	v_lshl_or_b32 v8, v3, 11, v4
	v_lshl_or_b32 v5, v5, 11, v4
	v_add_u32_e32 v3, 0x10000, v8
	v_add_u32_e32 v4, 0x20000, v8
	v_lshlrev_b32_e32 v248, 1, v0
	v_lshrrev_b32_e32 v249, 6, v0
	v_and_b32_e32 v248, 0x70, v248
	v_readfirstlane_b32 s96, v249
	v_xor_b32_e32 v240, v8, v248
	v_xor_b32_e32 v244, v5, v248
	s_lshl_b32 s96, s96, 10
	v_add_u32_e32 v241, 0x10000, v240
	v_add_u32_e32 v242, 0x20000, v240
	v_add_u32_e32 v243, 0x30000, v240
	v_add_u32_e32 v245, 0x10000, v244
	v_add_u32_e32 v246, 0x20000, v244
	v_add_u32_e32 v247, 0x30000, v244
	s_mov_b64 s[92:93], s[36:37]
	s_mov_b64 s[94:95], s[4:5]
	s_mov_b32 m0, s96
	s_nop 0
	global_load_lds_dwordx4 v240, s[92:93]
	s_add_u32 m0, s96, 0x1000
	s_nop 0
	global_load_lds_dwordx4 v241, s[92:93]
	s_add_u32 m0, s96, 0x2000
	s_nop 0
	global_load_lds_dwordx4 v242, s[92:93]
	s_add_u32 m0, s96, 0x3000
	s_nop 0
	global_load_lds_dwordx4 v243, s[92:93]
	s_add_u32 m0, s96, 0x4000
	s_nop 0
	global_load_lds_dwordx4 v244, s[94:95]
	s_add_u32 m0, s96, 0x5000
	s_nop 0
	global_load_lds_dwordx4 v245, s[94:95]
	s_add_u32 m0, s96, 0x6000
	s_nop 0
	global_load_lds_dwordx4 v246, s[94:95]
	s_add_u32 m0, s96, 0x7000
	s_nop 0
	global_load_lds_dwordx4 v247, s[94:95]
	v_add_u32_e32 v3, 0x20000, v5
	v_add_u32_e32 v4, 0x30000, v5
	v_add_u32_e32 v3, 0x30000, v8
	v_add_u32_e32 v4, 0x10000, v5
	v_xor_b32_e32 v3, v2, v79
	v_lshlrev_b32_e32 v2, 7, v2
	v_lshlrev_b32_e32 v3, 4, v3
	v_and_or_b32 v2, v3, s20, v2
	v_add_u32_e32 v2, 0, v2
	v_or_b32_e32 v9, 0x80, v8
	v_or_b32_e32 v3, 0x80, v5
	v_add_u32_e32 v4, 0x10080, v5
	v_add_u32_e32 v6, 0x20080, v5
	v_add_u32_e32 v7, 0x30080, v5
	v_add_u32_e32 v42, 0x10080, v8
	v_add_u32_e32 v43, 0x20080, v8
	v_add_u32_e32 v44, 0x30080, v8
	v_and_b32_e32 v80, 15, v79
	v_ashrrev_i32_e32 v81, 7, v79
	v_bfe_u32 v82, v79, 6, 1
	v_bfe_u32 v83, v79, 4, 2
	s_waitcnt vmcnt(0) lgkmcnt(0)
	s_barrier
	v_lshrrev_b32_e32 v3, 4, v79
	v_lshlrev_b32_e32 v4, 7, v80
	v_and_b32_e32 v9, 7, v79
	v_lshl_or_b32 v6, v81, 13, v4
	v_bitop3_b32 v3, v3, v9, 3 bitop3:0x6c
	v_lshl_or_b32 v4, v82, 13, v4
	v_lshlrev_b32_e32 v3, 4, v3
	v_add_u32_e32 v66, 0, v6
	v_add_u32_e32 v6, v66, v3
	v_add_u32_e32 v4, 0, v4
	v_add_u32_e32 v7, v4, v3
	ds_read_b128 v[42:45], v6
	ds_read_b128 v[46:49], v6 offset:2048
	ds_read_b128 v[50:53], v7 offset:16384
	ds_read_b128 v[54:57], v7 offset:18432
	ds_read_b128 v[58:61], v6 offset:4096
	ds_read_b128 v[62:65], v6 offset:6144
	ds_read_b128 v[84:87], v7 offset:20480
	ds_read_b128 v[88:91], v7 offset:22528
	v_bitop3_b32 v3, v83, v9, 4 bitop3:0x36
	v_lshlrev_b32_e32 v9, 4, v3
	s_setprio 2
	s_add_u32 s92, s92, 0x80
	s_addc_u32 s93, s93, 0
	s_add_u32 s94, s94, 0x80
	s_addc_u32 s95, s95, 0
	s_add_u32 m0, s96, 0x8000
	v_add_u32_e32 v3, v66, v9
	global_load_lds_dwordx4 v240, s[92:93]
	s_add_u32 m0, s96, 0x9000
	v_add_u32_e32 v4, v4, v9
	global_load_lds_dwordx4 v241, s[92:93]
	s_add_u32 m0, s96, 0xa000
	ds_read_b128 v[10:13], v3
	global_load_lds_dwordx4 v242, s[92:93]
	s_add_u32 m0, s96, 0xb000
	ds_read_b128 v[96:99], v4 offset:16384
	global_load_lds_dwordx4 v243, s[92:93]
	s_add_u32 m0, s96, 0xc000
	s_waitcnt lgkmcnt(7)
	global_load_lds_dwordx4 v244, s[94:95]
	s_add_u32 m0, s96, 0xd000
	v_mfma_f32_16x16x32_bf16 v[100:103], v[50:53], v[42:45], 0
	global_load_lds_dwordx4 v245, s[94:95]
	s_add_u32 m0, s96, 0xe000
	s_waitcnt lgkmcnt(6)
	global_load_lds_dwordx4 v246, s[94:95]
	s_add_u32 m0, s96, 0xf000
	v_mfma_f32_16x16x32_bf16 v[104:107], v[54:57], v[42:45], 0
	global_load_lds_dwordx4 v247, s[94:95]
	s_waitcnt lgkmcnt(3)
	v_mfma_f32_16x16x32_bf16 v[108:111], v[84:87], v[42:45], 0
	s_waitcnt lgkmcnt(2)
	v_mfma_f32_16x16x32_bf16 v[42:45], v[88:91], v[42:45], 0
	ds_read_b128 v[14:17], v3 offset:2048
	ds_read_b128 v[116:119], v4 offset:18432
	v_mfma_f32_16x16x32_bf16 v[120:123], v[50:53], v[46:49], 0
	v_mfma_f32_16x16x32_bf16 v[124:127], v[54:57], v[46:49], 0
	v_mfma_f32_16x16x32_bf16 v[132:135], v[84:87], v[46:49], 0
	v_mfma_f32_16x16x32_bf16 v[46:49], v[88:91], v[46:49], 0
	ds_read_b128 v[18:21], v3 offset:4096
	ds_read_b128 v[150:153], v4 offset:20480
	v_mfma_f32_16x16x32_bf16 v[154:157], v[50:53], v[58:61], 0
	v_mfma_f32_16x16x32_bf16 v[158:161], v[54:57], v[58:61], 0
	v_mfma_f32_16x16x32_bf16 v[162:165], v[84:87], v[58:61], 0
	v_mfma_f32_16x16x32_bf16 v[58:61], v[88:91], v[58:61], 0
	ds_read_b128 v[22:25], v3 offset:6144
	ds_read_b128 v[170:173], v4 offset:22528
	v_mfma_f32_16x16x32_bf16 v[50:53], v[50:53], v[62:65], 0
	v_mfma_f32_16x16x32_bf16 v[54:57], v[54:57], v[62:65], 0
	v_mfma_f32_16x16x32_bf16 v[84:87], v[84:87], v[62:65], 0
	v_mfma_f32_16x16x32_bf16 v[62:65], v[88:91], v[62:65], 0
	s_waitcnt lgkmcnt(6)
; template <int MODE>
; __device__ __forceinline__ void gemm_tile(const Params& P, int tm, int tn, unsigned char* smem) {
;     ...
; #pragma unroll
;         for (int i = 0; i < 4; ++i) { fa[i] = *(const bf16x8*)(sA + arow_off + i * 2048 + ch0); fb[i] = *(const bf16x8*)(sB + brow_off + i * 2048 + ch0); }
;         __builtin_amdgcn_sched_barrier(0);
;         __builtin_amdgcn_s_setprio(2);
;         if (wr_ok) *(uint4*)(nA + soff0) = ra0;
;         if (ld_ok) ra0 = *(const uint4*)(Ab + (aoff + 0u * LDA + koa));
;         ga[0] = *(const bf16x8*)(sA + arow_off + 0 * 2048 + ch1); gb[0] = *(const bf16x8*)(sB + brow_off + 0 * 2048 + ch1);
;         __builtin_amdgcn_sched_barrier(0);
; #pragma unroll
;         for (int j = 0; j < 4; ++j) acc[0][j] = __builtin_amdgcn_mfma_f32_16x16x32_bf16(fb[j], fa[0], acc[0][j], 0, 0, 0);
;         __builtin_amdgcn_sched_barrier(0);
;         if (wr_ok) *(uint4*)(nA + soff0 + 4096) = ra1;
;         if (ld_ok) ra1 = *(const uint4*)(Ab + (aoff + 32u * LDA + koa));
;         ga[1] = *(const bf16x8*)(sA + arow_off + 1 * 2048 + ch1); gb[1] = *(const bf16x8*)(sB + brow_off + 1 * 2048 + ch1);
;         __builtin_amdgcn_sched_barrier(0);
; #pragma unroll
;         for (int j = 0; j < 4; ++j) acc[1][j] = __builtin_amdgcn_mfma_f32_16x16x32_bf16(fb[j], fa[1], acc[1][j], 0, 0, 0);
;         __builtin_amdgcn_sched_barrier(0);
;         if (wr_ok) *(uint4*)(nA + soff0 + 8192) = ra2;
;         if (ld_ok) ra2 = *(const uint4*)(Ab + (aoff + 64u * LDA + koa));
;         ga[2] = *(const bf16x8*)(sA + arow_off + 2 * 2048 + ch1); gb[2] = *(const bf16x8*)(sB + brow_off + 2 * 2048 + ch1);
;         __builtin_amdgcn_sched_barrier(0);
; #pragma unroll
;         for (int j = 0; j < 4; ++j) acc[2][j] = __builtin_amdgcn_mfma_f32_16x16x32_bf16(fb[j], fa[2], acc[2][j], 0, 0, 0);
;         __builtin_amdgcn_sched_barrier(0);
;         if (wr_ok) *(uint4*)(nA + soff0 + 12288) = ra3;
;         if (ld_ok) ra3 = *(const uint4*)(Ab + (aoff + 96u * LDA + koa));
;         ga[3] = *(const bf16x8*)(sA + arow_off + 3 * 2048 + ch1); gb[3] = *(const bf16x8*)(sB + brow_off + 3 * 2048 + ch1);
;         __builtin_amdgcn_sched_barrier(0);
; #pragma unroll
;         for (int j = 0; j < 4; ++j) acc[3][j] = __builtin_amdgcn_mfma_f32_16x16x32_bf16(fb[j], fa[3], acc[3][j], 0, 0, 0);
;         __builtin_amdgcn_sched_barrier(0);
;         if (wr_ok) *(uint4*)(nB + soff0) = rb0;
	v_mfma_f32_16x16x32_bf16 v[26:29], v[96:99], v[10:13], v[100:103]
	s_waitcnt lgkmcnt(4)
	v_mfma_f32_16x16x32_bf16 v[100:103], v[116:119], v[10:13], v[104:107]
	s_waitcnt lgkmcnt(2)
	v_mfma_f32_16x16x32_bf16 v[104:107], v[150:153], v[10:13], v[108:111]
	s_waitcnt lgkmcnt(0)
	v_mfma_f32_16x16x32_bf16 v[10:13], v[170:173], v[10:13], v[42:45]
	v_mfma_f32_16x16x32_bf16 v[30:33], v[96:99], v[14:17], v[120:123]
	v_mfma_f32_16x16x32_bf16 v[108:111], v[116:119], v[14:17], v[124:127]
	v_mfma_f32_16x16x32_bf16 v[120:123], v[150:153], v[14:17], v[132:135]
	v_mfma_f32_16x16x32_bf16 v[14:17], v[170:173], v[14:17], v[46:49]
	v_mfma_f32_16x16x32_bf16 v[34:37], v[96:99], v[18:21], v[154:157]
	v_mfma_f32_16x16x32_bf16 v[124:127], v[116:119], v[18:21], v[158:161]
	v_mfma_f32_16x16x32_bf16 v[132:135], v[150:153], v[18:21], v[162:165]
	v_mfma_f32_16x16x32_bf16 v[18:21], v[170:173], v[18:21], v[58:61]
	v_mfma_f32_16x16x32_bf16 v[38:41], v[96:99], v[22:25], v[50:53]
	v_mfma_f32_16x16x32_bf16 v[50:53], v[116:119], v[22:25], v[54:57]
	v_mfma_f32_16x16x32_bf16 v[54:57], v[150:153], v[22:25], v[84:87]
	v_mfma_f32_16x16x32_bf16 v[22:25], v[170:173], v[22:25], v[62:65]
	s_setprio 0
	s_waitcnt vmcnt(0) lgkmcnt(0)
	s_barrier
	ds_read_b128 v[62:65], v6 offset:32768
	ds_read_b128 v[84:87], v6 offset:34816
	ds_read_b128 v[96:99], v7 offset:49152
	ds_read_b128 v[116:119], v7 offset:51200
	ds_read_b128 v[150:153], v6 offset:36864
	ds_read_b128 v[154:157], v6 offset:38912
	ds_read_b128 v[158:161], v7 offset:53248
	ds_read_b128 v[162:165], v7 offset:55296
	s_setprio 2
	s_add_u32 s92, s92, 0x80
	s_addc_u32 s93, s93, 0
	s_add_u32 s94, s94, 0x80
	s_addc_u32 s95, s95, 0
	s_mov_b32 m0, s96
	ds_read_b128 v[92:95], v3 offset:32768
	global_load_lds_dwordx4 v240, s[92:93]
	s_add_u32 m0, s96, 0x1000
	ds_read_b128 v[174:177], v4 offset:49152
	global_load_lds_dwordx4 v241, s[92:93]
	s_add_u32 m0, s96, 0x2000
	s_waitcnt lgkmcnt(7)
	global_load_lds_dwordx4 v242, s[92:93]
	s_add_u32 m0, s96, 0x3000
	v_mfma_f32_16x16x32_bf16 v[26:29], v[96:99], v[62:65], v[26:29]
	global_load_lds_dwordx4 v243, s[92:93]
	s_add_u32 m0, s96, 0x4000
	s_waitcnt lgkmcnt(2)
	global_load_lds_dwordx4 v244, s[94:95]
	s_add_u32 m0, s96, 0x5000
	v_mfma_f32_16x16x32_bf16 v[10:13], v[162:165], v[62:65], v[10:13]
	global_load_lds_dwordx4 v245, s[94:95]
	s_add_u32 m0, s96, 0x6000
	v_mfma_f32_16x16x32_bf16 v[100:103], v[116:119], v[62:65], v[100:103]
	global_load_lds_dwordx4 v246, s[94:95]
	s_add_u32 m0, s96, 0x7000
	v_mfma_f32_16x16x32_bf16 v[104:107], v[158:161], v[62:65], v[104:107]
	global_load_lds_dwordx4 v247, s[94:95]
	v_mfma_f32_16x16x32_bf16 v[30:33], v[96:99], v[84:87], v[30:33]
	v_mfma_f32_16x16x32_bf16 v[14:17], v[162:165], v[84:87], v[14:17]
	ds_read_b128 v[112:115], v3 offset:34816
	v_mfma_f32_16x16x32_bf16 v[108:111], v[116:119], v[84:87], v[108:111]
	ds_read_b128 v[178:181], v4 offset:51200
	v_mfma_f32_16x16x32_bf16 v[120:123], v[158:161], v[84:87], v[120:123]
	v_mfma_f32_16x16x32_bf16 v[34:37], v[96:99], v[150:153], v[34:37]
	v_mfma_f32_16x16x32_bf16 v[18:21], v[162:165], v[150:153], v[18:21]
	ds_read_b128 v[146:149], v3 offset:36864
	v_mfma_f32_16x16x32_bf16 v[124:127], v[116:119], v[150:153], v[124:127]
	ds_read_b128 v[182:185], v4 offset:53248
	v_mfma_f32_16x16x32_bf16 v[132:135], v[158:161], v[150:153], v[132:135]
	v_mfma_f32_16x16x32_bf16 v[38:41], v[96:99], v[154:157], v[38:41]
	v_mfma_f32_16x16x32_bf16 v[50:53], v[116:119], v[154:157], v[50:53]
	ds_read_b128 v[166:169], v3 offset:38912
	v_mfma_f32_16x16x32_bf16 v[54:57], v[158:161], v[154:157], v[54:57]
	ds_read_b128 v[186:189], v4 offset:55296
	v_mfma_f32_16x16x32_bf16 v[22:25], v[162:165], v[154:157], v[22:25]
	s_waitcnt lgkmcnt(6)
	v_mfma_f32_16x16x32_bf16 v[26:29], v[174:177], v[92:95], v[26:29]
	s_waitcnt lgkmcnt(0)
	v_mfma_f32_16x16x32_bf16 v[10:13], v[186:189], v[92:95], v[10:13]
	v_mfma_f32_16x16x32_bf16 v[88:91], v[178:181], v[92:95], v[100:103]
	v_mfma_f32_16x16x32_bf16 v[100:103], v[182:185], v[92:95], v[104:107]
	v_mfma_f32_16x16x32_bf16 v[30:33], v[174:177], v[112:115], v[30:33]
	v_mfma_f32_16x16x32_bf16 v[42:45], v[178:181], v[112:115], v[108:111]
	v_mfma_f32_16x16x32_bf16 v[14:17], v[186:189], v[112:115], v[14:17]
	v_mfma_f32_16x16x32_bf16 v[104:107], v[182:185], v[112:115], v[120:123]
	v_mfma_f32_16x16x32_bf16 v[34:37], v[174:177], v[146:149], v[34:37]
	v_mfma_f32_16x16x32_bf16 v[46:49], v[178:181], v[146:149], v[124:127]
	v_mfma_f32_16x16x32_bf16 v[18:21], v[186:189], v[146:149], v[18:21]
	v_mfma_f32_16x16x32_bf16 v[112:115], v[182:185], v[146:149], v[132:135]
	v_mfma_f32_16x16x32_bf16 v[38:41], v[174:177], v[166:169], v[38:41]
	v_mfma_f32_16x16x32_bf16 v[50:53], v[178:181], v[166:169], v[50:53]
	v_mfma_f32_16x16x32_bf16 v[54:57], v[182:185], v[166:169], v[54:57]
	v_mfma_f32_16x16x32_bf16 v[22:25], v[186:189], v[166:169], v[22:25]
	s_setprio 0
	s_waitcnt vmcnt(0) lgkmcnt(0)
	s_barrier
; template <int MODE>
; __device__ __forceinline__ void gemm_tile(const Params& P, int tm, int tn, unsigned char* smem) {
;     ...
; #pragma unroll
;         for (int i = 0; i < 4; ++i) { fa[i] = *(const bf16x8*)(sA + arow_off + i * 2048 + ch0); fb[i] = *(const bf16x8*)(sB + brow_off + i * 2048 + ch0); }
;         __builtin_amdgcn_sched_barrier(0);
;         __builtin_amdgcn_s_setprio(2);
;         if (wr_ok) *(uint4*)(nA + soff0) = ra0;
;         if (ld_ok) ra0 = *(const uint4*)(Ab + (aoff + 0u * LDA + koa));
;         ga[0] = *(const bf16x8*)(sA + arow_off + 0 * 2048 + ch1); gb[0] = *(const bf16x8*)(sB + brow_off + 0 * 2048 + ch1);
;         __builtin_amdgcn_sched_barrier(0);
; #pragma unroll
;         for (int j = 0; j < 4; ++j) acc[0][j] = __builtin_amdgcn_mfma_f32_16x16x32_bf16(fb[j], fa[0], acc[0][j], 0, 0, 0);
;         __builtin_amdgcn_sched_barrier(0);
;         if (wr_ok) *(uint4*)(nA + soff0 + 4096) = ra1;
;         if (ld_ok) ra1 = *(const uint4*)(Ab + (aoff + 32u * LDA + koa));
;         ga[1] = *(const bf16x8*)(sA + arow_off + 1 * 2048 + ch1); gb[1] = *(const bf16x8*)(sB + brow_off + 1 * 2048 + ch1);
;         __builtin_amdgcn_sched_barrier(0);
; #pragma unroll
;         for (int j = 0; j < 4; ++j) acc[1][j] = __builtin_amdgcn_mfma_f32_16x16x32_bf16(fb[j], fa[1], acc[1][j], 0, 0, 0);
;         __builtin_amdgcn_sched_barrier(0);
;         if (wr_ok) *(uint4*)(nA + soff0 + 8192) = ra2;
;         if (ld_ok) ra2 = *(const uint4*)(Ab + (aoff + 64u * LDA + koa));
;         ga[2] = *(const bf16x8*)(sA + arow_off + 2 * 2048 + ch1); gb[2] = *(const bf16x8*)(sB + brow_off + 2 * 2048 + ch1);
;         __builtin_amdgcn_sched_barrier(0);
; #pragma unroll
;         for (int j = 0; j < 4; ++j) acc[2][j] = __builtin_amdgcn_mfma_f32_16x16x32_bf16(fb[j], fa[2], acc[2][j], 0, 0, 0);
;         __builtin_amdgcn_sched_barrier(0);
;         if (wr_ok) *(uint4*)(nA + soff0 + 12288) = ra3;
;         if (ld_ok) ra3 = *(const uint4*)(Ab + (aoff + 96u * LDA + koa));
;         ga[3] = *(const bf16x8*)(sA + arow_off + 3 * 2048 + ch1); gb[3] = *(const bf16x8*)(sB + brow_off + 3 * 2048 + ch1);
;         __builtin_amdgcn_sched_barrier(0);
; #pragma unroll
;         for (int j = 0; j < 4; ++j) acc[3][j] = __builtin_amdgcn_mfma_f32_16x16x32_bf16(fb[j], fa[3], acc[3][j], 0, 0, 0);
;         __builtin_amdgcn_sched_barrier(0);
;         if (wr_ok) *(uint4*)(nB + soff0) = rb0;
	ds_read_b128 v[58:61], v6
	ds_read_b128 v[120:123], v6 offset:2048
	ds_read_b128 v[124:127], v7 offset:16384
	ds_read_b128 v[132:135], v7 offset:18432
	ds_read_b128 v[146:149], v6 offset:4096
	ds_read_b128 v[154:157], v6 offset:6144
	ds_read_b128 v[158:161], v7 offset:20480
	ds_read_b128 v[162:165], v7 offset:22528
	s_setprio 2
	s_add_u32 s92, s92, 0x80
	s_addc_u32 s93, s93, 0
	s_add_u32 s94, s94, 0x80
	s_addc_u32 s95, s95, 0
	s_add_u32 m0, s96, 0x8000
	ds_read_b128 v[170:173], v3
	global_load_lds_dwordx4 v240, s[92:93]
	s_add_u32 m0, s96, 0x9000
	ds_read_b128 v[174:177], v4 offset:16384
	global_load_lds_dwordx4 v241, s[92:93]
	s_add_u32 m0, s96, 0xa000
	s_waitcnt lgkmcnt(7)
	global_load_lds_dwordx4 v242, s[92:93]
	s_add_u32 m0, s96, 0xb000
	v_mfma_f32_16x16x32_bf16 v[26:29], v[124:127], v[58:61], v[26:29]
	global_load_lds_dwordx4 v243, s[92:93]
	s_add_u32 m0, s96, 0xc000
	s_waitcnt lgkmcnt(2)
	global_load_lds_dwordx4 v244, s[94:95]
	s_add_u32 m0, s96, 0xd000
	v_mfma_f32_16x16x32_bf16 v[10:13], v[162:165], v[58:61], v[10:13]
	global_load_lds_dwordx4 v245, s[94:95]
	s_add_u32 m0, s96, 0xe000
	v_mfma_f32_16x16x32_bf16 v[88:91], v[132:135], v[58:61], v[88:91]
	global_load_lds_dwordx4 v246, s[94:95]
	s_add_u32 m0, s96, 0xf000
	v_mfma_f32_16x16x32_bf16 v[100:103], v[158:161], v[58:61], v[100:103]
	global_load_lds_dwordx4 v247, s[94:95]
	v_mfma_f32_16x16x32_bf16 v[30:33], v[124:127], v[120:123], v[30:33]
	v_mfma_f32_16x16x32_bf16 v[42:45], v[132:135], v[120:123], v[42:45]
	ds_read_b128 v[62:65], v3 offset:2048
	v_mfma_f32_16x16x32_bf16 v[14:17], v[162:165], v[120:123], v[14:17]
	ds_read_b128 v[178:181], v4 offset:18432
	v_mfma_f32_16x16x32_bf16 v[104:107], v[158:161], v[120:123], v[104:107]
	v_mfma_f32_16x16x32_bf16 v[34:37], v[124:127], v[146:149], v[34:37]
	v_mfma_f32_16x16x32_bf16 v[46:49], v[132:135], v[146:149], v[46:49]
	ds_read_b128 v[84:87], v3 offset:4096
	v_mfma_f32_16x16x32_bf16 v[18:21], v[162:165], v[146:149], v[18:21]
	ds_read_b128 v[182:185], v4 offset:20480
	v_mfma_f32_16x16x32_bf16 v[112:115], v[158:161], v[146:149], v[112:115]
	v_mfma_f32_16x16x32_bf16 v[38:41], v[124:127], v[154:157], v[38:41]
	v_mfma_f32_16x16x32_bf16 v[50:53], v[132:135], v[154:157], v[50:53]
	ds_read_b128 v[150:153], v3 offset:6144
	v_mfma_f32_16x16x32_bf16 v[54:57], v[158:161], v[154:157], v[54:57]
	ds_read_b128 v[186:189], v4 offset:22528
	v_mfma_f32_16x16x32_bf16 v[22:25], v[162:165], v[154:157], v[22:25]
	s_waitcnt lgkmcnt(6)
	v_mfma_f32_16x16x32_bf16 v[26:29], v[174:177], v[170:173], v[26:29]
	s_waitcnt lgkmcnt(0)
	v_mfma_f32_16x16x32_bf16 v[10:13], v[186:189], v[170:173], v[10:13]
	v_mfma_f32_16x16x32_bf16 v[88:91], v[178:181], v[170:173], v[88:91]
	v_mfma_f32_16x16x32_bf16 v[96:99], v[182:185], v[170:173], v[100:103]
	v_mfma_f32_16x16x32_bf16 v[30:33], v[174:177], v[62:65], v[30:33]
	v_mfma_f32_16x16x32_bf16 v[42:45], v[178:181], v[62:65], v[42:45]
	v_mfma_f32_16x16x32_bf16 v[14:17], v[186:189], v[62:65], v[14:17]
	v_mfma_f32_16x16x32_bf16 v[92:95], v[182:185], v[62:65], v[104:107]
	v_mfma_f32_16x16x32_bf16 v[34:37], v[174:177], v[84:87], v[34:37]
	v_mfma_f32_16x16x32_bf16 v[46:49], v[178:181], v[84:87], v[46:49]
	v_mfma_f32_16x16x32_bf16 v[18:21], v[186:189], v[84:87], v[18:21]
	v_mfma_f32_16x16x32_bf16 v[104:107], v[182:185], v[84:87], v[112:115]
	v_mfma_f32_16x16x32_bf16 v[38:41], v[174:177], v[150:153], v[38:41]
	v_mfma_f32_16x16x32_bf16 v[50:53], v[178:181], v[150:153], v[50:53]
	v_mfma_f32_16x16x32_bf16 v[54:57], v[182:185], v[150:153], v[54:57]
	v_mfma_f32_16x16x32_bf16 v[22:25], v[186:189], v[150:153], v[22:25]
	s_setprio 0
	s_waitcnt vmcnt(0) lgkmcnt(0)
	s_barrier
	ds_read_b128 v[108:111], v6 offset:32768
	ds_read_b128 v[112:115], v6 offset:34816
	ds_read_b128 v[116:119], v7 offset:49152
	ds_read_b128 v[132:135], v7 offset:51200
	ds_read_b128 v[150:153], v6 offset:36864
	ds_read_b128 v[154:157], v6 offset:38912
	ds_read_b128 v[158:161], v7 offset:53248
	ds_read_b128 v[162:165], v7 offset:55296
	s_setprio 2
	s_add_u32 s92, s92, 0x80
	s_addc_u32 s93, s93, 0
	s_add_u32 s94, s94, 0x80
	s_addc_u32 s95, s95, 0
	s_mov_b32 m0, s96
	ds_read_b128 v[166:169], v3 offset:32768
	global_load_lds_dwordx4 v240, s[92:93]
	s_add_u32 m0, s96, 0x1000
	ds_read_b128 v[174:177], v4 offset:49152
	global_load_lds_dwordx4 v241, s[92:93]
	s_add_u32 m0, s96, 0x2000
	s_waitcnt lgkmcnt(7)
	global_load_lds_dwordx4 v242, s[92:93]
	s_add_u32 m0, s96, 0x3000
	v_mfma_f32_16x16x32_bf16 v[26:29], v[116:119], v[108:111], v[26:29]
	global_load_lds_dwordx4 v243, s[92:93]
	s_add_u32 m0, s96, 0x4000
	s_waitcnt lgkmcnt(2)
	global_load_lds_dwordx4 v244, s[94:95]
	s_add_u32 m0, s96, 0x5000
	v_mfma_f32_16x16x32_bf16 v[10:13], v[162:165], v[108:111], v[10:13]
	global_load_lds_dwordx4 v245, s[94:95]
	s_add_u32 m0, s96, 0x6000
	v_mfma_f32_16x16x32_bf16 v[88:91], v[132:135], v[108:111], v[88:91]
	global_load_lds_dwordx4 v246, s[94:95]
	s_add_u32 m0, s96, 0x7000
	v_mfma_f32_16x16x32_bf16 v[96:99], v[158:161], v[108:111], v[96:99]
	global_load_lds_dwordx4 v247, s[94:95]
	v_mfma_f32_16x16x32_bf16 v[30:33], v[116:119], v[112:115], v[30:33]
	v_mfma_f32_16x16x32_bf16 v[42:45], v[132:135], v[112:115], v[42:45]
	ds_read_b128 v[58:61], v3 offset:34816
	v_mfma_f32_16x16x32_bf16 v[14:17], v[162:165], v[112:115], v[14:17]
	ds_read_b128 v[178:181], v4 offset:51200
	v_mfma_f32_16x16x32_bf16 v[92:95], v[158:161], v[112:115], v[92:95]
	v_mfma_f32_16x16x32_bf16 v[34:37], v[116:119], v[150:153], v[34:37]
	v_mfma_f32_16x16x32_bf16 v[46:49], v[132:135], v[150:153], v[46:49]
	ds_read_b128 v[120:123], v3 offset:36864
	v_mfma_f32_16x16x32_bf16 v[18:21], v[162:165], v[150:153], v[18:21]
	ds_read_b128 v[182:185], v4 offset:53248
	v_mfma_f32_16x16x32_bf16 v[104:107], v[158:161], v[150:153], v[104:107]
	v_mfma_f32_16x16x32_bf16 v[38:41], v[116:119], v[154:157], v[38:41]
	v_mfma_f32_16x16x32_bf16 v[50:53], v[132:135], v[154:157], v[50:53]
	ds_read_b128 v[146:149], v3 offset:38912
	v_mfma_f32_16x16x32_bf16 v[54:57], v[158:161], v[154:157], v[54:57]
	ds_read_b128 v[186:189], v4 offset:55296
	v_mfma_f32_16x16x32_bf16 v[22:25], v[162:165], v[154:157], v[22:25]
	s_waitcnt lgkmcnt(6)
; template <int MODE>
; __device__ __forceinline__ void gemm_tile(const Params& P, int tm, int tn, unsigned char* smem) {
;     ...
; #pragma unroll
;         for (int i = 0; i < 4; ++i) { fa[i] = *(const bf16x8*)(sA + arow_off + i * 2048 + ch0); fb[i] = *(const bf16x8*)(sB + brow_off + i * 2048 + ch0); }
;         __builtin_amdgcn_sched_barrier(0);
;         __builtin_amdgcn_s_setprio(2);
;         if (wr_ok) *(uint4*)(nA + soff0) = ra0;
;         if (ld_ok) ra0 = *(const uint4*)(Ab + (aoff + 0u * LDA + koa));
;         ga[0] = *(const bf16x8*)(sA + arow_off + 0 * 2048 + ch1); gb[0] = *(const bf16x8*)(sB + brow_off + 0 * 2048 + ch1);
;         __builtin_amdgcn_sched_barrier(0);
; #pragma unroll
;         for (int j = 0; j < 4; ++j) acc[0][j] = __builtin_amdgcn_mfma_f32_16x16x32_bf16(fb[j], fa[0], acc[0][j], 0, 0, 0);
;         __builtin_amdgcn_sched_barrier(0);
;         if (wr_ok) *(uint4*)(nA + soff0 + 4096) = ra1;
;         if (ld_ok) ra1 = *(const uint4*)(Ab + (aoff + 32u * LDA + koa));
;         ga[1] = *(const bf16x8*)(sA + arow_off + 1 * 2048 + ch1); gb[1] = *(const bf16x8*)(sB + brow_off + 1 * 2048 + ch1);
;         __builtin_amdgcn_sched_barrier(0);
; #pragma unroll
;         for (int j = 0; j < 4; ++j) acc[1][j] = __builtin_amdgcn_mfma_f32_16x16x32_bf16(fb[j], fa[1], acc[1][j], 0, 0, 0);
;         __builtin_amdgcn_sched_barrier(0);
;         if (wr_ok) *(uint4*)(nA + soff0 + 8192) = ra2;
;         if (ld_ok) ra2 = *(const uint4*)(Ab + (aoff + 64u * LDA + koa));
;         ga[2] = *(const bf16x8*)(sA + arow_off + 2 * 2048 + ch1); gb[2] = *(const bf16x8*)(sB + brow_off + 2 * 2048 + ch1);
;         __builtin_amdgcn_sched_barrier(0);
; #pragma unroll
;         for (int j = 0; j < 4; ++j) acc[2][j] = __builtin_amdgcn_mfma_f32_16x16x32_bf16(fb[j], fa[2], acc[2][j], 0, 0, 0);
;         __builtin_amdgcn_sched_barrier(0);
;         if (wr_ok) *(uint4*)(nA + soff0 + 12288) = ra3;
;         if (ld_ok) ra3 = *(const uint4*)(Ab + (aoff + 96u * LDA + koa));
;         ga[3] = *(const bf16x8*)(sA + arow_off + 3 * 2048 + ch1); gb[3] = *(const bf16x8*)(sB + brow_off + 3 * 2048 + ch1);
;         __builtin_amdgcn_sched_barrier(0);
; #pragma unroll
;         for (int j = 0; j < 4; ++j) acc[3][j] = __builtin_amdgcn_mfma_f32_16x16x32_bf16(fb[j], fa[3], acc[3][j], 0, 0, 0);
;         __builtin_amdgcn_sched_barrier(0);
;         if (wr_ok) *(uint4*)(nB + soff0) = rb0;
	v_mfma_f32_16x16x32_bf16 v[26:29], v[174:177], v[166:169], v[26:29]
	s_waitcnt lgkmcnt(0)
	v_mfma_f32_16x16x32_bf16 v[10:13], v[186:189], v[166:169], v[10:13]
	v_mfma_f32_16x16x32_bf16 v[88:91], v[178:181], v[166:169], v[88:91]
	v_mfma_f32_16x16x32_bf16 v[96:99], v[182:185], v[166:169], v[96:99]
	v_mfma_f32_16x16x32_bf16 v[30:33], v[174:177], v[58:61], v[30:33]
	v_mfma_f32_16x16x32_bf16 v[42:45], v[178:181], v[58:61], v[42:45]
	v_mfma_f32_16x16x32_bf16 v[14:17], v[186:189], v[58:61], v[14:17]
	v_mfma_f32_16x16x32_bf16 v[92:95], v[182:185], v[58:61], v[92:95]
	v_mfma_f32_16x16x32_bf16 v[34:37], v[174:177], v[120:123], v[34:37]
	v_mfma_f32_16x16x32_bf16 v[46:49], v[178:181], v[120:123], v[46:49]
	v_mfma_f32_16x16x32_bf16 v[62:65], v[182:185], v[120:123], v[104:107]
	v_mfma_f32_16x16x32_bf16 v[18:21], v[186:189], v[120:123], v[18:21]
	v_mfma_f32_16x16x32_bf16 v[38:41], v[174:177], v[146:149], v[38:41]
	v_mfma_f32_16x16x32_bf16 v[50:53], v[178:181], v[146:149], v[50:53]
	v_mfma_f32_16x16x32_bf16 v[54:57], v[182:185], v[146:149], v[54:57]
	v_mfma_f32_16x16x32_bf16 v[22:25], v[186:189], v[146:149], v[22:25]
	s_setprio 0
	s_waitcnt vmcnt(0) lgkmcnt(0)
	s_barrier
	ds_read_b128 v[84:87], v6
	ds_read_b128 v[104:107], v6 offset:2048
	ds_read_b128 v[120:123], v7 offset:16384
	ds_read_b128 v[132:135], v7 offset:18432
	ds_read_b128 v[146:149], v6 offset:4096
	ds_read_b128 v[154:157], v6 offset:6144
	ds_read_b128 v[158:161], v7 offset:20480
	ds_read_b128 v[162:165], v7 offset:22528
	s_setprio 2
	s_add_u32 s92, s92, 0x80
	s_addc_u32 s93, s93, 0
	s_add_u32 s94, s94, 0x80
	s_addc_u32 s95, s95, 0
	s_add_u32 m0, s96, 0x8000
	ds_read_b128 v[170:173], v3
	global_load_lds_dwordx4 v240, s[92:93]
	s_add_u32 m0, s96, 0x9000
	ds_read_b128 v[174:177], v4 offset:16384
	global_load_lds_dwordx4 v241, s[92:93]
	s_add_u32 m0, s96, 0xa000
	s_waitcnt lgkmcnt(7)
	global_load_lds_dwordx4 v242, s[92:93]
	s_add_u32 m0, s96, 0xb000
	v_mfma_f32_16x16x32_bf16 v[26:29], v[120:123], v[84:87], v[26:29]
	global_load_lds_dwordx4 v243, s[92:93]
	s_add_u32 m0, s96, 0xc000
	s_waitcnt lgkmcnt(2)
	global_load_lds_dwordx4 v244, s[94:95]
	s_add_u32 m0, s96, 0xd000
	v_mfma_f32_16x16x32_bf16 v[10:13], v[162:165], v[84:87], v[10:13]
	global_load_lds_dwordx4 v245, s[94:95]
	s_add_u32 m0, s96, 0xe000
	v_mfma_f32_16x16x32_bf16 v[88:91], v[132:135], v[84:87], v[88:91]
	global_load_lds_dwordx4 v246, s[94:95]
	s_add_u32 m0, s96, 0xf000
	v_mfma_f32_16x16x32_bf16 v[96:99], v[158:161], v[84:87], v[96:99]
	global_load_lds_dwordx4 v247, s[94:95]
	v_mfma_f32_16x16x32_bf16 v[30:33], v[120:123], v[104:107], v[30:33]
	v_mfma_f32_16x16x32_bf16 v[42:45], v[132:135], v[104:107], v[42:45]
	ds_read_b128 v[108:111], v3 offset:2048
	v_mfma_f32_16x16x32_bf16 v[14:17], v[162:165], v[104:107], v[14:17]
	ds_read_b128 v[178:181], v4 offset:18432
	v_mfma_f32_16x16x32_bf16 v[92:95], v[158:161], v[104:107], v[92:95]
	v_mfma_f32_16x16x32_bf16 v[34:37], v[120:123], v[146:149], v[34:37]
	v_mfma_f32_16x16x32_bf16 v[46:49], v[132:135], v[146:149], v[46:49]
	ds_read_b128 v[112:115], v3 offset:4096
	v_mfma_f32_16x16x32_bf16 v[62:65], v[158:161], v[146:149], v[62:65]
	ds_read_b128 v[182:185], v4 offset:20480
	v_mfma_f32_16x16x32_bf16 v[18:21], v[162:165], v[146:149], v[18:21]
	v_mfma_f32_16x16x32_bf16 v[38:41], v[120:123], v[154:157], v[38:41]
	v_mfma_f32_16x16x32_bf16 v[50:53], v[132:135], v[154:157], v[50:53]
	ds_read_b128 v[150:153], v3 offset:6144
	v_mfma_f32_16x16x32_bf16 v[54:57], v[158:161], v[154:157], v[54:57]
	ds_read_b128 v[186:189], v4 offset:22528
	v_mfma_f32_16x16x32_bf16 v[22:25], v[162:165], v[154:157], v[22:25]
	s_waitcnt lgkmcnt(6)
	v_mfma_f32_16x16x32_bf16 v[26:29], v[174:177], v[170:173], v[26:29]
	s_waitcnt lgkmcnt(0)
	v_mfma_f32_16x16x32_bf16 v[10:13], v[186:189], v[170:173], v[10:13]
	v_mfma_f32_16x16x32_bf16 v[88:91], v[178:181], v[170:173], v[88:91]
	v_mfma_f32_16x16x32_bf16 v[96:99], v[182:185], v[170:173], v[96:99]
	v_mfma_f32_16x16x32_bf16 v[30:33], v[174:177], v[108:111], v[30:33]
	v_mfma_f32_16x16x32_bf16 v[42:45], v[178:181], v[108:111], v[42:45]
	v_mfma_f32_16x16x32_bf16 v[14:17], v[186:189], v[108:111], v[14:17]
	v_mfma_f32_16x16x32_bf16 v[92:95], v[182:185], v[108:111], v[92:95]
	v_mfma_f32_16x16x32_bf16 v[34:37], v[174:177], v[112:115], v[34:37]
	v_mfma_f32_16x16x32_bf16 v[46:49], v[178:181], v[112:115], v[46:49]
	v_mfma_f32_16x16x32_bf16 v[58:61], v[182:185], v[112:115], v[62:65]
	v_mfma_f32_16x16x32_bf16 v[18:21], v[186:189], v[112:115], v[18:21]
	v_mfma_f32_16x16x32_bf16 v[38:41], v[174:177], v[150:153], v[38:41]
	v_mfma_f32_16x16x32_bf16 v[50:53], v[178:181], v[150:153], v[50:53]
	v_mfma_f32_16x16x32_bf16 v[54:57], v[182:185], v[150:153], v[54:57]
	v_mfma_f32_16x16x32_bf16 v[22:25], v[186:189], v[150:153], v[22:25]
	s_setprio 0
	s_waitcnt vmcnt(0) lgkmcnt(0)
	s_barrier
; template <int MODE>
; __device__ __forceinline__ void gemm_tile(const Params& P, int tm, int tn, unsigned char* smem) {
;     ...
; #pragma unroll
;         for (int i = 0; i < 4; ++i) { fa[i] = *(const bf16x8*)(sA + arow_off + i * 2048 + ch0); fb[i] = *(const bf16x8*)(sB + brow_off + i * 2048 + ch0); }
;         __builtin_amdgcn_sched_barrier(0);
;         __builtin_amdgcn_s_setprio(2);
;         if (wr_ok) *(uint4*)(nA + soff0) = ra0;
;         if (ld_ok) ra0 = *(const uint4*)(Ab + (aoff + 0u * LDA + koa));
;         ga[0] = *(const bf16x8*)(sA + arow_off + 0 * 2048 + ch1); gb[0] = *(const bf16x8*)(sB + brow_off + 0 * 2048 + ch1);
;         __builtin_amdgcn_sched_barrier(0);
; #pragma unroll
;         for (int j = 0; j < 4; ++j) acc[0][j] = __builtin_amdgcn_mfma_f32_16x16x32_bf16(fb[j], fa[0], acc[0][j], 0, 0, 0);
;         __builtin_amdgcn_sched_barrier(0);
;         if (wr_ok) *(uint4*)(nA + soff0 + 4096) = ra1;
;         if (ld_ok) ra1 = *(const uint4*)(Ab + (aoff + 32u * LDA + koa));
;         ga[1] = *(const bf16x8*)(sA + arow_off + 1 * 2048 + ch1); gb[1] = *(const bf16x8*)(sB + brow_off + 1 * 2048 + ch1);
;         __builtin_amdgcn_sched_barrier(0);
; #pragma unroll
;         for (int j = 0; j < 4; ++j) acc[1][j] = __builtin_amdgcn_mfma_f32_16x16x32_bf16(fb[j], fa[1], acc[1][j], 0, 0, 0);
;         __builtin_amdgcn_sched_barrier(0);
;         if (wr_ok) *(uint4*)(nA + soff0 + 8192) = ra2;
;         if (ld_ok) ra2 = *(const uint4*)(Ab + (aoff + 64u * LDA + koa));
;         ga[2] = *(const bf16x8*)(sA + arow_off + 2 * 2048 + ch1); gb[2] = *(const bf16x8*)(sB + brow_off + 2 * 2048 + ch1);
;         __builtin_amdgcn_sched_barrier(0);
; #pragma unroll
;         for (int j = 0; j < 4; ++j) acc[2][j] = __builtin_amdgcn_mfma_f32_16x16x32_bf16(fb[j], fa[2], acc[2][j], 0, 0, 0);
;         __builtin_amdgcn_sched_barrier(0);
;         if (wr_ok) *(uint4*)(nA + soff0 + 12288) = ra3;
;         if (ld_ok) ra3 = *(const uint4*)(Ab + (aoff + 96u * LDA + koa));
;         ga[3] = *(const bf16x8*)(sA + arow_off + 3 * 2048 + ch1); gb[3] = *(const bf16x8*)(sB + brow_off + 3 * 2048 + ch1);
;         __builtin_amdgcn_sched_barrier(0);
; #pragma unroll
;         for (int j = 0; j < 4; ++j) acc[3][j] = __builtin_amdgcn_mfma_f32_16x16x32_bf16(fb[j], fa[3], acc[3][j], 0, 0, 0);
;         __builtin_amdgcn_sched_barrier(0);
;         if (wr_ok) *(uint4*)(nB + soff0) = rb0;
	ds_read_b128 v[100:103], v6 offset:32768
	ds_read_b128 v[112:115], v6 offset:34816
	ds_read_b128 v[124:127], v7 offset:49152
	ds_read_b128 v[132:135], v7 offset:51200
	ds_read_b128 v[150:153], v6 offset:36864
	ds_read_b128 v[154:157], v6 offset:38912
	ds_read_b128 v[158:161], v7 offset:53248
	ds_read_b128 v[162:165], v7 offset:55296
	s_setprio 2
	s_add_u32 s92, s92, 0x80
	s_addc_u32 s93, s93, 0
	s_add_u32 s94, s94, 0x80
	s_addc_u32 s95, s95, 0
	s_mov_b32 m0, s96
	ds_read_b128 v[166:169], v3 offset:32768
	global_load_lds_dwordx4 v240, s[92:93]
	s_add_u32 m0, s96, 0x1000
	ds_read_b128 v[174:177], v4 offset:49152
	global_load_lds_dwordx4 v241, s[92:93]
	s_add_u32 m0, s96, 0x2000
	s_waitcnt lgkmcnt(7)
	global_load_lds_dwordx4 v242, s[92:93]
	s_add_u32 m0, s96, 0x3000
	v_mfma_f32_16x16x32_bf16 v[26:29], v[124:127], v[100:103], v[26:29]
	global_load_lds_dwordx4 v243, s[92:93]
	s_add_u32 m0, s96, 0x4000
	s_waitcnt lgkmcnt(2)
	global_load_lds_dwordx4 v244, s[94:95]
	s_add_u32 m0, s96, 0x5000
	v_mfma_f32_16x16x32_bf16 v[10:13], v[162:165], v[100:103], v[10:13]
	global_load_lds_dwordx4 v245, s[94:95]
	s_add_u32 m0, s96, 0x6000
	v_mfma_f32_16x16x32_bf16 v[88:91], v[132:135], v[100:103], v[88:91]
	global_load_lds_dwordx4 v246, s[94:95]
	s_add_u32 m0, s96, 0x7000
	v_mfma_f32_16x16x32_bf16 v[96:99], v[158:161], v[100:103], v[96:99]
	global_load_lds_dwordx4 v247, s[94:95]
	v_mfma_f32_16x16x32_bf16 v[30:33], v[124:127], v[112:115], v[30:33]
	v_mfma_f32_16x16x32_bf16 v[42:45], v[132:135], v[112:115], v[42:45]
	ds_read_b128 v[84:87], v3 offset:34816
	v_mfma_f32_16x16x32_bf16 v[14:17], v[162:165], v[112:115], v[14:17]
	ds_read_b128 v[178:181], v4 offset:51200
	v_mfma_f32_16x16x32_bf16 v[92:95], v[158:161], v[112:115], v[92:95]
	v_mfma_f32_16x16x32_bf16 v[34:37], v[124:127], v[150:153], v[34:37]
	v_mfma_f32_16x16x32_bf16 v[46:49], v[132:135], v[150:153], v[46:49]
	ds_read_b128 v[104:107], v3 offset:36864
	v_mfma_f32_16x16x32_bf16 v[58:61], v[158:161], v[150:153], v[58:61]
	ds_read_b128 v[182:185], v4 offset:53248
	v_mfma_f32_16x16x32_bf16 v[18:21], v[162:165], v[150:153], v[18:21]
	v_mfma_f32_16x16x32_bf16 v[38:41], v[124:127], v[154:157], v[38:41]
	v_mfma_f32_16x16x32_bf16 v[50:53], v[132:135], v[154:157], v[50:53]
	ds_read_b128 v[146:149], v3 offset:38912
	v_mfma_f32_16x16x32_bf16 v[54:57], v[158:161], v[154:157], v[54:57]
	ds_read_b128 v[186:189], v4 offset:55296
	v_mfma_f32_16x16x32_bf16 v[22:25], v[162:165], v[154:157], v[22:25]
	s_waitcnt lgkmcnt(6)
	v_mfma_f32_16x16x32_bf16 v[26:29], v[174:177], v[166:169], v[26:29]
	s_waitcnt lgkmcnt(0)
	v_mfma_f32_16x16x32_bf16 v[10:13], v[186:189], v[166:169], v[10:13]
	v_mfma_f32_16x16x32_bf16 v[88:91], v[178:181], v[166:169], v[88:91]
	v_mfma_f32_16x16x32_bf16 v[96:99], v[182:185], v[166:169], v[96:99]
	v_mfma_f32_16x16x32_bf16 v[30:33], v[174:177], v[84:87], v[30:33]
	v_mfma_f32_16x16x32_bf16 v[42:45], v[178:181], v[84:87], v[42:45]
	v_mfma_f32_16x16x32_bf16 v[14:17], v[186:189], v[84:87], v[14:17]
	v_mfma_f32_16x16x32_bf16 v[92:95], v[182:185], v[84:87], v[92:95]
	v_mfma_f32_16x16x32_bf16 v[34:37], v[174:177], v[104:107], v[34:37]
	v_mfma_f32_16x16x32_bf16 v[46:49], v[178:181], v[104:107], v[46:49]
	v_mfma_f32_16x16x32_bf16 v[58:61], v[182:185], v[104:107], v[58:61]
	v_mfma_f32_16x16x32_bf16 v[18:21], v[186:189], v[104:107], v[18:21]
	v_mfma_f32_16x16x32_bf16 v[38:41], v[174:177], v[146:149], v[38:41]
	v_mfma_f32_16x16x32_bf16 v[50:53], v[178:181], v[146:149], v[50:53]
	v_mfma_f32_16x16x32_bf16 v[54:57], v[182:185], v[146:149], v[54:57]
	v_mfma_f32_16x16x32_bf16 v[22:25], v[186:189], v[146:149], v[22:25]
	s_setprio 0
	s_waitcnt vmcnt(0) lgkmcnt(0)
	s_barrier
	ds_read_b128 v[62:65], v6
	ds_read_b128 v[108:111], v6 offset:2048
	ds_read_b128 v[116:119], v7 offset:16384
	ds_read_b128 v[132:135], v7 offset:18432
	ds_read_b128 v[146:149], v6 offset:4096
	ds_read_b128 v[154:157], v6 offset:6144
	ds_read_b128 v[158:161], v7 offset:20480
	ds_read_b128 v[162:165], v7 offset:22528
	s_setprio 2
	s_add_u32 s92, s92, 0x80
	s_addc_u32 s93, s93, 0
	s_add_u32 s94, s94, 0x80
	s_addc_u32 s95, s95, 0
	s_add_u32 m0, s96, 0x8000
	ds_read_b128 v[170:173], v3
	global_load_lds_dwordx4 v240, s[92:93]
	s_add_u32 m0, s96, 0x9000
	ds_read_b128 v[174:177], v4 offset:16384
	global_load_lds_dwordx4 v241, s[92:93]
	s_add_u32 m0, s96, 0xa000
	s_waitcnt lgkmcnt(7)
	global_load_lds_dwordx4 v242, s[92:93]
	s_add_u32 m0, s96, 0xb000
	v_mfma_f32_16x16x32_bf16 v[26:29], v[116:119], v[62:65], v[26:29]
	global_load_lds_dwordx4 v243, s[92:93]
	s_add_u32 m0, s96, 0xc000
	s_waitcnt lgkmcnt(2)
	global_load_lds_dwordx4 v244, s[94:95]
	s_add_u32 m0, s96, 0xd000
	v_mfma_f32_16x16x32_bf16 v[10:13], v[162:165], v[62:65], v[10:13]
	global_load_lds_dwordx4 v245, s[94:95]
	s_add_u32 m0, s96, 0xe000
	v_mfma_f32_16x16x32_bf16 v[88:91], v[132:135], v[62:65], v[88:91]
	global_load_lds_dwordx4 v246, s[94:95]
	s_add_u32 m0, s96, 0xf000
	v_mfma_f32_16x16x32_bf16 v[96:99], v[158:161], v[62:65], v[96:99]
	global_load_lds_dwordx4 v247, s[94:95]
	v_mfma_f32_16x16x32_bf16 v[30:33], v[116:119], v[108:111], v[30:33]
	v_mfma_f32_16x16x32_bf16 v[42:45], v[132:135], v[108:111], v[42:45]
	ds_read_b128 v[100:103], v3 offset:2048
	v_mfma_f32_16x16x32_bf16 v[14:17], v[162:165], v[108:111], v[14:17]
	ds_read_b128 v[178:181], v4 offset:18432
	v_mfma_f32_16x16x32_bf16 v[92:95], v[158:161], v[108:111], v[92:95]
	v_mfma_f32_16x16x32_bf16 v[34:37], v[116:119], v[146:149], v[34:37]
	v_mfma_f32_16x16x32_bf16 v[46:49], v[132:135], v[146:149], v[46:49]
	ds_read_b128 v[112:115], v3 offset:4096
	v_mfma_f32_16x16x32_bf16 v[58:61], v[158:161], v[146:149], v[58:61]
	ds_read_b128 v[182:185], v4 offset:20480
	v_mfma_f32_16x16x32_bf16 v[18:21], v[162:165], v[146:149], v[18:21]
	v_mfma_f32_16x16x32_bf16 v[38:41], v[116:119], v[154:157], v[38:41]
	v_mfma_f32_16x16x32_bf16 v[50:53], v[132:135], v[154:157], v[50:53]
	ds_read_b128 v[150:153], v3 offset:6144
	v_mfma_f32_16x16x32_bf16 v[54:57], v[158:161], v[154:157], v[54:57]
	ds_read_b128 v[186:189], v4 offset:22528
	v_mfma_f32_16x16x32_bf16 v[22:25], v[162:165], v[154:157], v[22:25]
	s_waitcnt lgkmcnt(6)
; template <int MODE>
; __device__ __forceinline__ void gemm_tile(const Params& P, int tm, int tn, unsigned char* smem) {
;     ...
; #pragma unroll
;         for (int i = 0; i < 4; ++i) { fa[i] = *(const bf16x8*)(sA + arow_off + i * 2048 + ch0); fb[i] = *(const bf16x8*)(sB + brow_off + i * 2048 + ch0); }
;         __builtin_amdgcn_sched_barrier(0);
;         __builtin_amdgcn_s_setprio(2);
;         if (wr_ok) *(uint4*)(nA + soff0) = ra0;
;         if (ld_ok) ra0 = *(const uint4*)(Ab + (aoff + 0u * LDA + koa));
;         ga[0] = *(const bf16x8*)(sA + arow_off + 0 * 2048 + ch1); gb[0] = *(const bf16x8*)(sB + brow_off + 0 * 2048 + ch1);
;         __builtin_amdgcn_sched_barrier(0);
; #pragma unroll
;         for (int j = 0; j < 4; ++j) acc[0][j] = __builtin_amdgcn_mfma_f32_16x16x32_bf16(fb[j], fa[0], acc[0][j], 0, 0, 0);
;         __builtin_amdgcn_sched_barrier(0);
;         if (wr_ok) *(uint4*)(nA + soff0 + 4096) = ra1;
;         if (ld_ok) ra1 = *(const uint4*)(Ab + (aoff + 32u * LDA + koa));
;         ga[1] = *(const bf16x8*)(sA + arow_off + 1 * 2048 + ch1); gb[1] = *(const bf16x8*)(sB + brow_off + 1 * 2048 + ch1);
;         __builtin_amdgcn_sched_barrier(0);
; #pragma unroll
;         for (int j = 0; j < 4; ++j) acc[1][j] = __builtin_amdgcn_mfma_f32_16x16x32_bf16(fb[j], fa[1], acc[1][j], 0, 0, 0);
;         __builtin_amdgcn_sched_barrier(0);
;         if (wr_ok) *(uint4*)(nA + soff0 + 8192) = ra2;
;         if (ld_ok) ra2 = *(const uint4*)(Ab + (aoff + 64u * LDA + koa));
;         ga[2] = *(const bf16x8*)(sA + arow_off + 2 * 2048 + ch1); gb[2] = *(const bf16x8*)(sB + brow_off + 2 * 2048 + ch1);
;         __builtin_amdgcn_sched_barrier(0);
; #pragma unroll
;         for (int j = 0; j < 4; ++j) acc[2][j] = __builtin_amdgcn_mfma_f32_16x16x32_bf16(fb[j], fa[2], acc[2][j], 0, 0, 0);
;         __builtin_amdgcn_sched_barrier(0);
;         if (wr_ok) *(uint4*)(nA + soff0 + 12288) = ra3;
;         if (ld_ok) ra3 = *(const uint4*)(Ab + (aoff + 96u * LDA + koa));
;         ga[3] = *(const bf16x8*)(sA + arow_off + 3 * 2048 + ch1); gb[3] = *(const bf16x8*)(sB + brow_off + 3 * 2048 + ch1);
;         __builtin_amdgcn_sched_barrier(0);
; #pragma unroll
;         for (int j = 0; j < 4; ++j) acc[3][j] = __builtin_amdgcn_mfma_f32_16x16x32_bf16(fb[j], fa[3], acc[3][j], 0, 0, 0);
;         __builtin_amdgcn_sched_barrier(0);
;         if (wr_ok) *(uint4*)(nB + soff0) = rb0;
	v_mfma_f32_16x16x32_bf16 v[26:29], v[174:177], v[170:173], v[26:29]
	s_waitcnt lgkmcnt(0)
	v_mfma_f32_16x16x32_bf16 v[10:13], v[186:189], v[170:173], v[10:13]
	v_mfma_f32_16x16x32_bf16 v[88:91], v[178:181], v[170:173], v[88:91]
	v_mfma_f32_16x16x32_bf16 v[96:99], v[182:185], v[170:173], v[96:99]
	v_mfma_f32_16x16x32_bf16 v[30:33], v[174:177], v[100:103], v[30:33]
	v_mfma_f32_16x16x32_bf16 v[42:45], v[178:181], v[100:103], v[42:45]
	v_mfma_f32_16x16x32_bf16 v[14:17], v[186:189], v[100:103], v[14:17]
	v_mfma_f32_16x16x32_bf16 v[92:95], v[182:185], v[100:103], v[92:95]
	v_mfma_f32_16x16x32_bf16 v[34:37], v[174:177], v[112:115], v[34:37]
	v_mfma_f32_16x16x32_bf16 v[46:49], v[178:181], v[112:115], v[46:49]
	v_mfma_f32_16x16x32_bf16 v[58:61], v[182:185], v[112:115], v[58:61]
	v_mfma_f32_16x16x32_bf16 v[18:21], v[186:189], v[112:115], v[18:21]
	v_mfma_f32_16x16x32_bf16 v[38:41], v[174:177], v[150:153], v[38:41]
	v_mfma_f32_16x16x32_bf16 v[50:53], v[178:181], v[150:153], v[50:53]
	v_mfma_f32_16x16x32_bf16 v[54:57], v[182:185], v[150:153], v[54:57]
	v_mfma_f32_16x16x32_bf16 v[22:25], v[186:189], v[150:153], v[22:25]
	s_setprio 0
	s_waitcnt vmcnt(0) lgkmcnt(0)
	s_barrier
	ds_read_b128 v[104:107], v6 offset:32768
	ds_read_b128 v[112:115], v6 offset:34816
	ds_read_b128 v[120:123], v7 offset:49152
	ds_read_b128 v[132:135], v7 offset:51200
	ds_read_b128 v[150:153], v6 offset:36864
	ds_read_b128 v[154:157], v6 offset:38912
	ds_read_b128 v[158:161], v7 offset:53248
	ds_read_b128 v[162:165], v7 offset:55296
	s_setprio 2
	s_add_u32 s92, s92, 0x80
	s_addc_u32 s93, s93, 0
	s_add_u32 s94, s94, 0x80
	s_addc_u32 s95, s95, 0
	s_mov_b32 m0, s96
	ds_read_b128 v[166:169], v3 offset:32768
	global_load_lds_dwordx4 v240, s[92:93]
	s_add_u32 m0, s96, 0x1000
	ds_read_b128 v[174:177], v4 offset:49152
	global_load_lds_dwordx4 v241, s[92:93]
	s_add_u32 m0, s96, 0x2000
	s_waitcnt lgkmcnt(7)
	global_load_lds_dwordx4 v242, s[92:93]
	s_add_u32 m0, s96, 0x3000
	v_mfma_f32_16x16x32_bf16 v[26:29], v[120:123], v[104:107], v[26:29]
	global_load_lds_dwordx4 v243, s[92:93]
	s_add_u32 m0, s96, 0x4000
	s_waitcnt lgkmcnt(2)
	global_load_lds_dwordx4 v244, s[94:95]
	s_add_u32 m0, s96, 0x5000
	v_mfma_f32_16x16x32_bf16 v[10:13], v[162:165], v[104:107], v[10:13]
	global_load_lds_dwordx4 v245, s[94:95]
	s_add_u32 m0, s96, 0x6000
	v_mfma_f32_16x16x32_bf16 v[88:91], v[132:135], v[104:107], v[88:91]
	global_load_lds_dwordx4 v246, s[94:95]
	s_add_u32 m0, s96, 0x7000
	v_mfma_f32_16x16x32_bf16 v[96:99], v[158:161], v[104:107], v[96:99]
	global_load_lds_dwordx4 v247, s[94:95]
	v_mfma_f32_16x16x32_bf16 v[30:33], v[120:123], v[112:115], v[30:33]
	v_mfma_f32_16x16x32_bf16 v[42:45], v[132:135], v[112:115], v[42:45]
	ds_read_b128 v[62:65], v3 offset:34816
	v_mfma_f32_16x16x32_bf16 v[14:17], v[162:165], v[112:115], v[14:17]
	ds_read_b128 v[178:181], v4 offset:51200
	v_mfma_f32_16x16x32_bf16 v[92:95], v[158:161], v[112:115], v[92:95]
	v_mfma_f32_16x16x32_bf16 v[34:37], v[120:123], v[150:153], v[34:37]
	v_mfma_f32_16x16x32_bf16 v[46:49], v[132:135], v[150:153], v[46:49]
	ds_read_b128 v[108:111], v3 offset:36864
	v_mfma_f32_16x16x32_bf16 v[58:61], v[158:161], v[150:153], v[58:61]
	ds_read_b128 v[182:185], v4 offset:53248
	v_mfma_f32_16x16x32_bf16 v[18:21], v[162:165], v[150:153], v[18:21]
	v_mfma_f32_16x16x32_bf16 v[38:41], v[120:123], v[154:157], v[38:41]
	v_mfma_f32_16x16x32_bf16 v[50:53], v[132:135], v[154:157], v[50:53]
	ds_read_b128 v[146:149], v3 offset:38912
	v_mfma_f32_16x16x32_bf16 v[54:57], v[158:161], v[154:157], v[54:57]
	ds_read_b128 v[186:189], v4 offset:55296
	v_mfma_f32_16x16x32_bf16 v[22:25], v[162:165], v[154:157], v[22:25]
	s_waitcnt lgkmcnt(6)
	v_mfma_f32_16x16x32_bf16 v[26:29], v[174:177], v[166:169], v[26:29]
	s_waitcnt lgkmcnt(0)
	v_mfma_f32_16x16x32_bf16 v[10:13], v[186:189], v[166:169], v[10:13]
	v_mfma_f32_16x16x32_bf16 v[88:91], v[178:181], v[166:169], v[88:91]
	v_mfma_f32_16x16x32_bf16 v[96:99], v[182:185], v[166:169], v[96:99]
	v_mfma_f32_16x16x32_bf16 v[30:33], v[174:177], v[62:65], v[30:33]
	v_mfma_f32_16x16x32_bf16 v[42:45], v[178:181], v[62:65], v[42:45]
	v_mfma_f32_16x16x32_bf16 v[14:17], v[186:189], v[62:65], v[14:17]
	v_mfma_f32_16x16x32_bf16 v[92:95], v[182:185], v[62:65], v[92:95]
	v_mfma_f32_16x16x32_bf16 v[34:37], v[174:177], v[108:111], v[34:37]
	v_mfma_f32_16x16x32_bf16 v[46:49], v[178:181], v[108:111], v[46:49]
	v_mfma_f32_16x16x32_bf16 v[58:61], v[182:185], v[108:111], v[58:61]
	v_mfma_f32_16x16x32_bf16 v[18:21], v[186:189], v[108:111], v[18:21]
	v_mfma_f32_16x16x32_bf16 v[38:41], v[174:177], v[146:149], v[38:41]
	v_mfma_f32_16x16x32_bf16 v[50:53], v[178:181], v[146:149], v[50:53]
	v_mfma_f32_16x16x32_bf16 v[54:57], v[182:185], v[146:149], v[54:57]
	v_mfma_f32_16x16x32_bf16 v[22:25], v[186:189], v[146:149], v[22:25]
	s_setprio 0
	s_waitcnt vmcnt(0) lgkmcnt(0)
	s_barrier
; template <int MODE>
; __device__ __forceinline__ void gemm_tile(const Params& P, int tm, int tn, unsigned char* smem) {
;     ...
; #pragma unroll
;         for (int i = 0; i < 4; ++i) { fa[i] = *(const bf16x8*)(sA + arow_off + i * 2048 + ch0); fb[i] = *(const bf16x8*)(sB + brow_off + i * 2048 + ch0); }
;         __builtin_amdgcn_sched_barrier(0);
;         __builtin_amdgcn_s_setprio(2);
;         if (wr_ok) *(uint4*)(nA + soff0) = ra0;
;         if (ld_ok) ra0 = *(const uint4*)(Ab + (aoff + 0u * LDA + koa));
;         ga[0] = *(const bf16x8*)(sA + arow_off + 0 * 2048 + ch1); gb[0] = *(const bf16x8*)(sB + brow_off + 0 * 2048 + ch1);
;         __builtin_amdgcn_sched_barrier(0);
; #pragma unroll
;         for (int j = 0; j < 4; ++j) acc[0][j] = __builtin_amdgcn_mfma_f32_16x16x32_bf16(fb[j], fa[0], acc[0][j], 0, 0, 0);
;         __builtin_amdgcn_sched_barrier(0);
;         if (wr_ok) *(uint4*)(nA + soff0 + 4096) = ra1;
;         if (ld_ok) ra1 = *(const uint4*)(Ab + (aoff + 32u * LDA + koa));
;         ga[1] = *(const bf16x8*)(sA + arow_off + 1 * 2048 + ch1); gb[1] = *(const bf16x8*)(sB + brow_off + 1 * 2048 + ch1);
;         __builtin_amdgcn_sched_barrier(0);
; #pragma unroll
;         for (int j = 0; j < 4; ++j) acc[1][j] = __builtin_amdgcn_mfma_f32_16x16x32_bf16(fb[j], fa[1], acc[1][j], 0, 0, 0);
;         __builtin_amdgcn_sched_barrier(0);
;         if (wr_ok) *(uint4*)(nA + soff0 + 8192) = ra2;
;         if (ld_ok) ra2 = *(const uint4*)(Ab + (aoff + 64u * LDA + koa));
;         ga[2] = *(const bf16x8*)(sA + arow_off + 2 * 2048 + ch1); gb[2] = *(const bf16x8*)(sB + brow_off + 2 * 2048 + ch1);
;         __builtin_amdgcn_sched_barrier(0);
; #pragma unroll
;         for (int j = 0; j < 4; ++j) acc[2][j] = __builtin_amdgcn_mfma_f32_16x16x32_bf16(fb[j], fa[2], acc[2][j], 0, 0, 0);
;         __builtin_amdgcn_sched_barrier(0);
;         if (wr_ok) *(uint4*)(nA + soff0 + 12288) = ra3;
;         if (ld_ok) ra3 = *(const uint4*)(Ab + (aoff + 96u * LDA + koa));
;         ga[3] = *(const bf16x8*)(sA + arow_off + 3 * 2048 + ch1); gb[3] = *(const bf16x8*)(sB + brow_off + 3 * 2048 + ch1);
;         __builtin_amdgcn_sched_barrier(0);
; #pragma unroll
;         for (int j = 0; j < 4; ++j) acc[3][j] = __builtin_amdgcn_mfma_f32_16x16x32_bf16(fb[j], fa[3], acc[3][j], 0, 0, 0);
;         __builtin_amdgcn_sched_barrier(0);
;         if (wr_ok) *(uint4*)(nB + soff0) = rb0;
	ds_read_b128 v[84:87], v6
	ds_read_b128 v[108:111], v6 offset:2048
	ds_read_b128 v[124:127], v7 offset:16384
	ds_read_b128 v[132:135], v7 offset:18432
	ds_read_b128 v[146:149], v6 offset:4096
	ds_read_b128 v[154:157], v6 offset:6144
	ds_read_b128 v[158:161], v7 offset:20480
	ds_read_b128 v[162:165], v7 offset:22528
	s_setprio 2
	s_add_u32 s92, s92, 0x80
	s_addc_u32 s93, s93, 0
	s_add_u32 s94, s94, 0x80
	s_addc_u32 s95, s95, 0
	s_add_u32 m0, s96, 0x8000
	ds_read_b128 v[170:173], v3
	global_load_lds_dwordx4 v240, s[92:93]
	s_add_u32 m0, s96, 0x9000
	ds_read_b128 v[174:177], v4 offset:16384
	global_load_lds_dwordx4 v241, s[92:93]
	s_add_u32 m0, s96, 0xa000
	s_waitcnt lgkmcnt(7)
	global_load_lds_dwordx4 v242, s[92:93]
	s_add_u32 m0, s96, 0xb000
	v_mfma_f32_16x16x32_bf16 v[26:29], v[124:127], v[84:87], v[26:29]
	global_load_lds_dwordx4 v243, s[92:93]
	s_add_u32 m0, s96, 0xc000
	s_waitcnt lgkmcnt(2)
	global_load_lds_dwordx4 v244, s[94:95]
	s_add_u32 m0, s96, 0xd000
	v_mfma_f32_16x16x32_bf16 v[10:13], v[162:165], v[84:87], v[10:13]
	global_load_lds_dwordx4 v245, s[94:95]
	s_add_u32 m0, s96, 0xe000
	v_mfma_f32_16x16x32_bf16 v[88:91], v[132:135], v[84:87], v[88:91]
	global_load_lds_dwordx4 v246, s[94:95]
	s_add_u32 m0, s96, 0xf000
	v_mfma_f32_16x16x32_bf16 v[96:99], v[158:161], v[84:87], v[96:99]
	global_load_lds_dwordx4 v247, s[94:95]
	v_mfma_f32_16x16x32_bf16 v[30:33], v[124:127], v[108:111], v[30:33]
	v_mfma_f32_16x16x32_bf16 v[42:45], v[132:135], v[108:111], v[42:45]
	ds_read_b128 v[104:107], v3 offset:2048
	v_mfma_f32_16x16x32_bf16 v[14:17], v[162:165], v[108:111], v[14:17]
	ds_read_b128 v[178:181], v4 offset:18432
	v_mfma_f32_16x16x32_bf16 v[92:95], v[158:161], v[108:111], v[92:95]
	v_mfma_f32_16x16x32_bf16 v[34:37], v[124:127], v[146:149], v[34:37]
	v_mfma_f32_16x16x32_bf16 v[46:49], v[132:135], v[146:149], v[46:49]
	ds_read_b128 v[112:115], v3 offset:4096
	v_mfma_f32_16x16x32_bf16 v[58:61], v[158:161], v[146:149], v[58:61]
	ds_read_b128 v[182:185], v4 offset:20480
	v_mfma_f32_16x16x32_bf16 v[18:21], v[162:165], v[146:149], v[18:21]
	v_mfma_f32_16x16x32_bf16 v[38:41], v[124:127], v[154:157], v[38:41]
	v_mfma_f32_16x16x32_bf16 v[50:53], v[132:135], v[154:157], v[50:53]
	ds_read_b128 v[150:153], v3 offset:6144
	v_mfma_f32_16x16x32_bf16 v[54:57], v[158:161], v[154:157], v[54:57]
	ds_read_b128 v[186:189], v4 offset:22528
	v_mfma_f32_16x16x32_bf16 v[22:25], v[162:165], v[154:157], v[22:25]
	s_waitcnt lgkmcnt(6)
	v_mfma_f32_16x16x32_bf16 v[26:29], v[174:177], v[170:173], v[26:29]
	s_waitcnt lgkmcnt(0)
	v_mfma_f32_16x16x32_bf16 v[10:13], v[186:189], v[170:173], v[10:13]
	v_mfma_f32_16x16x32_bf16 v[88:91], v[178:181], v[170:173], v[88:91]
	v_mfma_f32_16x16x32_bf16 v[96:99], v[182:185], v[170:173], v[96:99]
	v_mfma_f32_16x16x32_bf16 v[30:33], v[174:177], v[104:107], v[30:33]
	v_mfma_f32_16x16x32_bf16 v[42:45], v[178:181], v[104:107], v[42:45]
	v_mfma_f32_16x16x32_bf16 v[14:17], v[186:189], v[104:107], v[14:17]
	v_mfma_f32_16x16x32_bf16 v[92:95], v[182:185], v[104:107], v[92:95]
	v_mfma_f32_16x16x32_bf16 v[34:37], v[174:177], v[112:115], v[34:37]
	v_mfma_f32_16x16x32_bf16 v[46:49], v[178:181], v[112:115], v[46:49]
	v_mfma_f32_16x16x32_bf16 v[58:61], v[182:185], v[112:115], v[58:61]
	v_mfma_f32_16x16x32_bf16 v[18:21], v[186:189], v[112:115], v[18:21]
	v_mfma_f32_16x16x32_bf16 v[38:41], v[174:177], v[150:153], v[38:41]
	v_mfma_f32_16x16x32_bf16 v[50:53], v[178:181], v[150:153], v[50:53]
	v_mfma_f32_16x16x32_bf16 v[54:57], v[182:185], v[150:153], v[54:57]
	v_mfma_f32_16x16x32_bf16 v[22:25], v[186:189], v[150:153], v[22:25]
	s_setprio 0
	s_waitcnt vmcnt(0) lgkmcnt(0)
	s_barrier
	ds_read_b128 v[100:103], v6 offset:32768
	ds_read_b128 v[112:115], v6 offset:34816
	ds_read_b128 v[116:119], v7 offset:49152
	ds_read_b128 v[132:135], v7 offset:51200
	ds_read_b128 v[150:153], v6 offset:36864
	ds_read_b128 v[154:157], v6 offset:38912
	ds_read_b128 v[158:161], v7 offset:53248
	ds_read_b128 v[162:165], v7 offset:55296
	s_setprio 2
	s_add_u32 s92, s92, 0x80
	s_addc_u32 s93, s93, 0
	s_add_u32 s94, s94, 0x80
	s_addc_u32 s95, s95, 0
	s_mov_b32 m0, s96
	ds_read_b128 v[166:169], v3 offset:32768
	global_load_lds_dwordx4 v240, s[92:93]
	s_add_u32 m0, s96, 0x1000
	ds_read_b128 v[174:177], v4 offset:49152
	global_load_lds_dwordx4 v241, s[92:93]
	s_add_u32 m0, s96, 0x2000
	s_waitcnt lgkmcnt(7)
	global_load_lds_dwordx4 v242, s[92:93]
	s_add_u32 m0, s96, 0x3000
	v_mfma_f32_16x16x32_bf16 v[26:29], v[116:119], v[100:103], v[26:29]
	global_load_lds_dwordx4 v243, s[92:93]
	s_add_u32 m0, s96, 0x4000
	s_waitcnt lgkmcnt(2)
	global_load_lds_dwordx4 v244, s[94:95]
	s_add_u32 m0, s96, 0x5000
	v_mfma_f32_16x16x32_bf16 v[10:13], v[162:165], v[100:103], v[10:13]
	global_load_lds_dwordx4 v245, s[94:95]
	s_add_u32 m0, s96, 0x6000
	v_mfma_f32_16x16x32_bf16 v[88:91], v[132:135], v[100:103], v[88:91]
	global_load_lds_dwordx4 v246, s[94:95]
	s_add_u32 m0, s96, 0x7000
	v_mfma_f32_16x16x32_bf16 v[96:99], v[158:161], v[100:103], v[96:99]
	global_load_lds_dwordx4 v247, s[94:95]
	v_mfma_f32_16x16x32_bf16 v[30:33], v[116:119], v[112:115], v[30:33]
	v_mfma_f32_16x16x32_bf16 v[42:45], v[132:135], v[112:115], v[42:45]
	ds_read_b128 v[84:87], v3 offset:34816
	v_mfma_f32_16x16x32_bf16 v[14:17], v[162:165], v[112:115], v[14:17]
	ds_read_b128 v[178:181], v4 offset:51200
	v_mfma_f32_16x16x32_bf16 v[92:95], v[158:161], v[112:115], v[92:95]
	v_mfma_f32_16x16x32_bf16 v[34:37], v[116:119], v[150:153], v[34:37]
	v_mfma_f32_16x16x32_bf16 v[46:49], v[132:135], v[150:153], v[46:49]
	ds_read_b128 v[108:111], v3 offset:36864
	v_mfma_f32_16x16x32_bf16 v[58:61], v[158:161], v[150:153], v[58:61]
	ds_read_b128 v[182:185], v4 offset:53248
	v_mfma_f32_16x16x32_bf16 v[18:21], v[162:165], v[150:153], v[18:21]
	v_mfma_f32_16x16x32_bf16 v[38:41], v[116:119], v[154:157], v[38:41]
	v_mfma_f32_16x16x32_bf16 v[50:53], v[132:135], v[154:157], v[50:53]
	ds_read_b128 v[146:149], v3 offset:38912
	v_mfma_f32_16x16x32_bf16 v[54:57], v[158:161], v[154:157], v[54:57]
	ds_read_b128 v[186:189], v4 offset:55296
	v_mfma_f32_16x16x32_bf16 v[22:25], v[162:165], v[154:157], v[22:25]
	s_waitcnt lgkmcnt(6)
; template <int MODE>
; __device__ __forceinline__ void gemm_tile(const Params& P, int tm, int tn, unsigned char* smem) {
;     ...
; #pragma unroll
;         for (int i = 0; i < 4; ++i) { fa[i] = *(const bf16x8*)(sA + arow_off + i * 2048 + ch0); fb[i] = *(const bf16x8*)(sB + brow_off + i * 2048 + ch0); }
;         __builtin_amdgcn_sched_barrier(0);
;         __builtin_amdgcn_s_setprio(2);
;         if (wr_ok) *(uint4*)(nA + soff0) = ra0;
;         if (ld_ok) ra0 = *(const uint4*)(Ab + (aoff + 0u * LDA + koa));
;         ga[0] = *(const bf16x8*)(sA + arow_off + 0 * 2048 + ch1); gb[0] = *(const bf16x8*)(sB + brow_off + 0 * 2048 + ch1);
;         __builtin_amdgcn_sched_barrier(0);
; #pragma unroll
;         for (int j = 0; j < 4; ++j) acc[0][j] = __builtin_amdgcn_mfma_f32_16x16x32_bf16(fb[j], fa[0], acc[0][j], 0, 0, 0);
;         __builtin_amdgcn_sched_barrier(0);
;         if (wr_ok) *(uint4*)(nA + soff0 + 4096) = ra1;
;         if (ld_ok) ra1 = *(const uint4*)(Ab + (aoff + 32u * LDA + koa));
;         ga[1] = *(const bf16x8*)(sA + arow_off + 1 * 2048 + ch1); gb[1] = *(const bf16x8*)(sB + brow_off + 1 * 2048 + ch1);
;         __builtin_amdgcn_sched_barrier(0);
; #pragma unroll
;         for (int j = 0; j < 4; ++j) acc[1][j] = __builtin_amdgcn_mfma_f32_16x16x32_bf16(fb[j], fa[1], acc[1][j], 0, 0, 0);
;         __builtin_amdgcn_sched_barrier(0);
;         if (wr_ok) *(uint4*)(nA + soff0 + 8192) = ra2;
;         if (ld_ok) ra2 = *(const uint4*)(Ab + (aoff + 64u * LDA + koa));
;         ga[2] = *(const bf16x8*)(sA + arow_off + 2 * 2048 + ch1); gb[2] = *(const bf16x8*)(sB + brow_off + 2 * 2048 + ch1);
;         __builtin_amdgcn_sched_barrier(0);
; #pragma unroll
;         for (int j = 0; j < 4; ++j) acc[2][j] = __builtin_amdgcn_mfma_f32_16x16x32_bf16(fb[j], fa[2], acc[2][j], 0, 0, 0);
;         __builtin_amdgcn_sched_barrier(0);
;         if (wr_ok) *(uint4*)(nA + soff0 + 12288) = ra3;
;         if (ld_ok) ra3 = *(const uint4*)(Ab + (aoff + 96u * LDA + koa));
;         ga[3] = *(const bf16x8*)(sA + arow_off + 3 * 2048 + ch1); gb[3] = *(const bf16x8*)(sB + brow_off + 3 * 2048 + ch1);
;         __builtin_amdgcn_sched_barrier(0);
; #pragma unroll
;         for (int j = 0; j < 4; ++j) acc[3][j] = __builtin_amdgcn_mfma_f32_16x16x32_bf16(fb[j], fa[3], acc[3][j], 0, 0, 0);
;         __builtin_amdgcn_sched_barrier(0);
;         if (wr_ok) *(uint4*)(nB + soff0) = rb0;
	v_mfma_f32_16x16x32_bf16 v[26:29], v[174:177], v[166:169], v[26:29]
	s_waitcnt lgkmcnt(0)
	v_mfma_f32_16x16x32_bf16 v[10:13], v[186:189], v[166:169], v[10:13]
	v_mfma_f32_16x16x32_bf16 v[88:91], v[178:181], v[166:169], v[88:91]
	v_mfma_f32_16x16x32_bf16 v[96:99], v[182:185], v[166:169], v[96:99]
	v_mfma_f32_16x16x32_bf16 v[30:33], v[174:177], v[84:87], v[30:33]
	v_mfma_f32_16x16x32_bf16 v[42:45], v[178:181], v[84:87], v[42:45]
	v_mfma_f32_16x16x32_bf16 v[14:17], v[186:189], v[84:87], v[14:17]
	v_mfma_f32_16x16x32_bf16 v[92:95], v[182:185], v[84:87], v[92:95]
	v_mfma_f32_16x16x32_bf16 v[34:37], v[174:177], v[108:111], v[34:37]
	v_mfma_f32_16x16x32_bf16 v[46:49], v[178:181], v[108:111], v[46:49]
	v_mfma_f32_16x16x32_bf16 v[58:61], v[182:185], v[108:111], v[58:61]
	v_mfma_f32_16x16x32_bf16 v[18:21], v[186:189], v[108:111], v[18:21]
	v_mfma_f32_16x16x32_bf16 v[38:41], v[174:177], v[146:149], v[38:41]
	v_mfma_f32_16x16x32_bf16 v[50:53], v[178:181], v[146:149], v[50:53]
	v_mfma_f32_16x16x32_bf16 v[54:57], v[182:185], v[146:149], v[54:57]
	v_mfma_f32_16x16x32_bf16 v[22:25], v[186:189], v[146:149], v[22:25]
	s_setprio 0
	s_waitcnt vmcnt(0) lgkmcnt(0)
	s_barrier
	ds_read_b128 v[62:65], v6
	ds_read_b128 v[108:111], v6 offset:2048
	ds_read_b128 v[120:123], v7 offset:16384
	ds_read_b128 v[132:135], v7 offset:18432
	ds_read_b128 v[146:149], v6 offset:4096
	ds_read_b128 v[154:157], v6 offset:6144
	ds_read_b128 v[158:161], v7 offset:20480
	ds_read_b128 v[162:165], v7 offset:22528
	s_setprio 2
	s_add_u32 s92, s92, 0x80
	s_addc_u32 s93, s93, 0
	s_add_u32 s94, s94, 0x80
	s_addc_u32 s95, s95, 0
	s_add_u32 m0, s96, 0x8000
	ds_read_b128 v[170:173], v3
	global_load_lds_dwordx4 v240, s[92:93]
	s_add_u32 m0, s96, 0x9000
	ds_read_b128 v[174:177], v4 offset:16384
	global_load_lds_dwordx4 v241, s[92:93]
	s_add_u32 m0, s96, 0xa000
	s_waitcnt lgkmcnt(7)
	global_load_lds_dwordx4 v242, s[92:93]
	s_add_u32 m0, s96, 0xb000
	v_mfma_f32_16x16x32_bf16 v[26:29], v[120:123], v[62:65], v[26:29]
	global_load_lds_dwordx4 v243, s[92:93]
	s_add_u32 m0, s96, 0xc000
	s_waitcnt lgkmcnt(2)
	global_load_lds_dwordx4 v244, s[94:95]
	s_add_u32 m0, s96, 0xd000
	v_mfma_f32_16x16x32_bf16 v[10:13], v[162:165], v[62:65], v[10:13]
	global_load_lds_dwordx4 v245, s[94:95]
	s_add_u32 m0, s96, 0xe000
	v_mfma_f32_16x16x32_bf16 v[88:91], v[132:135], v[62:65], v[88:91]
	global_load_lds_dwordx4 v246, s[94:95]
	s_add_u32 m0, s96, 0xf000
	v_mfma_f32_16x16x32_bf16 v[96:99], v[158:161], v[62:65], v[96:99]
	global_load_lds_dwordx4 v247, s[94:95]
	v_mfma_f32_16x16x32_bf16 v[30:33], v[120:123], v[108:111], v[30:33]
	v_mfma_f32_16x16x32_bf16 v[42:45], v[132:135], v[108:111], v[42:45]
	ds_read_b128 v[100:103], v3 offset:2048
	v_mfma_f32_16x16x32_bf16 v[14:17], v[162:165], v[108:111], v[14:17]
	ds_read_b128 v[178:181], v4 offset:18432
	v_mfma_f32_16x16x32_bf16 v[92:95], v[158:161], v[108:111], v[92:95]
	v_mfma_f32_16x16x32_bf16 v[34:37], v[120:123], v[146:149], v[34:37]
	v_mfma_f32_16x16x32_bf16 v[46:49], v[132:135], v[146:149], v[46:49]
	ds_read_b128 v[112:115], v3 offset:4096
	v_mfma_f32_16x16x32_bf16 v[58:61], v[158:161], v[146:149], v[58:61]
	ds_read_b128 v[182:185], v4 offset:20480
	v_mfma_f32_16x16x32_bf16 v[18:21], v[162:165], v[146:149], v[18:21]
	v_mfma_f32_16x16x32_bf16 v[38:41], v[120:123], v[154:157], v[38:41]
	v_mfma_f32_16x16x32_bf16 v[50:53], v[132:135], v[154:157], v[50:53]
	ds_read_b128 v[150:153], v3 offset:6144
	v_mfma_f32_16x16x32_bf16 v[54:57], v[158:161], v[154:157], v[54:57]
	ds_read_b128 v[186:189], v4 offset:22528
	v_mfma_f32_16x16x32_bf16 v[22:25], v[162:165], v[154:157], v[22:25]
	s_waitcnt lgkmcnt(6)
	v_mfma_f32_16x16x32_bf16 v[26:29], v[174:177], v[170:173], v[26:29]
	s_waitcnt lgkmcnt(0)
	v_mfma_f32_16x16x32_bf16 v[10:13], v[186:189], v[170:173], v[10:13]
	v_mfma_f32_16x16x32_bf16 v[88:91], v[178:181], v[170:173], v[88:91]
	v_mfma_f32_16x16x32_bf16 v[96:99], v[182:185], v[170:173], v[96:99]
	v_mfma_f32_16x16x32_bf16 v[30:33], v[174:177], v[100:103], v[30:33]
	v_mfma_f32_16x16x32_bf16 v[42:45], v[178:181], v[100:103], v[42:45]
	v_mfma_f32_16x16x32_bf16 v[14:17], v[186:189], v[100:103], v[14:17]
	v_mfma_f32_16x16x32_bf16 v[92:95], v[182:185], v[100:103], v[92:95]
	v_mfma_f32_16x16x32_bf16 v[34:37], v[174:177], v[112:115], v[34:37]
	v_mfma_f32_16x16x32_bf16 v[46:49], v[178:181], v[112:115], v[46:49]
	v_mfma_f32_16x16x32_bf16 v[58:61], v[182:185], v[112:115], v[58:61]
	v_mfma_f32_16x16x32_bf16 v[18:21], v[186:189], v[112:115], v[18:21]
	v_mfma_f32_16x16x32_bf16 v[38:41], v[174:177], v[150:153], v[38:41]
	v_mfma_f32_16x16x32_bf16 v[50:53], v[178:181], v[150:153], v[50:53]
	v_mfma_f32_16x16x32_bf16 v[54:57], v[182:185], v[150:153], v[54:57]
	v_mfma_f32_16x16x32_bf16 v[22:25], v[186:189], v[150:153], v[22:25]
	s_setprio 0
	s_waitcnt vmcnt(0) lgkmcnt(0)
	s_barrier
; template <int MODE>
; __device__ __forceinline__ void gemm_tile(const Params& P, int tm, int tn, unsigned char* smem) {
;     ...
; #pragma unroll
;         for (int i = 0; i < 4; ++i) { fa[i] = *(const bf16x8*)(sA + arow_off + i * 2048 + ch0); fb[i] = *(const bf16x8*)(sB + brow_off + i * 2048 + ch0); }
;         __builtin_amdgcn_sched_barrier(0);
;         __builtin_amdgcn_s_setprio(2);
;         if (wr_ok) *(uint4*)(nA + soff0) = ra0;
;         if (ld_ok) ra0 = *(const uint4*)(Ab + (aoff + 0u * LDA + koa));
;         ga[0] = *(const bf16x8*)(sA + arow_off + 0 * 2048 + ch1); gb[0] = *(const bf16x8*)(sB + brow_off + 0 * 2048 + ch1);
;         __builtin_amdgcn_sched_barrier(0);
; #pragma unroll
;         for (int j = 0; j < 4; ++j) acc[0][j] = __builtin_amdgcn_mfma_f32_16x16x32_bf16(fb[j], fa[0], acc[0][j], 0, 0, 0);
;         __builtin_amdgcn_sched_barrier(0);
;         if (wr_ok) *(uint4*)(nA + soff0 + 4096) = ra1;
;         if (ld_ok) ra1 = *(const uint4*)(Ab + (aoff + 32u * LDA + koa));
;         ga[1] = *(const bf16x8*)(sA + arow_off + 1 * 2048 + ch1); gb[1] = *(const bf16x8*)(sB + brow_off + 1 * 2048 + ch1);
;         __builtin_amdgcn_sched_barrier(0);
; #pragma unroll
;         for (int j = 0; j < 4; ++j) acc[1][j] = __builtin_amdgcn_mfma_f32_16x16x32_bf16(fb[j], fa[1], acc[1][j], 0, 0, 0);
;         __builtin_amdgcn_sched_barrier(0);
;         if (wr_ok) *(uint4*)(nA + soff0 + 8192) = ra2;
;         if (ld_ok) ra2 = *(const uint4*)(Ab + (aoff + 64u * LDA + koa));
;         ga[2] = *(const bf16x8*)(sA + arow_off + 2 * 2048 + ch1); gb[2] = *(const bf16x8*)(sB + brow_off + 2 * 2048 + ch1);
;         __builtin_amdgcn_sched_barrier(0);
; #pragma unroll
;         for (int j = 0; j < 4; ++j) acc[2][j] = __builtin_amdgcn_mfma_f32_16x16x32_bf16(fb[j], fa[2], acc[2][j], 0, 0, 0);
;         __builtin_amdgcn_sched_barrier(0);
;         if (wr_ok) *(uint4*)(nA + soff0 + 12288) = ra3;
;         if (ld_ok) ra3 = *(const uint4*)(Ab + (aoff + 96u * LDA + koa));
;         ga[3] = *(const bf16x8*)(sA + arow_off + 3 * 2048 + ch1); gb[3] = *(const bf16x8*)(sB + brow_off + 3 * 2048 + ch1);
;         __builtin_amdgcn_sched_barrier(0);
; #pragma unroll
;         for (int j = 0; j < 4; ++j) acc[3][j] = __builtin_amdgcn_mfma_f32_16x16x32_bf16(fb[j], fa[3], acc[3][j], 0, 0, 0);
;         __builtin_amdgcn_sched_barrier(0);
;         if (wr_ok) *(uint4*)(nB + soff0) = rb0;
	ds_read_b128 v[104:107], v6 offset:32768
	ds_read_b128 v[112:115], v6 offset:34816
	ds_read_b128 v[124:127], v7 offset:49152
	ds_read_b128 v[132:135], v7 offset:51200
	ds_read_b128 v[150:153], v6 offset:36864
	ds_read_b128 v[154:157], v6 offset:38912
	ds_read_b128 v[158:161], v7 offset:53248
	ds_read_b128 v[162:165], v7 offset:55296
	s_setprio 2
	s_add_u32 s92, s92, 0x80
	s_addc_u32 s93, s93, 0
	s_add_u32 s94, s94, 0x80
	s_addc_u32 s95, s95, 0
	s_mov_b32 m0, s96
	ds_read_b128 v[166:169], v3 offset:32768
	global_load_lds_dwordx4 v240, s[92:93]
	s_add_u32 m0, s96, 0x1000
	ds_read_b128 v[174:177], v4 offset:49152
	global_load_lds_dwordx4 v241, s[92:93]
	s_add_u32 m0, s96, 0x2000
	s_waitcnt lgkmcnt(7)
	global_load_lds_dwordx4 v242, s[92:93]
	s_add_u32 m0, s96, 0x3000
	v_mfma_f32_16x16x32_bf16 v[26:29], v[124:127], v[104:107], v[26:29]
	global_load_lds_dwordx4 v243, s[92:93]
	s_add_u32 m0, s96, 0x4000
	s_waitcnt lgkmcnt(2)
	global_load_lds_dwordx4 v244, s[94:95]
	s_add_u32 m0, s96, 0x5000
	v_mfma_f32_16x16x32_bf16 v[10:13], v[162:165], v[104:107], v[10:13]
	global_load_lds_dwordx4 v245, s[94:95]
	s_add_u32 m0, s96, 0x6000
	v_mfma_f32_16x16x32_bf16 v[88:91], v[132:135], v[104:107], v[88:91]
	global_load_lds_dwordx4 v246, s[94:95]
	s_add_u32 m0, s96, 0x7000
	v_mfma_f32_16x16x32_bf16 v[96:99], v[158:161], v[104:107], v[96:99]
	global_load_lds_dwordx4 v247, s[94:95]
	v_mfma_f32_16x16x32_bf16 v[30:33], v[124:127], v[112:115], v[30:33]
	v_mfma_f32_16x16x32_bf16 v[42:45], v[132:135], v[112:115], v[42:45]
	ds_read_b128 v[62:65], v3 offset:34816
	v_mfma_f32_16x16x32_bf16 v[14:17], v[162:165], v[112:115], v[14:17]
	ds_read_b128 v[178:181], v4 offset:51200
	v_mfma_f32_16x16x32_bf16 v[92:95], v[158:161], v[112:115], v[92:95]
	v_mfma_f32_16x16x32_bf16 v[34:37], v[124:127], v[150:153], v[34:37]
	v_mfma_f32_16x16x32_bf16 v[46:49], v[132:135], v[150:153], v[46:49]
	ds_read_b128 v[108:111], v3 offset:36864
	v_mfma_f32_16x16x32_bf16 v[58:61], v[158:161], v[150:153], v[58:61]
	ds_read_b128 v[182:185], v4 offset:53248
	v_mfma_f32_16x16x32_bf16 v[18:21], v[162:165], v[150:153], v[18:21]
	v_mfma_f32_16x16x32_bf16 v[38:41], v[124:127], v[154:157], v[38:41]
	v_mfma_f32_16x16x32_bf16 v[50:53], v[132:135], v[154:157], v[50:53]
	ds_read_b128 v[146:149], v3 offset:38912
	v_mfma_f32_16x16x32_bf16 v[54:57], v[158:161], v[154:157], v[54:57]
	ds_read_b128 v[186:189], v4 offset:55296
	v_mfma_f32_16x16x32_bf16 v[22:25], v[162:165], v[154:157], v[22:25]
	s_waitcnt lgkmcnt(6)
	v_mfma_f32_16x16x32_bf16 v[26:29], v[174:177], v[166:169], v[26:29]
	s_waitcnt lgkmcnt(0)
	v_mfma_f32_16x16x32_bf16 v[10:13], v[186:189], v[166:169], v[10:13]
	v_mfma_f32_16x16x32_bf16 v[88:91], v[178:181], v[166:169], v[88:91]
	v_mfma_f32_16x16x32_bf16 v[96:99], v[182:185], v[166:169], v[96:99]
	v_mfma_f32_16x16x32_bf16 v[30:33], v[174:177], v[62:65], v[30:33]
	v_mfma_f32_16x16x32_bf16 v[42:45], v[178:181], v[62:65], v[42:45]
	v_mfma_f32_16x16x32_bf16 v[14:17], v[186:189], v[62:65], v[14:17]
	v_mfma_f32_16x16x32_bf16 v[92:95], v[182:185], v[62:65], v[92:95]
	v_mfma_f32_16x16x32_bf16 v[34:37], v[174:177], v[108:111], v[34:37]
	v_mfma_f32_16x16x32_bf16 v[46:49], v[178:181], v[108:111], v[46:49]
	v_mfma_f32_16x16x32_bf16 v[58:61], v[182:185], v[108:111], v[58:61]
	v_mfma_f32_16x16x32_bf16 v[18:21], v[186:189], v[108:111], v[18:21]
	v_mfma_f32_16x16x32_bf16 v[38:41], v[174:177], v[146:149], v[38:41]
	v_mfma_f32_16x16x32_bf16 v[50:53], v[178:181], v[146:149], v[50:53]
	v_mfma_f32_16x16x32_bf16 v[54:57], v[182:185], v[146:149], v[54:57]
	v_mfma_f32_16x16x32_bf16 v[22:25], v[186:189], v[146:149], v[22:25]
	s_setprio 0
	s_waitcnt vmcnt(0) lgkmcnt(0)
	s_barrier
	ds_read_b128 v[84:87], v6
	ds_read_b128 v[108:111], v6 offset:2048
	ds_read_b128 v[116:119], v7 offset:16384
	ds_read_b128 v[132:135], v7 offset:18432
	ds_read_b128 v[146:149], v6 offset:4096
	ds_read_b128 v[154:157], v6 offset:6144
	ds_read_b128 v[158:161], v7 offset:20480
	ds_read_b128 v[162:165], v7 offset:22528
	s_setprio 2
	s_add_u32 s92, s92, 0x80
	s_addc_u32 s93, s93, 0
	s_add_u32 s94, s94, 0x80
	s_addc_u32 s95, s95, 0
	s_add_u32 m0, s96, 0x8000
	ds_read_b128 v[170:173], v3
	global_load_lds_dwordx4 v240, s[92:93]
	s_add_u32 m0, s96, 0x9000
	ds_read_b128 v[174:177], v4 offset:16384
	global_load_lds_dwordx4 v241, s[92:93]
	s_add_u32 m0, s96, 0xa000
	s_waitcnt lgkmcnt(7)
	global_load_lds_dwordx4 v242, s[92:93]
	s_add_u32 m0, s96, 0xb000
	v_mfma_f32_16x16x32_bf16 v[26:29], v[116:119], v[84:87], v[26:29]
	global_load_lds_dwordx4 v243, s[92:93]
	s_add_u32 m0, s96, 0xc000
	s_waitcnt lgkmcnt(2)
	global_load_lds_dwordx4 v244, s[94:95]
	s_add_u32 m0, s96, 0xd000
	v_mfma_f32_16x16x32_bf16 v[10:13], v[162:165], v[84:87], v[10:13]
	global_load_lds_dwordx4 v245, s[94:95]
	s_add_u32 m0, s96, 0xe000
	v_mfma_f32_16x16x32_bf16 v[88:91], v[132:135], v[84:87], v[88:91]
	global_load_lds_dwordx4 v246, s[94:95]
	s_add_u32 m0, s96, 0xf000
	v_mfma_f32_16x16x32_bf16 v[96:99], v[158:161], v[84:87], v[96:99]
	global_load_lds_dwordx4 v247, s[94:95]
	v_mfma_f32_16x16x32_bf16 v[30:33], v[116:119], v[108:111], v[30:33]
	v_mfma_f32_16x16x32_bf16 v[42:45], v[132:135], v[108:111], v[42:45]
	ds_read_b128 v[104:107], v3 offset:2048
	v_mfma_f32_16x16x32_bf16 v[14:17], v[162:165], v[108:111], v[14:17]
	ds_read_b128 v[178:181], v4 offset:18432
	v_mfma_f32_16x16x32_bf16 v[92:95], v[158:161], v[108:111], v[92:95]
	v_mfma_f32_16x16x32_bf16 v[34:37], v[116:119], v[146:149], v[34:37]
	v_mfma_f32_16x16x32_bf16 v[46:49], v[132:135], v[146:149], v[46:49]
	ds_read_b128 v[112:115], v3 offset:4096
	v_mfma_f32_16x16x32_bf16 v[58:61], v[158:161], v[146:149], v[58:61]
	ds_read_b128 v[182:185], v4 offset:20480
	v_mfma_f32_16x16x32_bf16 v[18:21], v[162:165], v[146:149], v[18:21]
	v_mfma_f32_16x16x32_bf16 v[38:41], v[116:119], v[154:157], v[38:41]
	v_mfma_f32_16x16x32_bf16 v[50:53], v[132:135], v[154:157], v[50:53]
	ds_read_b128 v[150:153], v3 offset:6144
	v_mfma_f32_16x16x32_bf16 v[54:57], v[158:161], v[154:157], v[54:57]
	ds_read_b128 v[186:189], v4 offset:22528
	v_mfma_f32_16x16x32_bf16 v[22:25], v[162:165], v[154:157], v[22:25]
	s_waitcnt lgkmcnt(6)
; template <int MODE>
; __device__ __forceinline__ void gemm_tile(const Params& P, int tm, int tn, unsigned char* smem) {
;     ...
; #pragma unroll
;         for (int i = 0; i < 4; ++i) { fa[i] = *(const bf16x8*)(sA + arow_off + i * 2048 + ch0); fb[i] = *(const bf16x8*)(sB + brow_off + i * 2048 + ch0); }
;         __builtin_amdgcn_sched_barrier(0);
;         __builtin_amdgcn_s_setprio(2);
;         if (wr_ok) *(uint4*)(nA + soff0) = ra0;
;         if (ld_ok) ra0 = *(const uint4*)(Ab + (aoff + 0u * LDA + koa));
;         ga[0] = *(const bf16x8*)(sA + arow_off + 0 * 2048 + ch1); gb[0] = *(const bf16x8*)(sB + brow_off + 0 * 2048 + ch1);
;         __builtin_amdgcn_sched_barrier(0);
; #pragma unroll
;         for (int j = 0; j < 4; ++j) acc[0][j] = __builtin_amdgcn_mfma_f32_16x16x32_bf16(fb[j], fa[0], acc[0][j], 0, 0, 0);
;         __builtin_amdgcn_sched_barrier(0);
;         if (wr_ok) *(uint4*)(nA + soff0 + 4096) = ra1;
;         if (ld_ok) ra1 = *(const uint4*)(Ab + (aoff + 32u * LDA + koa));
;         ga[1] = *(const bf16x8*)(sA + arow_off + 1 * 2048 + ch1); gb[1] = *(const bf16x8*)(sB + brow_off + 1 * 2048 + ch1);
;         __builtin_amdgcn_sched_barrier(0);
; #pragma unroll
;         for (int j = 0; j < 4; ++j) acc[1][j] = __builtin_amdgcn_mfma_f32_16x16x32_bf16(fb[j], fa[1], acc[1][j], 0, 0, 0);
;         __builtin_amdgcn_sched_barrier(0);
;         if (wr_ok) *(uint4*)(nA + soff0 + 8192) = ra2;
;         if (ld_ok) ra2 = *(const uint4*)(Ab + (aoff + 64u * LDA + koa));
;         ga[2] = *(const bf16x8*)(sA + arow_off + 2 * 2048 + ch1); gb[2] = *(const bf16x8*)(sB + brow_off + 2 * 2048 + ch1);
;         __builtin_amdgcn_sched_barrier(0);
; #pragma unroll
;         for (int j = 0; j < 4; ++j) acc[2][j] = __builtin_amdgcn_mfma_f32_16x16x32_bf16(fb[j], fa[2], acc[2][j], 0, 0, 0);
;         __builtin_amdgcn_sched_barrier(0);
;         if (wr_ok) *(uint4*)(nA + soff0 + 12288) = ra3;
;         if (ld_ok) ra3 = *(const uint4*)(Ab + (aoff + 96u * LDA + koa));
;         ga[3] = *(const bf16x8*)(sA + arow_off + 3 * 2048 + ch1); gb[3] = *(const bf16x8*)(sB + brow_off + 3 * 2048 + ch1);
;         __builtin_amdgcn_sched_barrier(0);
; #pragma unroll
;         for (int j = 0; j < 4; ++j) acc[3][j] = __builtin_amdgcn_mfma_f32_16x16x32_bf16(fb[j], fa[3], acc[3][j], 0, 0, 0);
;         __builtin_amdgcn_sched_barrier(0);
;         if (wr_ok) *(uint4*)(nB + soff0) = rb0;
	v_mfma_f32_16x16x32_bf16 v[26:29], v[174:177], v[170:173], v[26:29]
	s_waitcnt lgkmcnt(0)
	v_mfma_f32_16x16x32_bf16 v[10:13], v[186:189], v[170:173], v[10:13]
	v_mfma_f32_16x16x32_bf16 v[88:91], v[178:181], v[170:173], v[88:91]
	v_mfma_f32_16x16x32_bf16 v[96:99], v[182:185], v[170:173], v[96:99]
	v_mfma_f32_16x16x32_bf16 v[30:33], v[174:177], v[104:107], v[30:33]
	v_mfma_f32_16x16x32_bf16 v[42:45], v[178:181], v[104:107], v[42:45]
	v_mfma_f32_16x16x32_bf16 v[14:17], v[186:189], v[104:107], v[14:17]
	v_mfma_f32_16x16x32_bf16 v[92:95], v[182:185], v[104:107], v[92:95]
	v_mfma_f32_16x16x32_bf16 v[34:37], v[174:177], v[112:115], v[34:37]
	v_mfma_f32_16x16x32_bf16 v[46:49], v[178:181], v[112:115], v[46:49]
	v_mfma_f32_16x16x32_bf16 v[58:61], v[182:185], v[112:115], v[58:61]
	v_mfma_f32_16x16x32_bf16 v[18:21], v[186:189], v[112:115], v[18:21]
	v_mfma_f32_16x16x32_bf16 v[38:41], v[174:177], v[150:153], v[38:41]
	v_mfma_f32_16x16x32_bf16 v[50:53], v[178:181], v[150:153], v[50:53]
	v_mfma_f32_16x16x32_bf16 v[54:57], v[182:185], v[150:153], v[54:57]
	v_mfma_f32_16x16x32_bf16 v[22:25], v[186:189], v[150:153], v[22:25]
	s_setprio 0
	s_waitcnt vmcnt(0) lgkmcnt(0)
	s_barrier
	ds_read_b128 v[100:103], v6 offset:32768
	ds_read_b128 v[112:115], v6 offset:34816
	ds_read_b128 v[120:123], v7 offset:49152
	ds_read_b128 v[132:135], v7 offset:51200
	ds_read_b128 v[150:153], v6 offset:36864
	ds_read_b128 v[154:157], v6 offset:38912
	ds_read_b128 v[158:161], v7 offset:53248
	ds_read_b128 v[162:165], v7 offset:55296
	s_setprio 2
	s_add_u32 s92, s92, 0x80
	s_addc_u32 s93, s93, 0
	s_add_u32 s94, s94, 0x80
	s_addc_u32 s95, s95, 0
	s_mov_b32 m0, s96
	ds_read_b128 v[166:169], v3 offset:32768
	global_load_lds_dwordx4 v240, s[92:93]
	s_add_u32 m0, s96, 0x1000
	ds_read_b128 v[174:177], v4 offset:49152
	global_load_lds_dwordx4 v241, s[92:93]
	s_add_u32 m0, s96, 0x2000
	s_waitcnt lgkmcnt(7)
	global_load_lds_dwordx4 v242, s[92:93]
	s_add_u32 m0, s96, 0x3000
	v_mfma_f32_16x16x32_bf16 v[26:29], v[120:123], v[100:103], v[26:29]
	global_load_lds_dwordx4 v243, s[92:93]
	s_add_u32 m0, s96, 0x4000
	s_waitcnt lgkmcnt(2)
	global_load_lds_dwordx4 v244, s[94:95]
	s_add_u32 m0, s96, 0x5000
	v_mfma_f32_16x16x32_bf16 v[10:13], v[162:165], v[100:103], v[10:13]
	global_load_lds_dwordx4 v245, s[94:95]
	s_add_u32 m0, s96, 0x6000
	v_mfma_f32_16x16x32_bf16 v[88:91], v[132:135], v[100:103], v[88:91]
	global_load_lds_dwordx4 v246, s[94:95]
	s_add_u32 m0, s96, 0x7000
	v_mfma_f32_16x16x32_bf16 v[96:99], v[158:161], v[100:103], v[96:99]
	global_load_lds_dwordx4 v247, s[94:95]
	v_mfma_f32_16x16x32_bf16 v[30:33], v[120:123], v[112:115], v[30:33]
	v_mfma_f32_16x16x32_bf16 v[42:45], v[132:135], v[112:115], v[42:45]
	ds_read_b128 v[84:87], v3 offset:34816
	v_mfma_f32_16x16x32_bf16 v[14:17], v[162:165], v[112:115], v[14:17]
	ds_read_b128 v[178:181], v4 offset:51200
	v_mfma_f32_16x16x32_bf16 v[92:95], v[158:161], v[112:115], v[92:95]
	v_mfma_f32_16x16x32_bf16 v[34:37], v[120:123], v[150:153], v[34:37]
	v_mfma_f32_16x16x32_bf16 v[46:49], v[132:135], v[150:153], v[46:49]
	ds_read_b128 v[108:111], v3 offset:36864
	v_mfma_f32_16x16x32_bf16 v[58:61], v[158:161], v[150:153], v[58:61]
	ds_read_b128 v[182:185], v4 offset:53248
	v_mfma_f32_16x16x32_bf16 v[18:21], v[162:165], v[150:153], v[18:21]
	v_add_u32_e32 v8, 0x30780, v8
	ds_read_b128 v[146:149], v3 offset:38912
	ds_read_b128 v[186:189], v4 offset:55296
	v_mfma_f32_16x16x32_bf16 v[38:41], v[120:123], v[154:157], v[38:41]
	v_mfma_f32_16x16x32_bf16 v[50:53], v[132:135], v[154:157], v[50:53]
	v_mfma_f32_16x16x32_bf16 v[54:57], v[158:161], v[154:157], v[54:57]
	v_mfma_f32_16x16x32_bf16 v[22:25], v[162:165], v[154:157], v[22:25]
	s_waitcnt lgkmcnt(6)
	v_mfma_f32_16x16x32_bf16 v[26:29], v[174:177], v[166:169], v[26:29]
	s_waitcnt lgkmcnt(0)
	v_mfma_f32_16x16x32_bf16 v[8:11], v[186:189], v[166:169], v[10:13]
	v_mfma_f32_16x16x32_bf16 v[88:91], v[178:181], v[166:169], v[88:91]
	v_mfma_f32_16x16x32_bf16 v[96:99], v[182:185], v[166:169], v[96:99]
	s_nop 0
	v_mfma_f32_16x16x32_bf16 v[30:33], v[174:177], v[84:87], v[30:33]
	v_mfma_f32_16x16x32_bf16 v[42:45], v[178:181], v[84:87], v[42:45]
	v_mfma_f32_16x16x32_bf16 v[12:15], v[186:189], v[84:87], v[14:17]
	v_mfma_f32_16x16x32_bf16 v[92:95], v[182:185], v[84:87], v[92:95]
	s_nop 1
	v_mfma_f32_16x16x32_bf16 v[34:37], v[174:177], v[108:111], v[34:37]
	v_mfma_f32_16x16x32_bf16 v[46:49], v[178:181], v[108:111], v[46:49]
	v_mfma_f32_16x16x32_bf16 v[58:61], v[182:185], v[108:111], v[58:61]
	v_mfma_f32_16x16x32_bf16 v[16:19], v[186:189], v[108:111], v[18:21]
	v_add_u32_e32 v5, 0x30780, v5
	v_mfma_f32_16x16x32_bf16 v[38:41], v[174:177], v[146:149], v[38:41]
	v_mfma_f32_16x16x32_bf16 v[50:53], v[178:181], v[146:149], v[50:53]
	v_mfma_f32_16x16x32_bf16 v[54:57], v[182:185], v[146:149], v[54:57]
	v_mfma_f32_16x16x32_bf16 v[20:23], v[186:189], v[146:149], v[22:25]
	s_setprio 0
	s_waitcnt vmcnt(0) lgkmcnt(0)
	s_barrier
; template <int MODE>
; __device__ __forceinline__ void gemm_tile(const Params& P, int tm, int tn, unsigned char* smem) {
;     ...
; #pragma unroll
;         for (int i = 0; i < 4; ++i) { fa[i] = *(const bf16x8*)(sA + arow_off + i * 2048 + ch0); fb[i] = *(const bf16x8*)(sB + brow_off + i * 2048 + ch0); }
;         __builtin_amdgcn_sched_barrier(0);
;         __builtin_amdgcn_s_setprio(2);
;         if (wr_ok) *(uint4*)(nA + soff0) = ra0;
;         if (ld_ok) ra0 = *(const uint4*)(Ab + (aoff + 0u * LDA + koa));
;         ga[0] = *(const bf16x8*)(sA + arow_off + 0 * 2048 + ch1); gb[0] = *(const bf16x8*)(sB + brow_off + 0 * 2048 + ch1);
;         __builtin_amdgcn_sched_barrier(0);
; #pragma unroll
;         for (int j = 0; j < 4; ++j) acc[0][j] = __builtin_amdgcn_mfma_f32_16x16x32_bf16(fb[j], fa[0], acc[0][j], 0, 0, 0);
;         __builtin_amdgcn_sched_barrier(0);
;         if (wr_ok) *(uint4*)(nA + soff0 + 4096) = ra1;
;         if (ld_ok) ra1 = *(const uint4*)(Ab + (aoff + 32u * LDA + koa));
;         ga[1] = *(const bf16x8*)(sA + arow_off + 1 * 2048 + ch1); gb[1] = *(const bf16x8*)(sB + brow_off + 1 * 2048 + ch1);
;         __builtin_amdgcn_sched_barrier(0);
; #pragma unroll
;         for (int j = 0; j < 4; ++j) acc[1][j] = __builtin_amdgcn_mfma_f32_16x16x32_bf16(fb[j], fa[1], acc[1][j], 0, 0, 0);
;         __builtin_amdgcn_sched_barrier(0);
;         if (wr_ok) *(uint4*)(nA + soff0 + 8192) = ra2;
;         if (ld_ok) ra2 = *(const uint4*)(Ab + (aoff + 64u * LDA + koa));
;         ga[2] = *(const bf16x8*)(sA + arow_off + 2 * 2048 + ch1); gb[2] = *(const bf16x8*)(sB + brow_off + 2 * 2048 + ch1);
;         __builtin_amdgcn_sched_barrier(0);
; #pragma unroll
;         for (int j = 0; j < 4; ++j) acc[2][j] = __builtin_amdgcn_mfma_f32_16x16x32_bf16(fb[j], fa[2], acc[2][j], 0, 0, 0);
;         __builtin_amdgcn_sched_barrier(0);
;         if (wr_ok) *(uint4*)(nA + soff0 + 12288) = ra3;
;         if (ld_ok) ra3 = *(const uint4*)(Ab + (aoff + 96u * LDA + koa));
;         ga[3] = *(const bf16x8*)(sA + arow_off + 3 * 2048 + ch1); gb[3] = *(const bf16x8*)(sB + brow_off + 3 * 2048 + ch1);
;         __builtin_amdgcn_sched_barrier(0);
; #pragma unroll
;         for (int j = 0; j < 4; ++j) acc[3][j] = __builtin_amdgcn_mfma_f32_16x16x32_bf16(fb[j], fa[3], acc[3][j], 0, 0, 0);
;         __builtin_amdgcn_sched_barrier(0);
;         if (wr_ok) *(uint4*)(nB + soff0) = rb0;
	ds_read_b128 v[62:65], v6
	ds_read_b128 v[108:111], v6 offset:2048
	ds_read_b128 v[124:127], v7 offset:16384
	ds_read_b128 v[132:135], v7 offset:18432
	ds_read_b128 v[146:149], v6 offset:4096
	ds_read_b128 v[154:157], v6 offset:6144
	ds_read_b128 v[158:161], v7 offset:20480
	ds_read_b128 v[162:165], v7 offset:22528
	s_setprio 2
	s_add_u32 s92, s92, 0x80
	s_addc_u32 s93, s93, 0
	s_add_u32 s94, s94, 0x80
	s_addc_u32 s95, s95, 0
	s_add_u32 m0, s96, 0x8000
	ds_read_b128 v[166:169], v3
	global_load_lds_dwordx4 v240, s[92:93]
	s_add_u32 m0, s96, 0x9000
	ds_read_b128 v[170:173], v4 offset:16384
	global_load_lds_dwordx4 v241, s[92:93]
	s_add_u32 m0, s96, 0xa000
	s_waitcnt lgkmcnt(7)
	global_load_lds_dwordx4 v242, s[92:93]
	s_add_u32 m0, s96, 0xb000
	v_mfma_f32_16x16x32_bf16 v[24:27], v[124:127], v[62:65], v[26:29]
	global_load_lds_dwordx4 v243, s[92:93]
	s_add_u32 m0, s96, 0xc000
	s_waitcnt lgkmcnt(2)
	global_load_lds_dwordx4 v244, s[94:95]
	s_add_u32 m0, s96, 0xd000
	v_mfma_f32_16x16x32_bf16 v[8:11], v[162:165], v[62:65], v[8:11]
	global_load_lds_dwordx4 v245, s[94:95]
	s_add_u32 m0, s96, 0xe000
	v_mfma_f32_16x16x32_bf16 v[88:91], v[132:135], v[62:65], v[88:91]
	global_load_lds_dwordx4 v246, s[94:95]
	s_add_u32 m0, s96, 0xf000
	v_mfma_f32_16x16x32_bf16 v[96:99], v[158:161], v[62:65], v[96:99]
	global_load_lds_dwordx4 v247, s[94:95]
	v_mfma_f32_16x16x32_bf16 v[28:31], v[124:127], v[108:111], v[30:33]
	v_mfma_f32_16x16x32_bf16 v[42:45], v[132:135], v[108:111], v[42:45]
	ds_read_b128 v[62:65], v3 offset:2048
	v_mfma_f32_16x16x32_bf16 v[12:15], v[162:165], v[108:111], v[12:15]
	ds_read_b128 v[100:103], v4 offset:18432
	v_mfma_f32_16x16x32_bf16 v[92:95], v[158:161], v[108:111], v[92:95]
	v_mfma_f32_16x16x32_bf16 v[32:35], v[124:127], v[146:149], v[34:37]
	v_mfma_f32_16x16x32_bf16 v[46:49], v[132:135], v[146:149], v[46:49]
	ds_read_b128 v[108:111], v3 offset:4096
	v_mfma_f32_16x16x32_bf16 v[58:61], v[158:161], v[146:149], v[58:61]
	ds_read_b128 v[112:115], v4 offset:20480
	v_mfma_f32_16x16x32_bf16 v[16:19], v[162:165], v[146:149], v[16:19]
	v_mfma_f32_16x16x32_bf16 v[36:39], v[124:127], v[154:157], v[38:41]
	v_mfma_f32_16x16x32_bf16 v[50:53], v[132:135], v[154:157], v[50:53]
	ds_read_b128 v[146:149], v3 offset:6144
	v_mfma_f32_16x16x32_bf16 v[54:57], v[158:161], v[154:157], v[54:57]
	ds_read_b128 v[150:153], v4 offset:22528
	v_mfma_f32_16x16x32_bf16 v[20:23], v[162:165], v[154:157], v[20:23]
	s_waitcnt lgkmcnt(6)
	v_mfma_f32_16x16x32_bf16 v[24:27], v[170:173], v[166:169], v[24:27]
	s_waitcnt lgkmcnt(0)
	v_mfma_f32_16x16x32_bf16 v[8:11], v[150:153], v[166:169], v[8:11]
	v_mfma_f32_16x16x32_bf16 v[88:91], v[100:103], v[166:169], v[88:91]
	v_mfma_f32_16x16x32_bf16 v[96:99], v[112:115], v[166:169], v[96:99]
	v_mfma_f32_16x16x32_bf16 v[28:31], v[170:173], v[62:65], v[28:31]
	v_mfma_f32_16x16x32_bf16 v[40:43], v[100:103], v[62:65], v[42:45]
	v_mfma_f32_16x16x32_bf16 v[12:15], v[150:153], v[62:65], v[12:15]
	v_mfma_f32_16x16x32_bf16 v[92:95], v[112:115], v[62:65], v[92:95]
	v_mfma_f32_16x16x32_bf16 v[32:35], v[170:173], v[108:111], v[32:35]
	v_mfma_f32_16x16x32_bf16 v[44:47], v[100:103], v[108:111], v[46:49]
	v_mfma_f32_16x16x32_bf16 v[58:61], v[112:115], v[108:111], v[58:61]
	v_mfma_f32_16x16x32_bf16 v[16:19], v[150:153], v[108:111], v[16:19]
	v_mfma_f32_16x16x32_bf16 v[36:39], v[170:173], v[146:149], v[36:39]
	v_mfma_f32_16x16x32_bf16 v[48:51], v[100:103], v[146:149], v[50:53]
	v_mfma_f32_16x16x32_bf16 v[52:55], v[112:115], v[146:149], v[54:57]
	v_mfma_f32_16x16x32_bf16 v[20:23], v[150:153], v[146:149], v[20:23]
	s_setprio 0
	s_waitcnt vmcnt(0) lgkmcnt(0)
	s_barrier
	ds_read_b128 v[62:65], v6 offset:32768
	ds_read_b128 v[84:87], v6 offset:34816
	ds_read_b128 v[100:103], v7 offset:49152
	ds_read_b128 v[104:107], v7 offset:51200
	ds_read_b128 v[108:111], v6 offset:36864
	ds_read_b128 v[112:115], v6 offset:38912
	ds_read_b128 v[116:119], v7 offset:53248
	ds_read_b128 v[120:123], v7 offset:55296
	s_setprio 2
	ds_read_b128 v[124:127], v3 offset:32768
	ds_read_b128 v[132:135], v4 offset:49152
	s_waitcnt lgkmcnt(7)
	v_mfma_f32_16x16x32_bf16 v[24:27], v[100:103], v[62:65], v[24:27]
	s_waitcnt lgkmcnt(2)
	v_mfma_f32_16x16x32_bf16 v[6:9], v[120:123], v[62:65], v[8:11]
	v_mfma_f32_16x16x32_bf16 v[88:91], v[104:107], v[62:65], v[88:91]
	v_mfma_f32_16x16x32_bf16 v[96:99], v[116:119], v[62:65], v[96:99]
	v_mfma_f32_16x16x32_bf16 v[28:31], v[100:103], v[84:87], v[28:31]
	ds_read_b128 v[146:149], v3 offset:34816
	v_mfma_f32_16x16x32_bf16 v[40:43], v[104:107], v[84:87], v[40:43]
	ds_read_b128 v[150:153], v4 offset:51200
	v_mfma_f32_16x16x32_bf16 v[10:13], v[120:123], v[84:87], v[12:15]
	v_mfma_f32_16x16x32_bf16 v[92:95], v[116:119], v[84:87], v[92:95]
	v_mfma_f32_16x16x32_bf16 v[14:17], v[120:123], v[108:111], v[16:19]
	ds_read_b128 v[84:87], v3 offset:36864
	v_mfma_f32_16x16x32_bf16 v[158:161], v[100:103], v[108:111], v[32:35]
	ds_read_b128 v[154:157], v4 offset:53248
	v_mfma_f32_16x16x32_bf16 v[162:165], v[104:107], v[108:111], v[44:47]
	v_mfma_f32_16x16x32_bf16 v[166:169], v[116:119], v[108:111], v[58:61]
	v_mfma_f32_16x16x32_bf16 v[100:103], v[100:103], v[112:115], v[36:39]
	ds_read_b128 v[108:111], v3 offset:38912
	v_mfma_f32_16x16x32_bf16 v[104:107], v[104:107], v[112:115], v[48:51]
	ds_read_b128 v[2:5], v4 offset:55296
	v_mfma_f32_16x16x32_bf16 v[116:119], v[116:119], v[112:115], v[52:55]
	v_mfma_f32_16x16x32_bf16 v[112:115], v[120:123], v[112:115], v[20:23]
	s_waitcnt lgkmcnt(6)
	v_mfma_f32_16x16x32_bf16 v[62:65], v[132:135], v[124:127], v[24:27]
	s_waitcnt lgkmcnt(4)
	v_mfma_f32_16x16x32_bf16 v[58:61], v[150:153], v[124:127], v[88:91]
	s_waitcnt lgkmcnt(2)
	v_mfma_f32_16x16x32_bf16 v[54:57], v[154:157], v[124:127], v[96:99]
	s_waitcnt lgkmcnt(0)
	v_mfma_f32_16x16x32_bf16 v[50:53], v[2:5], v[124:127], v[6:9]
	v_mfma_f32_16x16x32_bf16 v[46:49], v[132:135], v[146:149], v[28:31]
	v_mfma_f32_16x16x32_bf16 v[42:45], v[150:153], v[146:149], v[40:43]
	v_mfma_f32_16x16x32_bf16 v[38:41], v[154:157], v[146:149], v[92:95]
	v_mfma_f32_16x16x32_bf16 v[34:37], v[2:5], v[146:149], v[10:13]
	v_mfma_f32_16x16x32_bf16 v[30:33], v[132:135], v[84:87], v[158:161]
	v_mfma_f32_16x16x32_bf16 v[26:29], v[150:153], v[84:87], v[162:165]
	v_mfma_f32_16x16x32_bf16 v[22:25], v[154:157], v[84:87], v[166:169]
	v_mfma_f32_16x16x32_bf16 v[18:21], v[2:5], v[84:87], v[14:17]
	v_mfma_f32_16x16x32_bf16 v[14:17], v[132:135], v[108:111], v[100:103]
	v_mfma_f32_16x16x32_bf16 v[10:13], v[150:153], v[108:111], v[104:107]
	v_mfma_f32_16x16x32_bf16 v[6:9], v[154:157], v[108:111], v[116:119]
	v_mfma_f32_16x16x32_bf16 v[2:5], v[2:5], v[108:111], v[112:115]
	s_setprio 0
	s_and_b32 s1, s0, -8
	s_cmp_lg_u32 s1, 16
	s_barrier
; __device__ __forceinline__ float x4_sum(float x) {
;     const unsigned xi = __float_as_uint(x);
;     const auto r = __builtin_amdgcn_permlane32_swap(xi, xi, false, false);
;     const float m = __uint_as_float(r[0]) + __uint_as_float(r[1]);
;     const unsigned mi = __float_as_uint(m);
;     const auto r2 = __builtin_amdgcn_permlane16_swap(mi, mi, false, false);
;     return __uint_as_float(r2[0]) + __uint_as_float(r2[1]);
; }
; template <int MODE>
; __device__ __forceinline__ void gemm_tile(const Params& P, int tm, int tn, unsigned char* smem) {
;     ...
;         if (n0 >= ZC_FQ && n0 < ZC_FV) {
;             const bool isk = n0 >= ZC_FK;
;             const float* gain = isk ? P.f_k_norm : P.f_q_norm;
;             const float scl = isk ? 1.0f : 0.125f * LOG2E;
;             float gn[4][4];
; #pragma unroll
;             for (int j = 0; j < 4; ++j)
; #pragma unroll
;                 for (int r = 0; r < 4; ++r) gn[j][r] = gain[16 * j + 4 * g + r];
; #pragma unroll
;             for (int i = 0; i < 4; ++i) {
;                 float ss = 0.f;
; #pragma unroll
;                 for (int j = 0; j < 4; ++j)
; #pragma unroll
;                     for (int r = 0; r < 4; ++r) ss += acc[i][j][r] * acc[i][j][r];
;                 ss = x4_sum(ss);
;                 const float rstd = rsqrtf(ss * (1.0f / 64.0f) + EPS) * scl;
; #pragma unroll
;                 for (int j = 0; j < 4; ++j)
; #pragma unroll
;                     for (int r = 0; r < 4; ++r) acc[i][j][r] *= rstd * gn[j][r];
;             }
	s_cbranch_scc1 .LBB0_181
	v_mul_f32_e32 v66, v63, v63
	v_fmac_f32_e32 v66, v62, v62
	v_fmac_f32_e32 v66, v64, v64
	v_fmac_f32_e32 v66, v65, v65
	v_fmac_f32_e32 v66, v58, v58
	v_fmac_f32_e32 v66, v59, v59
	v_fmac_f32_e32 v66, v60, v60
	v_fmac_f32_e32 v66, v61, v61
	v_fmac_f32_e32 v66, v54, v54
	v_fmac_f32_e32 v66, v55, v55
	v_fmac_f32_e32 v66, v56, v56
	v_fmac_f32_e32 v66, v57, v57
	v_pk_mul_f32 v[84:85], v[50:51], v[50:51]
	v_pk_mul_f32 v[68:69], v[52:53], v[52:53]
	v_add_f32_e32 v66, v84, v66
	v_add_f32_e32 v66, v85, v66
	v_add_f32_e32 v66, v68, v66
	v_add_f32_e32 v66, v69, v66
	v_mov_b32_e32 v68, v66
	s_nop 1
	v_permlane32_swap_b32_e32 v66, v68
	v_add_f32_e32 v69, v66, v68
	v_mul_f32_e32 v66, v47, v47
	v_fmac_f32_e32 v66, v46, v46
	v_fmac_f32_e32 v66, v48, v48
	v_fmac_f32_e32 v66, v49, v49
	v_fmac_f32_e32 v66, v42, v42
	v_fmac_f32_e32 v66, v43, v43
	v_fmac_f32_e32 v66, v44, v44
	v_fmac_f32_e32 v66, v45, v45
	v_fmac_f32_e32 v66, v38, v38
	v_fmac_f32_e32 v66, v39, v39
	v_fmac_f32_e32 v66, v40, v40
	v_fmac_f32_e32 v66, v41, v41
	v_pk_mul_f32 v[88:89], v[34:35], v[34:35]
	v_pk_mul_f32 v[86:87], v[36:37], v[36:37]
	v_add_f32_e32 v66, v88, v66
	v_add_f32_e32 v66, v89, v66
	v_add_f32_e32 v66, v86, v66
	v_add_f32_e32 v66, v87, v66
	v_mov_b32_e32 v68, v66
	s_nop 1
	v_permlane32_swap_b32_e32 v66, v68
	v_add_f32_e32 v68, v66, v68
	v_mov_b32_e32 v85, v69
	v_mov_b32_e32 v84, v68
	s_nop 0
	v_permlane16_swap_b32_e32 v69, v85
	v_permlane16_swap_b32_e32 v68, v84
	v_pk_add_f32 v[84:85], v[68:69], v[84:85]
	v_mov_b64_e32 v[68:69], s[8:9]
	v_mul_f32_e32 v97, v31, v31
	s_cmp_gt_u32 s0, 19
	v_pk_fma_f32 v[88:89], v[84:85], s[6:7], v[68:69] op_sel_hi:[1,0,0]
	v_fmac_f32_e32 v97, v30, v30
	s_cselect_b64 s[0:1], -1, 0
	v_mul_f32_e32 v66, 0x4b800000, v89
	v_cmp_gt_f32_e32 vcc, s21, v89
	v_fmac_f32_e32 v97, v32, v32
	v_cndmask_b32_e64 v108, v78, 1.0, s[0:1]
	s_and_b64 s[0:1], s[0:1], exec
	v_cndmask_b32_e32 v66, v89, v66, vcc
	v_fmac_f32_e32 v97, v33, v33
	v_rsq_f32_e32 v66, v66
	v_mul_f32_e32 v70, 0x4b800000, v88
	v_cmp_gt_f32_e64 s[0:1], s21, v88
	v_fmac_f32_e32 v97, v26, v26
	v_fmac_f32_e32 v97, v27, v27
	v_cndmask_b32_e64 v70, v88, v70, s[0:1]
	v_rsq_f32_e32 v88, v70
	v_fmac_f32_e32 v97, v28, v28
	s_cselect_b32 s13, s41, s39
	s_cselect_b32 s12, s40, s38
	v_lshlrev_b32_e32 v96, 4, v83
	v_fmac_f32_e32 v97, v29, v29
	global_load_dwordx4 v[84:87], v96, s[12:13]
	v_mul_f32_e32 v70, 0x45800000, v66
	v_fmac_f32_e32 v97, v22, v22
	v_cndmask_b32_e32 v66, v66, v70, vcc
	v_fmac_f32_e32 v97, v23, v23
	v_mul_f32_e32 v70, v108, v66
	v_mul_f32_e32 v66, 0x45800000, v88
	v_fmac_f32_e32 v97, v24, v24
	v_cndmask_b32_e64 v66, v88, v66, s[0:1]
	global_load_dwordx4 v[88:91], v96, s[12:13] offset:64
	v_fmac_f32_e32 v97, v25, v25
	v_pk_mul_f32 v[94:95], v[18:19], v[18:19]
	v_pk_mul_f32 v[92:93], v[20:21], v[20:21]
	v_add_f32_e32 v94, v94, v97
	v_add_f32_e32 v94, v95, v94
	v_add_f32_e32 v92, v92, v94
	v_add_f32_e32 v97, v93, v92
	global_load_dwordx4 v[92:95], v96, s[12:13] offset:128
	v_mov_b32_e32 v98, v97
	s_nop 1
	v_permlane32_swap_b32_e32 v97, v98
	v_add_f32_e32 v101, v97, v98
	global_load_dwordx4 v[96:99], v96, s[12:13] offset:192
	v_mul_f32_e32 v100, v15, v15
	v_fmac_f32_e32 v100, v14, v14
	v_fmac_f32_e32 v100, v16, v16
	v_fmac_f32_e32 v100, v17, v17
	v_fmac_f32_e32 v100, v10, v10
	v_fmac_f32_e32 v100, v11, v11
	v_fmac_f32_e32 v100, v12, v12
	v_fmac_f32_e32 v100, v13, v13
	v_fmac_f32_e32 v100, v6, v6
	v_fmac_f32_e32 v100, v7, v7
	v_fmac_f32_e32 v100, v8, v8
	v_fmac_f32_e32 v100, v9, v9
	v_pk_mul_f32 v[106:107], v[2:3], v[2:3]
	v_pk_mul_f32 v[104:105], v[4:5], v[4:5]
	v_add_f32_e32 v100, v106, v100
	v_add_f32_e32 v100, v107, v100
	v_add_f32_e32 v100, v104, v100
	v_add_f32_e32 v100, v105, v100
	v_mov_b32_e32 v102, v100
	s_nop 1
	v_permlane32_swap_b32_e32 v100, v102
	v_add_f32_e32 v100, v100, v102
	v_mov_b32_e32 v103, v101
	v_mov_b32_e32 v102, v100
	s_nop 0
	v_permlane16_swap_b32_e32 v101, v103
	v_permlane16_swap_b32_e32 v100, v102
	v_pk_add_f32 v[100:101], v[100:101], v[102:103]
	v_mul_f32_e32 v66, v108, v66
	v_pk_fma_f32 v[68:69], v[100:101], s[6:7], v[68:69] op_sel_hi:[1,0,0]
	s_waitcnt vmcnt(3)
; template <int MODE>
; __device__ __forceinline__ void gemm_tile(const Params& P, int tm, int tn, unsigned char* smem) {
;     ...
; #pragma unroll
;             for (int j = 0; j < 4; ++j)
; #pragma unroll
;                 for (int r = 0; r < 4; ++r) gn[j][r] = gain[16 * j + 4 * g + r];
; #pragma unroll
;             for (int i = 0; i < 4; ++i) {
;                 float ss = 0.f;
; #pragma unroll
;                 for (int j = 0; j < 4; ++j)
; #pragma unroll
;                     for (int r = 0; r < 4; ++r) ss += acc[i][j][r] * acc[i][j][r];
;                 ss = x4_sum(ss);
;                 const float rstd = rsqrtf(ss * (1.0f / 64.0f) + EPS) * scl;
; #pragma unroll
;                 for (int j = 0; j < 4; ++j)
; #pragma unroll
;                     for (int r = 0; r < 4; ++r) acc[i][j][r] *= rstd * gn[j][r];
;             }
	v_pk_mul_f32 v[102:103], v[84:85], v[70:71] op_sel_hi:[1,0]
	v_mul_f32_e32 v100, 0x4b800000, v69
	v_cmp_gt_f32_e32 vcc, s21, v69
	v_cmp_gt_f32_e64 s[0:1], s21, v68
	v_pk_mul_f32 v[62:63], v[62:63], v[102:103]
	v_cndmask_b32_e32 v69, v69, v100, vcc
	v_mul_f32_e32 v100, 0x4b800000, v68
	v_rsq_f32_e32 v69, v69
	v_cndmask_b32_e64 v68, v68, v100, s[0:1]
	v_rsq_f32_e32 v100, v68
	v_pk_mul_f32 v[102:103], v[84:85], v[66:67] op_sel_hi:[1,0]
	v_mul_f32_e32 v68, 0x45800000, v69
	v_cndmask_b32_e32 v68, v69, v68, vcc
	v_mul_f32_e32 v69, 0x45800000, v100
	v_cndmask_b32_e64 v69, v100, v69, s[0:1]
	v_mul_f32_e32 v68, v108, v68
	v_mul_f32_e32 v100, v108, v69
	v_pk_mul_f32 v[104:105], v[86:87], v[70:71] op_sel_hi:[1,0]
	v_pk_mul_f32 v[46:47], v[46:47], v[102:103]
	v_pk_mul_f32 v[102:103], v[84:85], v[68:69] op_sel_hi:[1,0]
	v_pk_mul_f32 v[84:85], v[84:85], v[100:101] op_sel_hi:[1,0]
	v_pk_mul_f32 v[64:65], v[64:65], v[104:105]
	v_pk_mul_f32 v[104:105], v[86:87], v[66:67] op_sel_hi:[1,0]
	v_pk_mul_f32 v[14:15], v[14:15], v[84:85]
	s_waitcnt vmcnt(2)
	v_pk_mul_f32 v[84:85], v[88:89], v[70:71] op_sel_hi:[1,0]
	v_pk_mul_f32 v[48:49], v[48:49], v[104:105]
	v_pk_mul_f32 v[104:105], v[86:87], v[68:69] op_sel_hi:[1,0]
	v_pk_mul_f32 v[86:87], v[86:87], v[100:101] op_sel_hi:[1,0]
	v_pk_mul_f32 v[58:59], v[58:59], v[84:85]
	v_pk_mul_f32 v[84:85], v[88:89], v[66:67] op_sel_hi:[1,0]
	v_pk_mul_f32 v[16:17], v[16:17], v[86:87]
	v_pk_mul_f32 v[86:87], v[90:91], v[70:71] op_sel_hi:[1,0]
	v_pk_mul_f32 v[42:43], v[42:43], v[84:85]
	v_pk_mul_f32 v[84:85], v[88:89], v[68:69] op_sel_hi:[1,0]
	v_pk_mul_f32 v[60:61], v[60:61], v[86:87]
	v_pk_mul_f32 v[86:87], v[90:91], v[66:67] op_sel_hi:[1,0]
	v_pk_mul_f32 v[26:27], v[26:27], v[84:85]
	v_pk_mul_f32 v[84:85], v[88:89], v[100:101] op_sel_hi:[1,0]
	v_pk_mul_f32 v[44:45], v[44:45], v[86:87]
	v_pk_mul_f32 v[86:87], v[90:91], v[68:69] op_sel_hi:[1,0]
	v_pk_mul_f32 v[10:11], v[10:11], v[84:85]
	s_waitcnt vmcnt(1)
	v_pk_mul_f32 v[84:85], v[92:93], v[70:71] op_sel_hi:[1,0]
	v_pk_mul_f32 v[28:29], v[28:29], v[86:87]
	v_pk_mul_f32 v[86:87], v[90:91], v[100:101] op_sel_hi:[1,0]
	v_pk_mul_f32 v[54:55], v[54:55], v[84:85]
	v_pk_mul_f32 v[84:85], v[92:93], v[66:67] op_sel_hi:[1,0]
	v_pk_mul_f32 v[12:13], v[12:13], v[86:87]
	v_pk_mul_f32 v[86:87], v[94:95], v[70:71] op_sel_hi:[1,0]
	v_pk_mul_f32 v[38:39], v[38:39], v[84:85]
	v_pk_mul_f32 v[84:85], v[92:93], v[68:69] op_sel_hi:[1,0]
	v_pk_mul_f32 v[56:57], v[56:57], v[86:87]
	v_pk_mul_f32 v[86:87], v[94:95], v[66:67] op_sel_hi:[1,0]
	v_pk_mul_f32 v[22:23], v[22:23], v[84:85]
	v_pk_mul_f32 v[84:85], v[92:93], v[100:101] op_sel_hi:[1,0]
	v_pk_mul_f32 v[40:41], v[40:41], v[86:87]
	v_pk_mul_f32 v[86:87], v[94:95], v[68:69] op_sel_hi:[1,0]
	v_pk_mul_f32 v[6:7], v[6:7], v[84:85]
	s_waitcnt vmcnt(0)
	v_pk_mul_f32 v[84:85], v[96:97], v[70:71] op_sel_hi:[1,0]
	v_pk_mul_f32 v[24:25], v[24:25], v[86:87]
	v_pk_mul_f32 v[86:87], v[94:95], v[100:101] op_sel_hi:[1,0]
	v_pk_mul_f32 v[50:51], v[50:51], v[84:85]
	v_pk_mul_f32 v[84:85], v[96:97], v[66:67] op_sel_hi:[1,0]
	v_pk_mul_f32 v[8:9], v[8:9], v[86:87]
	v_pk_mul_f32 v[86:87], v[98:99], v[70:71] op_sel_hi:[1,0]
	v_pk_mul_f32 v[34:35], v[34:35], v[84:85]
	v_pk_mul_f32 v[84:85], v[96:97], v[68:69] op_sel_hi:[1,0]
	v_pk_mul_f32 v[68:69], v[98:99], v[68:69] op_sel_hi:[1,0]
	v_pk_mul_f32 v[52:53], v[52:53], v[86:87]
	v_pk_mul_f32 v[86:87], v[98:99], v[66:67] op_sel_hi:[1,0]
	v_pk_mul_f32 v[20:21], v[20:21], v[68:69]
	v_pk_mul_f32 v[18:19], v[18:19], v[84:85]
	v_pk_mul_f32 v[68:69], v[96:97], v[100:101] op_sel_hi:[1,0]
	v_pk_mul_f32 v[84:85], v[98:99], v[100:101] op_sel_hi:[1,0]
	v_pk_mul_f32 v[32:33], v[32:33], v[104:105]
	v_pk_mul_f32 v[30:31], v[30:31], v[102:103]
	v_pk_mul_f32 v[36:37], v[36:37], v[86:87]
	v_pk_mul_f32 v[4:5], v[4:5], v[84:85]
	v_pk_mul_f32 v[2:3], v[2:3], v[68:69]
	s_branch .LBB0_181

; template <int MODE>
; __device__ __forceinline__ void gemm_tile(const Params& P, int tm, int tn, unsigned char* smem) {
;     ...
;     const int tid = opaque_tid(), lane = tid & 63, wave = tid >> 6, wr = wave >> 1, wc = wave & 1, g = lane >> 4, lr = lane & 15;
;     const int m0 = tm * 128, n0 = tn * 128;
;     const int srow = tid >> 3, sc = tid & 7;
;     constexpr unsigned LDA = (MODE == 2 ? NZ : 1024) * 2u;
;     unsigned aoff, boff; int soff0;
;     {
;         int ar = m0 + srow;
;         if (MODE == 2) { const int b = ar >> 11, t = ar & 2047; ar = b * L + NMETA + t; }
;         aoff = (unsigned)ar * LDA + (unsigned)sc * 16u;
;         boff = (unsigned)(n0 + srow) * 2048u + (unsigned)sc * 16u;
;         soff0 = srow * 128 + ((sc ^ (srow & 7)) << 4);
;     }
;     const unsigned char* Ab = (const unsigned char*)A; const unsigned char* Bb = (const unsigned char*)Bt;
;     float4 ssp0, ssp1, ssp2, ssp3;
;     if (MODE == 3) {
;         const float* ssq = (const float*)(P.ws + WS_SSQ) + (size_t)(m0 + wr * 64 + lr) * 16 + 4 * g;
;         ssp0 = *(const float4*)(ssq); ssp1 = *(const float4*)(ssq + 16 * 16); ssp2 = *(const float4*)(ssq + 32 * 16); ssp3 = *(const float4*)(ssq + 48 * 16);
;     }
;     f32x4 acc[4][4];
; #pragma unroll
;     for (int i = 0; i < 4; ++i)
; #pragma unroll
;         for (int j = 0; j < 4; ++j) acc[i][j] = (f32x4){0.f, 0.f, 0.f, 0.f};
;     uint4 ra0, ra1, ra2, ra3, rb0, rb1, rb2, rb3;
;     ...
;     unsigned char* sA0 = smem; unsigned char* sB0 = smem + 16384; unsigned char* sA1 = smem + 32768; unsigned char* sB1 = smem + 49152;
;     G_LOAD(0)
;     G_WRITE(sA0, sB0)
;     __syncthreads();
;     const int arow_off = (wr * 64 + lr) * 128, brow_off = (wc * 64 + lr) * 128, sw = lr & 7;
;     G_LOAD(1)
;     ...
; #pragma unroll
;         for (int i = 0; i < 4; ++i) { fa[i] = *(const bf16x8*)(sA + arow_off + i * 2048 + ch0); fb[i] = *(const bf16x8*)(sB + brow_off + i * 2048 + ch0); }
;         __builtin_amdgcn_sched_barrier(0);
;         __builtin_amdgcn_s_setprio(2);
;         if (wr_ok) *(uint4*)(nA + soff0) = ra0;
;         if (ld_ok) ra0 = *(const uint4*)(Ab + (aoff + 0u * LDA + koa));
;         ga[0] = *(const bf16x8*)(sA + arow_off + 0 * 2048 + ch1); gb[0] = *(const bf16x8*)(sB + brow_off + 0 * 2048 + ch1);
;         __builtin_amdgcn_sched_barrier(0);
; #pragma unroll
.LBB0_1263:
	s_lshr_b32 s0, s14, 4
	s_and_b32 s0, s0, 0x1fffff8
	s_and_b32 s1, s14, 7
	s_or_b32 s0, s0, s1
	v_mov_b32_e32 v88, v0
	s_bfe_u32 s2, s14, 0x40003
	s_lshl_b32 s23, s0, 7
	v_ashrrev_i32_e32 v6, 3, v88
	v_lshlrev_b32_e32 v3, 4, v88
	v_add_u32_e32 v2, s23, v6
	v_and_b32_e32 v3, 0x70, v3
	s_lshl_b32 s0, s2, 18
	v_lshl_add_u32 v4, v6, 11, s0
	v_lshl_or_b32 v24, v2, 11, v3
	v_or_b32_e32 v18, v4, v3
	v_add_u32_e32 v2, 0x10000, v24
	v_add_u32_e32 v3, 0x20000, v24
	v_lshlrev_b32_e32 v248, 1, v0
	v_lshrrev_b32_e32 v249, 6, v0
	v_and_b32_e32 v248, 0x70, v248
	v_readfirstlane_b32 s96, v249
	v_xor_b32_e32 v240, v24, v248
	v_xor_b32_e32 v244, v18, v248
	s_lshl_b32 s96, s96, 10
	v_add_u32_e32 v241, 0x10000, v240
	v_add_u32_e32 v242, 0x20000, v240
	v_add_u32_e32 v243, 0x30000, v240
	v_add_u32_e32 v245, 0x10000, v244
	v_add_u32_e32 v246, 0x20000, v244
	v_add_u32_e32 v247, 0x30000, v244
	s_mov_b64 s[92:93], s[36:37]
	s_mov_b64 s[94:95], s[6:7]
	s_mov_b32 m0, s96
	s_nop 0
	global_load_lds_dwordx4 v240, s[92:93]
	s_add_u32 m0, s96, 0x1000
	s_nop 0
	global_load_lds_dwordx4 v241, s[92:93]
	s_add_u32 m0, s96, 0x2000
	s_nop 0
	global_load_lds_dwordx4 v242, s[92:93]
	s_add_u32 m0, s96, 0x3000
	s_nop 0
	global_load_lds_dwordx4 v243, s[92:93]
	s_add_u32 m0, s96, 0x4000
	s_nop 0
	global_load_lds_dwordx4 v244, s[94:95]
	s_add_u32 m0, s96, 0x5000
	s_nop 0
	global_load_lds_dwordx4 v245, s[94:95]
	s_add_u32 m0, s96, 0x6000
	s_nop 0
	global_load_lds_dwordx4 v246, s[94:95]
	s_add_u32 m0, s96, 0x7000
	s_nop 0
	global_load_lds_dwordx4 v247, s[94:95]
	v_add_u32_e32 v2, 0x20000, v18
	v_add_u32_e32 v3, 0x30000, v18
	v_add_u32_e32 v2, 0x30000, v24
	v_add_u32_e32 v3, 0x10000, v18
	v_ashrrev_i32_e32 v2, 1, v88
	v_and_b32_e32 v25, 0xffffffc0, v2
	v_and_b32_e32 v90, 15, v88
	v_add_u32_e32 v2, s23, v25
	v_or_b32_e32 v84, v2, v90
	v_ashrrev_i32_e32 v85, 31, v84
	v_xor_b32_e32 v7, v6, v88
	v_bfe_u32 v89, v88, 4, 2
	v_lshlrev_b64 v[2:3], 6, v[84:85]
	v_lshlrev_b32_e32 v6, 7, v6
	v_lshlrev_b32_e32 v7, 4, v7
	v_lshlrev_b32_e32 v82, 4, v89
	v_lshl_add_u64 v[2:3], s[4:5], 0, v[2:3]
	v_and_or_b32 v6, v7, s15, v6
	v_lshl_add_u64 v[54:55], v[2:3], 0, v[82:83]
	v_add_u32_e32 v19, 0, v6
	v_or_b32_e32 v62, 0x80, v24
	global_load_dwordx4 v[10:13], v[54:55], off
	global_load_dwordx4 v[2:5], v[54:55], off offset:3072
	v_or_b32_e32 v58, 0x80, v18
	v_add_u32_e32 v59, 0x10080, v18
	v_add_u32_e32 v60, 0x20080, v18
	v_add_u32_e32 v61, 0x30080, v18
	v_add_u32_e32 v63, 0x10080, v24
	v_add_u32_e32 v64, 0x20080, v24
	v_add_u32_e32 v65, 0x30080, v24
	global_load_dwordx4 v[14:17], v[54:55], off offset:1024
	global_load_dwordx4 v[6:9], v[54:55], off offset:2048
	v_or_b32_e32 v82, v25, v90
	v_and_b32_e32 v25, 7, v88
	v_bfe_u32 v91, v88, 6, 1
	v_lshl_add_u32 v104, v82, 7, 0
	s_waitcnt vmcnt(4) lgkmcnt(0)
	s_barrier
	v_lshrrev_b32_e32 v20, 4, v88
	v_lshlrev_b32_e32 v21, 7, v90
	v_bitop3_b32 v20, v20, v25, 3 bitop3:0x6c
	v_lshl_or_b32 v21, v91, 13, v21
	v_lshlrev_b32_e32 v20, 4, v20
	v_add_u32_e32 v22, v104, v20
	v_add_u32_e32 v21, 0, v21
	v_add_u32_e32 v23, v21, v20
	ds_read_b128 v[58:61], v22
	ds_read_b128 v[62:65], v22 offset:2048
	ds_read_b128 v[66:69], v23 offset:16384
	ds_read_b128 v[70:73], v23 offset:18432
	ds_read_b128 v[74:77], v22 offset:4096
	ds_read_b128 v[78:81], v22 offset:6144
	ds_read_b128 v[92:95], v23 offset:20480
	ds_read_b128 v[96:99], v23 offset:22528
	v_bitop3_b32 v20, v89, v25, 4 bitop3:0x36
	v_lshlrev_b32_e32 v25, 4, v20
	s_setprio 2
	s_add_u32 s92, s92, 0x80
	s_addc_u32 s93, s93, 0
	s_add_u32 s94, s94, 0x80
	s_addc_u32 s95, s95, 0
	s_add_u32 m0, s96, 0x8000
	v_add_u32_e32 v20, v104, v25
	global_load_lds_dwordx4 v240, s[92:93]
	s_add_u32 m0, s96, 0x9000
	v_add_u32_e32 v21, v21, v25
	global_load_lds_dwordx4 v241, s[92:93]
	s_add_u32 m0, s96, 0xa000
	ds_read_b128 v[26:29], v20
	global_load_lds_dwordx4 v242, s[92:93]
	s_add_u32 m0, s96, 0xb000
	ds_read_b128 v[104:107], v21 offset:16384
	global_load_lds_dwordx4 v243, s[92:93]
	s_add_u32 m0, s96, 0xc000
	s_waitcnt lgkmcnt(7)
	global_load_lds_dwordx4 v244, s[94:95]
	s_add_u32 m0, s96, 0xd000
	v_mfma_f32_16x16x32_bf16 v[108:111], v[66:69], v[58:61], 0
	global_load_lds_dwordx4 v245, s[94:95]
	s_add_u32 m0, s96, 0xe000
	s_waitcnt lgkmcnt(6)
	global_load_lds_dwordx4 v246, s[94:95]
	s_add_u32 m0, s96, 0xf000
	v_mfma_f32_16x16x32_bf16 v[112:115], v[70:73], v[58:61], 0
	global_load_lds_dwordx4 v247, s[94:95]
	s_waitcnt lgkmcnt(3)
	v_mfma_f32_16x16x32_bf16 v[116:119], v[92:95], v[58:61], 0
	s_waitcnt lgkmcnt(2)
	v_mfma_f32_16x16x32_bf16 v[58:61], v[96:99], v[58:61], 0
	ds_read_b128 v[30:33], v20 offset:2048
	ds_read_b128 v[124:127], v21 offset:18432
	v_mfma_f32_16x16x32_bf16 v[132:135], v[66:69], v[62:65], 0
	v_mfma_f32_16x16x32_bf16 v[136:139], v[70:73], v[62:65], 0
	v_mfma_f32_16x16x32_bf16 v[140:143], v[92:95], v[62:65], 0
	v_mfma_f32_16x16x32_bf16 v[62:65], v[96:99], v[62:65], 0
	ds_read_b128 v[34:37], v20 offset:4096
	ds_read_b128 v[148:151], v21 offset:20480
	v_mfma_f32_16x16x32_bf16 v[152:155], v[66:69], v[74:77], 0
	v_mfma_f32_16x16x32_bf16 v[156:159], v[70:73], v[74:77], 0
	v_mfma_f32_16x16x32_bf16 v[160:163], v[92:95], v[74:77], 0
	v_mfma_f32_16x16x32_bf16 v[74:77], v[96:99], v[74:77], 0
	ds_read_b128 v[38:41], v20 offset:6144
	ds_read_b128 v[168:171], v21 offset:22528
	v_mfma_f32_16x16x32_bf16 v[66:69], v[66:69], v[78:81], 0
	v_mfma_f32_16x16x32_bf16 v[70:73], v[70:73], v[78:81], 0
	v_mfma_f32_16x16x32_bf16 v[92:95], v[92:95], v[78:81], 0
	v_mfma_f32_16x16x32_bf16 v[78:81], v[96:99], v[78:81], 0
	s_waitcnt lgkmcnt(6)
	v_mfma_f32_16x16x32_bf16 v[42:45], v[104:107], v[26:29], v[108:111]
	s_waitcnt lgkmcnt(4)
	v_mfma_f32_16x16x32_bf16 v[108:111], v[124:127], v[26:29], v[112:115]
	s_waitcnt lgkmcnt(2)
	v_mfma_f32_16x16x32_bf16 v[112:115], v[148:151], v[26:29], v[116:119]
	s_waitcnt lgkmcnt(0)
	v_mfma_f32_16x16x32_bf16 v[26:29], v[168:171], v[26:29], v[58:61]
	v_mfma_f32_16x16x32_bf16 v[46:49], v[104:107], v[30:33], v[132:135]
	v_mfma_f32_16x16x32_bf16 v[116:119], v[124:127], v[30:33], v[136:139]
	v_mfma_f32_16x16x32_bf16 v[132:135], v[148:151], v[30:33], v[140:143]
	v_mfma_f32_16x16x32_bf16 v[30:33], v[168:171], v[30:33], v[62:65]
	v_mfma_f32_16x16x32_bf16 v[50:53], v[104:107], v[34:37], v[152:155]
	v_mfma_f32_16x16x32_bf16 v[136:139], v[124:127], v[34:37], v[156:159]
	v_mfma_f32_16x16x32_bf16 v[140:143], v[148:151], v[34:37], v[160:163]
	v_mfma_f32_16x16x32_bf16 v[34:37], v[168:171], v[34:37], v[74:77]
	v_mfma_f32_16x16x32_bf16 v[54:57], v[104:107], v[38:41], v[66:69]
	v_mfma_f32_16x16x32_bf16 v[66:69], v[124:127], v[38:41], v[70:73]
	v_mfma_f32_16x16x32_bf16 v[70:73], v[148:151], v[38:41], v[92:95]
	v_mfma_f32_16x16x32_bf16 v[38:41], v[168:171], v[38:41], v[78:81]
	s_setprio 0
	s_waitcnt vmcnt(0) lgkmcnt(0)
	s_barrier
; template <int MODE>
; __device__ __forceinline__ void gemm_tile(const Params& P, int tm, int tn, unsigned char* smem) {
;     ...
; #pragma unroll
;         for (int i = 0; i < 4; ++i) { fa[i] = *(const bf16x8*)(sA + arow_off + i * 2048 + ch0); fb[i] = *(const bf16x8*)(sB + brow_off + i * 2048 + ch0); }
;         __builtin_amdgcn_sched_barrier(0);
;         __builtin_amdgcn_s_setprio(2);
;         if (wr_ok) *(uint4*)(nA + soff0) = ra0;
;         if (ld_ok) ra0 = *(const uint4*)(Ab + (aoff + 0u * LDA + koa));
;         ga[0] = *(const bf16x8*)(sA + arow_off + 0 * 2048 + ch1); gb[0] = *(const bf16x8*)(sB + brow_off + 0 * 2048 + ch1);
;         __builtin_amdgcn_sched_barrier(0);
; #pragma unroll
;         for (int j = 0; j < 4; ++j) acc[0][j] = __builtin_amdgcn_mfma_f32_16x16x32_bf16(fb[j], fa[0], acc[0][j], 0, 0, 0);
;         __builtin_amdgcn_sched_barrier(0);
;         if (wr_ok) *(uint4*)(nA + soff0 + 4096) = ra1;
;         if (ld_ok) ra1 = *(const uint4*)(Ab + (aoff + 32u * LDA + koa));
;         ga[1] = *(const bf16x8*)(sA + arow_off + 1 * 2048 + ch1); gb[1] = *(const bf16x8*)(sB + brow_off + 1 * 2048 + ch1);
;         __builtin_amdgcn_sched_barrier(0);
; #pragma unroll
;         for (int j = 0; j < 4; ++j) acc[1][j] = __builtin_amdgcn_mfma_f32_16x16x32_bf16(fb[j], fa[1], acc[1][j], 0, 0, 0);
;         __builtin_amdgcn_sched_barrier(0);
;         if (wr_ok) *(uint4*)(nA + soff0 + 8192) = ra2;
;         if (ld_ok) ra2 = *(const uint4*)(Ab + (aoff + 64u * LDA + koa));
;         ga[2] = *(const bf16x8*)(sA + arow_off + 2 * 2048 + ch1); gb[2] = *(const bf16x8*)(sB + brow_off + 2 * 2048 + ch1);
;         __builtin_amdgcn_sched_barrier(0);
; #pragma unroll
;         for (int j = 0; j < 4; ++j) acc[2][j] = __builtin_amdgcn_mfma_f32_16x16x32_bf16(fb[j], fa[2], acc[2][j], 0, 0, 0);
;         __builtin_amdgcn_sched_barrier(0);
;         if (wr_ok) *(uint4*)(nA + soff0 + 12288) = ra3;
;         if (ld_ok) ra3 = *(const uint4*)(Ab + (aoff + 96u * LDA + koa));
;         ga[3] = *(const bf16x8*)(sA + arow_off + 3 * 2048 + ch1); gb[3] = *(const bf16x8*)(sB + brow_off + 3 * 2048 + ch1);
;         __builtin_amdgcn_sched_barrier(0);
; #pragma unroll
;         for (int j = 0; j < 4; ++j) acc[3][j] = __builtin_amdgcn_mfma_f32_16x16x32_bf16(fb[j], fa[3], acc[3][j], 0, 0, 0);
;         __builtin_amdgcn_sched_barrier(0);
;         if (wr_ok) *(uint4*)(nB + soff0) = rb0;
	ds_read_b128 v[78:81], v22 offset:32768
	ds_read_b128 v[92:95], v22 offset:34816
	ds_read_b128 v[104:107], v23 offset:49152
	ds_read_b128 v[124:127], v23 offset:51200
	ds_read_b128 v[148:151], v22 offset:36864
	ds_read_b128 v[152:155], v22 offset:38912
	ds_read_b128 v[156:159], v23 offset:53248
	ds_read_b128 v[160:163], v23 offset:55296
	s_setprio 2
	s_add_u32 s92, s92, 0x80
	s_addc_u32 s93, s93, 0
	s_add_u32 s94, s94, 0x80
	s_addc_u32 s95, s95, 0
	s_mov_b32 m0, s96
	ds_read_b128 v[100:103], v20 offset:32768
	global_load_lds_dwordx4 v240, s[92:93]
	s_add_u32 m0, s96, 0x1000
	ds_read_b128 v[172:175], v21 offset:49152
	global_load_lds_dwordx4 v241, s[92:93]
	s_add_u32 m0, s96, 0x2000
	s_waitcnt lgkmcnt(7)
	global_load_lds_dwordx4 v242, s[92:93]
	s_add_u32 m0, s96, 0x3000
	v_mfma_f32_16x16x32_bf16 v[42:45], v[104:107], v[78:81], v[42:45]
	global_load_lds_dwordx4 v243, s[92:93]
	s_add_u32 m0, s96, 0x4000
	s_waitcnt lgkmcnt(2)
	global_load_lds_dwordx4 v244, s[94:95]
	s_add_u32 m0, s96, 0x5000
	v_mfma_f32_16x16x32_bf16 v[26:29], v[160:163], v[78:81], v[26:29]
	global_load_lds_dwordx4 v245, s[94:95]
	s_add_u32 m0, s96, 0x6000
	v_mfma_f32_16x16x32_bf16 v[108:111], v[124:127], v[78:81], v[108:111]
	global_load_lds_dwordx4 v246, s[94:95]
	s_add_u32 m0, s96, 0x7000
	v_mfma_f32_16x16x32_bf16 v[112:115], v[156:159], v[78:81], v[112:115]
	global_load_lds_dwordx4 v247, s[94:95]
	v_mfma_f32_16x16x32_bf16 v[46:49], v[104:107], v[92:95], v[46:49]
	v_mfma_f32_16x16x32_bf16 v[30:33], v[160:163], v[92:95], v[30:33]
	ds_read_b128 v[120:123], v20 offset:34816
	v_mfma_f32_16x16x32_bf16 v[116:119], v[124:127], v[92:95], v[116:119]
	ds_read_b128 v[176:179], v21 offset:51200
	v_mfma_f32_16x16x32_bf16 v[132:135], v[156:159], v[92:95], v[132:135]
	v_mfma_f32_16x16x32_bf16 v[50:53], v[104:107], v[148:151], v[50:53]
	v_mfma_f32_16x16x32_bf16 v[34:37], v[160:163], v[148:151], v[34:37]
	ds_read_b128 v[144:147], v20 offset:36864
	v_mfma_f32_16x16x32_bf16 v[136:139], v[124:127], v[148:151], v[136:139]
	ds_read_b128 v[180:183], v21 offset:53248
	v_mfma_f32_16x16x32_bf16 v[140:143], v[156:159], v[148:151], v[140:143]
	v_mfma_f32_16x16x32_bf16 v[54:57], v[104:107], v[152:155], v[54:57]
	v_mfma_f32_16x16x32_bf16 v[66:69], v[124:127], v[152:155], v[66:69]
	ds_read_b128 v[164:167], v20 offset:38912
	v_mfma_f32_16x16x32_bf16 v[70:73], v[156:159], v[152:155], v[70:73]
	ds_read_b128 v[184:187], v21 offset:55296
	v_mfma_f32_16x16x32_bf16 v[38:41], v[160:163], v[152:155], v[38:41]
	s_waitcnt lgkmcnt(6)
	v_mfma_f32_16x16x32_bf16 v[42:45], v[172:175], v[100:103], v[42:45]
	s_waitcnt lgkmcnt(0)
	v_mfma_f32_16x16x32_bf16 v[26:29], v[184:187], v[100:103], v[26:29]
	v_mfma_f32_16x16x32_bf16 v[96:99], v[176:179], v[100:103], v[108:111]
	v_mfma_f32_16x16x32_bf16 v[108:111], v[180:183], v[100:103], v[112:115]
	v_mfma_f32_16x16x32_bf16 v[46:49], v[172:175], v[120:123], v[46:49]
	v_mfma_f32_16x16x32_bf16 v[58:61], v[176:179], v[120:123], v[116:119]
	v_mfma_f32_16x16x32_bf16 v[30:33], v[184:187], v[120:123], v[30:33]
	v_mfma_f32_16x16x32_bf16 v[112:115], v[180:183], v[120:123], v[132:135]
	v_mfma_f32_16x16x32_bf16 v[50:53], v[172:175], v[144:147], v[50:53]
	v_mfma_f32_16x16x32_bf16 v[62:65], v[176:179], v[144:147], v[136:139]
	v_mfma_f32_16x16x32_bf16 v[34:37], v[184:187], v[144:147], v[34:37]
	v_mfma_f32_16x16x32_bf16 v[120:123], v[180:183], v[144:147], v[140:143]
	v_mfma_f32_16x16x32_bf16 v[54:57], v[172:175], v[164:167], v[54:57]
	v_mfma_f32_16x16x32_bf16 v[66:69], v[176:179], v[164:167], v[66:69]
	v_mfma_f32_16x16x32_bf16 v[70:73], v[180:183], v[164:167], v[70:73]
	v_mfma_f32_16x16x32_bf16 v[38:41], v[184:187], v[164:167], v[38:41]
	s_setprio 0
	s_waitcnt vmcnt(0) lgkmcnt(0)
	s_barrier
	ds_read_b128 v[74:77], v22
	ds_read_b128 v[132:135], v22 offset:2048
	ds_read_b128 v[136:139], v23 offset:16384
	ds_read_b128 v[140:143], v23 offset:18432
	ds_read_b128 v[144:147], v22 offset:4096
	ds_read_b128 v[152:155], v22 offset:6144
	ds_read_b128 v[156:159], v23 offset:20480
	ds_read_b128 v[160:163], v23 offset:22528
	s_setprio 2
	s_add_u32 s92, s92, 0x80
	s_addc_u32 s93, s93, 0
	s_add_u32 s94, s94, 0x80
	s_addc_u32 s95, s95, 0
	s_add_u32 m0, s96, 0x8000
	ds_read_b128 v[168:171], v20
	global_load_lds_dwordx4 v240, s[92:93]
	s_add_u32 m0, s96, 0x9000
	ds_read_b128 v[172:175], v21 offset:16384
	global_load_lds_dwordx4 v241, s[92:93]
	s_add_u32 m0, s96, 0xa000
	s_waitcnt lgkmcnt(7)
	global_load_lds_dwordx4 v242, s[92:93]
	s_add_u32 m0, s96, 0xb000
	v_mfma_f32_16x16x32_bf16 v[42:45], v[136:139], v[74:77], v[42:45]
	global_load_lds_dwordx4 v243, s[92:93]
	s_add_u32 m0, s96, 0xc000
	s_waitcnt lgkmcnt(2)
	global_load_lds_dwordx4 v244, s[94:95]
	s_add_u32 m0, s96, 0xd000
	v_mfma_f32_16x16x32_bf16 v[26:29], v[160:163], v[74:77], v[26:29]
	global_load_lds_dwordx4 v245, s[94:95]
	s_add_u32 m0, s96, 0xe000
	v_mfma_f32_16x16x32_bf16 v[96:99], v[140:143], v[74:77], v[96:99]
	global_load_lds_dwordx4 v246, s[94:95]
	s_add_u32 m0, s96, 0xf000
	v_mfma_f32_16x16x32_bf16 v[108:111], v[156:159], v[74:77], v[108:111]
	global_load_lds_dwordx4 v247, s[94:95]
	v_mfma_f32_16x16x32_bf16 v[46:49], v[136:139], v[132:135], v[46:49]
	v_mfma_f32_16x16x32_bf16 v[58:61], v[140:143], v[132:135], v[58:61]
	ds_read_b128 v[78:81], v20 offset:2048
	v_mfma_f32_16x16x32_bf16 v[30:33], v[160:163], v[132:135], v[30:33]
	ds_read_b128 v[176:179], v21 offset:18432
	v_mfma_f32_16x16x32_bf16 v[112:115], v[156:159], v[132:135], v[112:115]
	v_mfma_f32_16x16x32_bf16 v[50:53], v[136:139], v[144:147], v[50:53]
	v_mfma_f32_16x16x32_bf16 v[62:65], v[140:143], v[144:147], v[62:65]
	ds_read_b128 v[92:95], v20 offset:4096
	v_mfma_f32_16x16x32_bf16 v[34:37], v[160:163], v[144:147], v[34:37]
	ds_read_b128 v[180:183], v21 offset:20480
	v_mfma_f32_16x16x32_bf16 v[120:123], v[156:159], v[144:147], v[120:123]
	v_mfma_f32_16x16x32_bf16 v[54:57], v[136:139], v[152:155], v[54:57]
	v_mfma_f32_16x16x32_bf16 v[66:69], v[140:143], v[152:155], v[66:69]
	ds_read_b128 v[148:151], v20 offset:6144
	v_mfma_f32_16x16x32_bf16 v[70:73], v[156:159], v[152:155], v[70:73]
	ds_read_b128 v[184:187], v21 offset:22528
	v_mfma_f32_16x16x32_bf16 v[38:41], v[160:163], v[152:155], v[38:41]
	s_waitcnt lgkmcnt(6)
; template <int MODE>
; __device__ __forceinline__ void gemm_tile(const Params& P, int tm, int tn, unsigned char* smem) {
;     ...
; #pragma unroll
;         for (int i = 0; i < 4; ++i) { fa[i] = *(const bf16x8*)(sA + arow_off + i * 2048 + ch0); fb[i] = *(const bf16x8*)(sB + brow_off + i * 2048 + ch0); }
;         __builtin_amdgcn_sched_barrier(0);
;         __builtin_amdgcn_s_setprio(2);
;         if (wr_ok) *(uint4*)(nA + soff0) = ra0;
;         if (ld_ok) ra0 = *(const uint4*)(Ab + (aoff + 0u * LDA + koa));
;         ga[0] = *(const bf16x8*)(sA + arow_off + 0 * 2048 + ch1); gb[0] = *(const bf16x8*)(sB + brow_off + 0 * 2048 + ch1);
;         __builtin_amdgcn_sched_barrier(0);
; #pragma unroll
;         for (int j = 0; j < 4; ++j) acc[0][j] = __builtin_amdgcn_mfma_f32_16x16x32_bf16(fb[j], fa[0], acc[0][j], 0, 0, 0);
;         __builtin_amdgcn_sched_barrier(0);
;         if (wr_ok) *(uint4*)(nA + soff0 + 4096) = ra1;
;         if (ld_ok) ra1 = *(const uint4*)(Ab + (aoff + 32u * LDA + koa));
;         ga[1] = *(const bf16x8*)(sA + arow_off + 1 * 2048 + ch1); gb[1] = *(const bf16x8*)(sB + brow_off + 1 * 2048 + ch1);
;         __builtin_amdgcn_sched_barrier(0);
; #pragma unroll
;         for (int j = 0; j < 4; ++j) acc[1][j] = __builtin_amdgcn_mfma_f32_16x16x32_bf16(fb[j], fa[1], acc[1][j], 0, 0, 0);
;         __builtin_amdgcn_sched_barrier(0);
;         if (wr_ok) *(uint4*)(nA + soff0 + 8192) = ra2;
;         if (ld_ok) ra2 = *(const uint4*)(Ab + (aoff + 64u * LDA + koa));
;         ga[2] = *(const bf16x8*)(sA + arow_off + 2 * 2048 + ch1); gb[2] = *(const bf16x8*)(sB + brow_off + 2 * 2048 + ch1);
;         __builtin_amdgcn_sched_barrier(0);
; #pragma unroll
;         for (int j = 0; j < 4; ++j) acc[2][j] = __builtin_amdgcn_mfma_f32_16x16x32_bf16(fb[j], fa[2], acc[2][j], 0, 0, 0);
;         __builtin_amdgcn_sched_barrier(0);
;         if (wr_ok) *(uint4*)(nA + soff0 + 12288) = ra3;
;         if (ld_ok) ra3 = *(const uint4*)(Ab + (aoff + 96u * LDA + koa));
;         ga[3] = *(const bf16x8*)(sA + arow_off + 3 * 2048 + ch1); gb[3] = *(const bf16x8*)(sB + brow_off + 3 * 2048 + ch1);
;         __builtin_amdgcn_sched_barrier(0);
; #pragma unroll
;         for (int j = 0; j < 4; ++j) acc[3][j] = __builtin_amdgcn_mfma_f32_16x16x32_bf16(fb[j], fa[3], acc[3][j], 0, 0, 0);
;         __builtin_amdgcn_sched_barrier(0);
;         if (wr_ok) *(uint4*)(nB + soff0) = rb0;
	v_mfma_f32_16x16x32_bf16 v[42:45], v[172:175], v[168:171], v[42:45]
	s_waitcnt lgkmcnt(0)
	v_mfma_f32_16x16x32_bf16 v[26:29], v[184:187], v[168:171], v[26:29]
	v_mfma_f32_16x16x32_bf16 v[96:99], v[176:179], v[168:171], v[96:99]
	v_mfma_f32_16x16x32_bf16 v[104:107], v[180:183], v[168:171], v[108:111]
	v_mfma_f32_16x16x32_bf16 v[46:49], v[172:175], v[78:81], v[46:49]
	v_mfma_f32_16x16x32_bf16 v[58:61], v[176:179], v[78:81], v[58:61]
	v_mfma_f32_16x16x32_bf16 v[30:33], v[184:187], v[78:81], v[30:33]
	v_mfma_f32_16x16x32_bf16 v[100:103], v[180:183], v[78:81], v[112:115]
	v_mfma_f32_16x16x32_bf16 v[50:53], v[172:175], v[92:95], v[50:53]
	v_mfma_f32_16x16x32_bf16 v[62:65], v[176:179], v[92:95], v[62:65]
	v_mfma_f32_16x16x32_bf16 v[34:37], v[184:187], v[92:95], v[34:37]
	v_mfma_f32_16x16x32_bf16 v[112:115], v[180:183], v[92:95], v[120:123]
	v_mfma_f32_16x16x32_bf16 v[54:57], v[172:175], v[148:151], v[54:57]
	v_mfma_f32_16x16x32_bf16 v[66:69], v[176:179], v[148:151], v[66:69]
	v_mfma_f32_16x16x32_bf16 v[70:73], v[180:183], v[148:151], v[70:73]
	v_mfma_f32_16x16x32_bf16 v[38:41], v[184:187], v[148:151], v[38:41]
	s_setprio 0
	s_waitcnt vmcnt(0) lgkmcnt(0)
	s_barrier
	ds_read_b128 v[116:119], v22 offset:32768
	ds_read_b128 v[120:123], v22 offset:34816
	ds_read_b128 v[124:127], v23 offset:49152
	ds_read_b128 v[140:143], v23 offset:51200
	ds_read_b128 v[148:151], v22 offset:36864
	ds_read_b128 v[152:155], v22 offset:38912
	ds_read_b128 v[156:159], v23 offset:53248
	ds_read_b128 v[160:163], v23 offset:55296
	s_setprio 2
	s_add_u32 s92, s92, 0x80
	s_addc_u32 s93, s93, 0
	s_add_u32 s94, s94, 0x80
	s_addc_u32 s95, s95, 0
	s_mov_b32 m0, s96
	ds_read_b128 v[164:167], v20 offset:32768
	global_load_lds_dwordx4 v240, s[92:93]
	s_add_u32 m0, s96, 0x1000
	ds_read_b128 v[172:175], v21 offset:49152
	global_load_lds_dwordx4 v241, s[92:93]
	s_add_u32 m0, s96, 0x2000
	s_waitcnt lgkmcnt(7)
	global_load_lds_dwordx4 v242, s[92:93]
	s_add_u32 m0, s96, 0x3000
	v_mfma_f32_16x16x32_bf16 v[42:45], v[124:127], v[116:119], v[42:45]
	global_load_lds_dwordx4 v243, s[92:93]
	s_add_u32 m0, s96, 0x4000
	s_waitcnt lgkmcnt(2)
	global_load_lds_dwordx4 v244, s[94:95]
	s_add_u32 m0, s96, 0x5000
	v_mfma_f32_16x16x32_bf16 v[26:29], v[160:163], v[116:119], v[26:29]
	global_load_lds_dwordx4 v245, s[94:95]
	s_add_u32 m0, s96, 0x6000
	v_mfma_f32_16x16x32_bf16 v[96:99], v[140:143], v[116:119], v[96:99]
	global_load_lds_dwordx4 v246, s[94:95]
	s_add_u32 m0, s96, 0x7000
	v_mfma_f32_16x16x32_bf16 v[104:107], v[156:159], v[116:119], v[104:107]
	global_load_lds_dwordx4 v247, s[94:95]
	v_mfma_f32_16x16x32_bf16 v[46:49], v[124:127], v[120:123], v[46:49]
	v_mfma_f32_16x16x32_bf16 v[58:61], v[140:143], v[120:123], v[58:61]
	ds_read_b128 v[74:77], v20 offset:34816
	v_mfma_f32_16x16x32_bf16 v[30:33], v[160:163], v[120:123], v[30:33]
	ds_read_b128 v[176:179], v21 offset:51200
	v_mfma_f32_16x16x32_bf16 v[100:103], v[156:159], v[120:123], v[100:103]
	v_mfma_f32_16x16x32_bf16 v[50:53], v[124:127], v[148:151], v[50:53]
	v_mfma_f32_16x16x32_bf16 v[62:65], v[140:143], v[148:151], v[62:65]
	ds_read_b128 v[132:135], v20 offset:36864
	v_mfma_f32_16x16x32_bf16 v[34:37], v[160:163], v[148:151], v[34:37]
	ds_read_b128 v[180:183], v21 offset:53248
	v_mfma_f32_16x16x32_bf16 v[112:115], v[156:159], v[148:151], v[112:115]
	v_mfma_f32_16x16x32_bf16 v[54:57], v[124:127], v[152:155], v[54:57]
	v_mfma_f32_16x16x32_bf16 v[66:69], v[140:143], v[152:155], v[66:69]
	ds_read_b128 v[144:147], v20 offset:38912
	v_mfma_f32_16x16x32_bf16 v[70:73], v[156:159], v[152:155], v[70:73]
	ds_read_b128 v[184:187], v21 offset:55296
	v_mfma_f32_16x16x32_bf16 v[38:41], v[160:163], v[152:155], v[38:41]
	s_waitcnt lgkmcnt(6)
	v_mfma_f32_16x16x32_bf16 v[42:45], v[172:175], v[164:167], v[42:45]
	s_waitcnt lgkmcnt(0)
	v_mfma_f32_16x16x32_bf16 v[26:29], v[184:187], v[164:167], v[26:29]
	v_mfma_f32_16x16x32_bf16 v[96:99], v[176:179], v[164:167], v[96:99]
	v_mfma_f32_16x16x32_bf16 v[104:107], v[180:183], v[164:167], v[104:107]
	v_mfma_f32_16x16x32_bf16 v[46:49], v[172:175], v[74:77], v[46:49]
	v_mfma_f32_16x16x32_bf16 v[58:61], v[176:179], v[74:77], v[58:61]
	v_mfma_f32_16x16x32_bf16 v[30:33], v[184:187], v[74:77], v[30:33]
	v_mfma_f32_16x16x32_bf16 v[100:103], v[180:183], v[74:77], v[100:103]
	v_mfma_f32_16x16x32_bf16 v[50:53], v[172:175], v[132:135], v[50:53]
	v_mfma_f32_16x16x32_bf16 v[62:65], v[176:179], v[132:135], v[62:65]
	v_mfma_f32_16x16x32_bf16 v[78:81], v[180:183], v[132:135], v[112:115]
	v_mfma_f32_16x16x32_bf16 v[34:37], v[184:187], v[132:135], v[34:37]
	v_mfma_f32_16x16x32_bf16 v[54:57], v[172:175], v[144:147], v[54:57]
	v_mfma_f32_16x16x32_bf16 v[66:69], v[176:179], v[144:147], v[66:69]
	v_mfma_f32_16x16x32_bf16 v[70:73], v[180:183], v[144:147], v[70:73]
	v_mfma_f32_16x16x32_bf16 v[38:41], v[184:187], v[144:147], v[38:41]
	s_setprio 0
	s_waitcnt vmcnt(0) lgkmcnt(0)
	s_barrier
; template <int MODE>
; __device__ __forceinline__ void gemm_tile(const Params& P, int tm, int tn, unsigned char* smem) {
;     ...
; #pragma unroll
;         for (int i = 0; i < 4; ++i) { fa[i] = *(const bf16x8*)(sA + arow_off + i * 2048 + ch0); fb[i] = *(const bf16x8*)(sB + brow_off + i * 2048 + ch0); }
;         __builtin_amdgcn_sched_barrier(0);
;         __builtin_amdgcn_s_setprio(2);
;         if (wr_ok) *(uint4*)(nA + soff0) = ra0;
;         if (ld_ok) ra0 = *(const uint4*)(Ab + (aoff + 0u * LDA + koa));
;         ga[0] = *(const bf16x8*)(sA + arow_off + 0 * 2048 + ch1); gb[0] = *(const bf16x8*)(sB + brow_off + 0 * 2048 + ch1);
;         __builtin_amdgcn_sched_barrier(0);
; #pragma unroll
;         for (int j = 0; j < 4; ++j) acc[0][j] = __builtin_amdgcn_mfma_f32_16x16x32_bf16(fb[j], fa[0], acc[0][j], 0, 0, 0);
;         __builtin_amdgcn_sched_barrier(0);
;         if (wr_ok) *(uint4*)(nA + soff0 + 4096) = ra1;
;         if (ld_ok) ra1 = *(const uint4*)(Ab + (aoff + 32u * LDA + koa));
;         ga[1] = *(const bf16x8*)(sA + arow_off + 1 * 2048 + ch1); gb[1] = *(const bf16x8*)(sB + brow_off + 1 * 2048 + ch1);
;         __builtin_amdgcn_sched_barrier(0);
; #pragma unroll
;         for (int j = 0; j < 4; ++j) acc[1][j] = __builtin_amdgcn_mfma_f32_16x16x32_bf16(fb[j], fa[1], acc[1][j], 0, 0, 0);
;         __builtin_amdgcn_sched_barrier(0);
;         if (wr_ok) *(uint4*)(nA + soff0 + 8192) = ra2;
;         if (ld_ok) ra2 = *(const uint4*)(Ab + (aoff + 64u * LDA + koa));
;         ga[2] = *(const bf16x8*)(sA + arow_off + 2 * 2048 + ch1); gb[2] = *(const bf16x8*)(sB + brow_off + 2 * 2048 + ch1);
;         __builtin_amdgcn_sched_barrier(0);
; #pragma unroll
;         for (int j = 0; j < 4; ++j) acc[2][j] = __builtin_amdgcn_mfma_f32_16x16x32_bf16(fb[j], fa[2], acc[2][j], 0, 0, 0);
;         __builtin_amdgcn_sched_barrier(0);
;         if (wr_ok) *(uint4*)(nA + soff0 + 12288) = ra3;
;         if (ld_ok) ra3 = *(const uint4*)(Ab + (aoff + 96u * LDA + koa));
;         ga[3] = *(const bf16x8*)(sA + arow_off + 3 * 2048 + ch1); gb[3] = *(const bf16x8*)(sB + brow_off + 3 * 2048 + ch1);
;         __builtin_amdgcn_sched_barrier(0);
; #pragma unroll
;         for (int j = 0; j < 4; ++j) acc[3][j] = __builtin_amdgcn_mfma_f32_16x16x32_bf16(fb[j], fa[3], acc[3][j], 0, 0, 0);
;         __builtin_amdgcn_sched_barrier(0);
;         if (wr_ok) *(uint4*)(nB + soff0) = rb0;
	ds_read_b128 v[92:95], v22
	ds_read_b128 v[112:115], v22 offset:2048
	ds_read_b128 v[132:135], v23 offset:16384
	ds_read_b128 v[140:143], v23 offset:18432
	ds_read_b128 v[144:147], v22 offset:4096
	ds_read_b128 v[152:155], v22 offset:6144
	ds_read_b128 v[156:159], v23 offset:20480
	ds_read_b128 v[160:163], v23 offset:22528
	s_setprio 2
	s_add_u32 s92, s92, 0x80
	s_addc_u32 s93, s93, 0
	s_add_u32 s94, s94, 0x80
	s_addc_u32 s95, s95, 0
	s_add_u32 m0, s96, 0x8000
	ds_read_b128 v[168:171], v20
	global_load_lds_dwordx4 v240, s[92:93]
	s_add_u32 m0, s96, 0x9000
	ds_read_b128 v[172:175], v21 offset:16384
	global_load_lds_dwordx4 v241, s[92:93]
	s_add_u32 m0, s96, 0xa000
	s_waitcnt lgkmcnt(7)
	global_load_lds_dwordx4 v242, s[92:93]
	s_add_u32 m0, s96, 0xb000
	v_mfma_f32_16x16x32_bf16 v[42:45], v[132:135], v[92:95], v[42:45]
	global_load_lds_dwordx4 v243, s[92:93]
	s_add_u32 m0, s96, 0xc000
	s_waitcnt lgkmcnt(2)
	global_load_lds_dwordx4 v244, s[94:95]
	s_add_u32 m0, s96, 0xd000
	v_mfma_f32_16x16x32_bf16 v[26:29], v[160:163], v[92:95], v[26:29]
	global_load_lds_dwordx4 v245, s[94:95]
	s_add_u32 m0, s96, 0xe000
	v_mfma_f32_16x16x32_bf16 v[96:99], v[140:143], v[92:95], v[96:99]
	global_load_lds_dwordx4 v246, s[94:95]
	s_add_u32 m0, s96, 0xf000
	v_mfma_f32_16x16x32_bf16 v[104:107], v[156:159], v[92:95], v[104:107]
	global_load_lds_dwordx4 v247, s[94:95]
	v_mfma_f32_16x16x32_bf16 v[46:49], v[132:135], v[112:115], v[46:49]
	v_mfma_f32_16x16x32_bf16 v[58:61], v[140:143], v[112:115], v[58:61]
	ds_read_b128 v[116:119], v20 offset:2048
	v_mfma_f32_16x16x32_bf16 v[30:33], v[160:163], v[112:115], v[30:33]
	ds_read_b128 v[176:179], v21 offset:18432
	v_mfma_f32_16x16x32_bf16 v[100:103], v[156:159], v[112:115], v[100:103]
	v_mfma_f32_16x16x32_bf16 v[50:53], v[132:135], v[144:147], v[50:53]
	v_mfma_f32_16x16x32_bf16 v[62:65], v[140:143], v[144:147], v[62:65]
	ds_read_b128 v[120:123], v20 offset:4096
	v_mfma_f32_16x16x32_bf16 v[78:81], v[156:159], v[144:147], v[78:81]
	ds_read_b128 v[180:183], v21 offset:20480
	v_mfma_f32_16x16x32_bf16 v[34:37], v[160:163], v[144:147], v[34:37]
	v_mfma_f32_16x16x32_bf16 v[54:57], v[132:135], v[152:155], v[54:57]
	v_mfma_f32_16x16x32_bf16 v[66:69], v[140:143], v[152:155], v[66:69]
	ds_read_b128 v[148:151], v20 offset:6144
	v_mfma_f32_16x16x32_bf16 v[70:73], v[156:159], v[152:155], v[70:73]
	ds_read_b128 v[184:187], v21 offset:22528
	v_mfma_f32_16x16x32_bf16 v[38:41], v[160:163], v[152:155], v[38:41]
	s_waitcnt lgkmcnt(6)
	v_mfma_f32_16x16x32_bf16 v[42:45], v[172:175], v[168:171], v[42:45]
	s_waitcnt lgkmcnt(0)
	v_mfma_f32_16x16x32_bf16 v[26:29], v[184:187], v[168:171], v[26:29]
	v_mfma_f32_16x16x32_bf16 v[96:99], v[176:179], v[168:171], v[96:99]
	v_mfma_f32_16x16x32_bf16 v[104:107], v[180:183], v[168:171], v[104:107]
	v_mfma_f32_16x16x32_bf16 v[46:49], v[172:175], v[116:119], v[46:49]
	v_mfma_f32_16x16x32_bf16 v[58:61], v[176:179], v[116:119], v[58:61]
	v_mfma_f32_16x16x32_bf16 v[30:33], v[184:187], v[116:119], v[30:33]
	v_mfma_f32_16x16x32_bf16 v[100:103], v[180:183], v[116:119], v[100:103]
	v_mfma_f32_16x16x32_bf16 v[50:53], v[172:175], v[120:123], v[50:53]
	v_mfma_f32_16x16x32_bf16 v[62:65], v[176:179], v[120:123], v[62:65]
	v_mfma_f32_16x16x32_bf16 v[74:77], v[180:183], v[120:123], v[78:81]
	v_mfma_f32_16x16x32_bf16 v[34:37], v[184:187], v[120:123], v[34:37]
	v_mfma_f32_16x16x32_bf16 v[54:57], v[172:175], v[148:151], v[54:57]
	v_mfma_f32_16x16x32_bf16 v[66:69], v[176:179], v[148:151], v[66:69]
	v_mfma_f32_16x16x32_bf16 v[70:73], v[180:183], v[148:151], v[70:73]
	v_mfma_f32_16x16x32_bf16 v[38:41], v[184:187], v[148:151], v[38:41]
	s_setprio 0
	s_waitcnt vmcnt(0) lgkmcnt(0)
	s_barrier
	ds_read_b128 v[108:111], v22 offset:32768
	ds_read_b128 v[120:123], v22 offset:34816
	ds_read_b128 v[136:139], v23 offset:49152
	ds_read_b128 v[140:143], v23 offset:51200
	ds_read_b128 v[148:151], v22 offset:36864
	ds_read_b128 v[152:155], v22 offset:38912
	ds_read_b128 v[156:159], v23 offset:53248
	ds_read_b128 v[160:163], v23 offset:55296
	s_setprio 2
	s_add_u32 s92, s92, 0x80
	s_addc_u32 s93, s93, 0
	s_add_u32 s94, s94, 0x80
	s_addc_u32 s95, s95, 0
	s_mov_b32 m0, s96
	ds_read_b128 v[164:167], v20 offset:32768
	global_load_lds_dwordx4 v240, s[92:93]
	s_add_u32 m0, s96, 0x1000
	ds_read_b128 v[172:175], v21 offset:49152
	global_load_lds_dwordx4 v241, s[92:93]
	s_add_u32 m0, s96, 0x2000
	s_waitcnt lgkmcnt(7)
	global_load_lds_dwordx4 v242, s[92:93]
	s_add_u32 m0, s96, 0x3000
	v_mfma_f32_16x16x32_bf16 v[42:45], v[136:139], v[108:111], v[42:45]
	global_load_lds_dwordx4 v243, s[92:93]
	s_add_u32 m0, s96, 0x4000
	s_waitcnt lgkmcnt(2)
	global_load_lds_dwordx4 v244, s[94:95]
	s_add_u32 m0, s96, 0x5000
	v_mfma_f32_16x16x32_bf16 v[26:29], v[160:163], v[108:111], v[26:29]
	global_load_lds_dwordx4 v245, s[94:95]
	s_add_u32 m0, s96, 0x6000
	v_mfma_f32_16x16x32_bf16 v[96:99], v[140:143], v[108:111], v[96:99]
	global_load_lds_dwordx4 v246, s[94:95]
	s_add_u32 m0, s96, 0x7000
	v_mfma_f32_16x16x32_bf16 v[104:107], v[156:159], v[108:111], v[104:107]
	global_load_lds_dwordx4 v247, s[94:95]
	v_mfma_f32_16x16x32_bf16 v[46:49], v[136:139], v[120:123], v[46:49]
	v_mfma_f32_16x16x32_bf16 v[58:61], v[140:143], v[120:123], v[58:61]
	ds_read_b128 v[92:95], v20 offset:34816
	v_mfma_f32_16x16x32_bf16 v[30:33], v[160:163], v[120:123], v[30:33]
	ds_read_b128 v[176:179], v21 offset:51200
	v_mfma_f32_16x16x32_bf16 v[100:103], v[156:159], v[120:123], v[100:103]
	v_mfma_f32_16x16x32_bf16 v[50:53], v[136:139], v[148:151], v[50:53]
	v_mfma_f32_16x16x32_bf16 v[62:65], v[140:143], v[148:151], v[62:65]
	ds_read_b128 v[112:115], v20 offset:36864
	v_mfma_f32_16x16x32_bf16 v[74:77], v[156:159], v[148:151], v[74:77]
	ds_read_b128 v[180:183], v21 offset:53248
	v_mfma_f32_16x16x32_bf16 v[34:37], v[160:163], v[148:151], v[34:37]
	v_mfma_f32_16x16x32_bf16 v[54:57], v[136:139], v[152:155], v[54:57]
	v_mfma_f32_16x16x32_bf16 v[66:69], v[140:143], v[152:155], v[66:69]
	ds_read_b128 v[144:147], v20 offset:38912
	v_mfma_f32_16x16x32_bf16 v[70:73], v[156:159], v[152:155], v[70:73]
	ds_read_b128 v[184:187], v21 offset:55296
	v_mfma_f32_16x16x32_bf16 v[38:41], v[160:163], v[152:155], v[38:41]
	s_waitcnt lgkmcnt(6)
; template <int MODE>
; __device__ __forceinline__ void gemm_tile(const Params& P, int tm, int tn, unsigned char* smem) {
;     ...
; #pragma unroll
;         for (int i = 0; i < 4; ++i) { fa[i] = *(const bf16x8*)(sA + arow_off + i * 2048 + ch0); fb[i] = *(const bf16x8*)(sB + brow_off + i * 2048 + ch0); }
;         __builtin_amdgcn_sched_barrier(0);
;         __builtin_amdgcn_s_setprio(2);
;         if (wr_ok) *(uint4*)(nA + soff0) = ra0;
;         if (ld_ok) ra0 = *(const uint4*)(Ab + (aoff + 0u * LDA + koa));
;         ga[0] = *(const bf16x8*)(sA + arow_off + 0 * 2048 + ch1); gb[0] = *(const bf16x8*)(sB + brow_off + 0 * 2048 + ch1);
;         __builtin_amdgcn_sched_barrier(0);
; #pragma unroll
;         for (int j = 0; j < 4; ++j) acc[0][j] = __builtin_amdgcn_mfma_f32_16x16x32_bf16(fb[j], fa[0], acc[0][j], 0, 0, 0);
;         __builtin_amdgcn_sched_barrier(0);
;         if (wr_ok) *(uint4*)(nA + soff0 + 4096) = ra1;
;         if (ld_ok) ra1 = *(const uint4*)(Ab + (aoff + 32u * LDA + koa));
;         ga[1] = *(const bf16x8*)(sA + arow_off + 1 * 2048 + ch1); gb[1] = *(const bf16x8*)(sB + brow_off + 1 * 2048 + ch1);
;         __builtin_amdgcn_sched_barrier(0);
; #pragma unroll
;         for (int j = 0; j < 4; ++j) acc[1][j] = __builtin_amdgcn_mfma_f32_16x16x32_bf16(fb[j], fa[1], acc[1][j], 0, 0, 0);
;         __builtin_amdgcn_sched_barrier(0);
;         if (wr_ok) *(uint4*)(nA + soff0 + 8192) = ra2;
;         if (ld_ok) ra2 = *(const uint4*)(Ab + (aoff + 64u * LDA + koa));
;         ga[2] = *(const bf16x8*)(sA + arow_off + 2 * 2048 + ch1); gb[2] = *(const bf16x8*)(sB + brow_off + 2 * 2048 + ch1);
;         __builtin_amdgcn_sched_barrier(0);
; #pragma unroll
;         for (int j = 0; j < 4; ++j) acc[2][j] = __builtin_amdgcn_mfma_f32_16x16x32_bf16(fb[j], fa[2], acc[2][j], 0, 0, 0);
;         __builtin_amdgcn_sched_barrier(0);
;         if (wr_ok) *(uint4*)(nA + soff0 + 12288) = ra3;
;         if (ld_ok) ra3 = *(const uint4*)(Ab + (aoff + 96u * LDA + koa));
;         ga[3] = *(const bf16x8*)(sA + arow_off + 3 * 2048 + ch1); gb[3] = *(const bf16x8*)(sB + brow_off + 3 * 2048 + ch1);
;         __builtin_amdgcn_sched_barrier(0);
; #pragma unroll
;         for (int j = 0; j < 4; ++j) acc[3][j] = __builtin_amdgcn_mfma_f32_16x16x32_bf16(fb[j], fa[3], acc[3][j], 0, 0, 0);
;         __builtin_amdgcn_sched_barrier(0);
;         if (wr_ok) *(uint4*)(nB + soff0) = rb0;
	v_mfma_f32_16x16x32_bf16 v[42:45], v[172:175], v[164:167], v[42:45]
	s_waitcnt lgkmcnt(0)
	v_mfma_f32_16x16x32_bf16 v[26:29], v[184:187], v[164:167], v[26:29]
	v_mfma_f32_16x16x32_bf16 v[96:99], v[176:179], v[164:167], v[96:99]
	v_mfma_f32_16x16x32_bf16 v[104:107], v[180:183], v[164:167], v[104:107]
	v_mfma_f32_16x16x32_bf16 v[46:49], v[172:175], v[92:95], v[46:49]
	v_mfma_f32_16x16x32_bf16 v[58:61], v[176:179], v[92:95], v[58:61]
	v_mfma_f32_16x16x32_bf16 v[30:33], v[184:187], v[92:95], v[30:33]
	v_mfma_f32_16x16x32_bf16 v[100:103], v[180:183], v[92:95], v[100:103]
	v_mfma_f32_16x16x32_bf16 v[50:53], v[172:175], v[112:115], v[50:53]
	v_mfma_f32_16x16x32_bf16 v[62:65], v[176:179], v[112:115], v[62:65]
	v_mfma_f32_16x16x32_bf16 v[74:77], v[180:183], v[112:115], v[74:77]
	v_mfma_f32_16x16x32_bf16 v[34:37], v[184:187], v[112:115], v[34:37]
	v_mfma_f32_16x16x32_bf16 v[54:57], v[172:175], v[144:147], v[54:57]
	v_mfma_f32_16x16x32_bf16 v[66:69], v[176:179], v[144:147], v[66:69]
	v_mfma_f32_16x16x32_bf16 v[70:73], v[180:183], v[144:147], v[70:73]
	v_mfma_f32_16x16x32_bf16 v[38:41], v[184:187], v[144:147], v[38:41]
	s_setprio 0
	s_waitcnt vmcnt(0) lgkmcnt(0)
	s_barrier
	ds_read_b128 v[78:81], v22
	ds_read_b128 v[116:119], v22 offset:2048
	ds_read_b128 v[124:127], v23 offset:16384
	ds_read_b128 v[140:143], v23 offset:18432
	ds_read_b128 v[144:147], v22 offset:4096
	ds_read_b128 v[152:155], v22 offset:6144
	ds_read_b128 v[156:159], v23 offset:20480
	ds_read_b128 v[160:163], v23 offset:22528
	s_setprio 2
	s_add_u32 s92, s92, 0x80
	s_addc_u32 s93, s93, 0
	s_add_u32 s94, s94, 0x80
	s_addc_u32 s95, s95, 0
	s_add_u32 m0, s96, 0x8000
	ds_read_b128 v[168:171], v20
	global_load_lds_dwordx4 v240, s[92:93]
	s_add_u32 m0, s96, 0x9000
	ds_read_b128 v[172:175], v21 offset:16384
	global_load_lds_dwordx4 v241, s[92:93]
	s_add_u32 m0, s96, 0xa000
	s_waitcnt lgkmcnt(7)
	global_load_lds_dwordx4 v242, s[92:93]
	s_add_u32 m0, s96, 0xb000
	v_mfma_f32_16x16x32_bf16 v[42:45], v[124:127], v[78:81], v[42:45]
	global_load_lds_dwordx4 v243, s[92:93]
	s_add_u32 m0, s96, 0xc000
	s_waitcnt lgkmcnt(2)
	global_load_lds_dwordx4 v244, s[94:95]
	s_add_u32 m0, s96, 0xd000
	v_mfma_f32_16x16x32_bf16 v[26:29], v[160:163], v[78:81], v[26:29]
	global_load_lds_dwordx4 v245, s[94:95]
	s_add_u32 m0, s96, 0xe000
	v_mfma_f32_16x16x32_bf16 v[96:99], v[140:143], v[78:81], v[96:99]
	global_load_lds_dwordx4 v246, s[94:95]
	s_add_u32 m0, s96, 0xf000
	v_mfma_f32_16x16x32_bf16 v[104:107], v[156:159], v[78:81], v[104:107]
	global_load_lds_dwordx4 v247, s[94:95]
	v_mfma_f32_16x16x32_bf16 v[46:49], v[124:127], v[116:119], v[46:49]
	v_mfma_f32_16x16x32_bf16 v[58:61], v[140:143], v[116:119], v[58:61]
	ds_read_b128 v[108:111], v20 offset:2048
	v_mfma_f32_16x16x32_bf16 v[30:33], v[160:163], v[116:119], v[30:33]
	ds_read_b128 v[176:179], v21 offset:18432
	v_mfma_f32_16x16x32_bf16 v[100:103], v[156:159], v[116:119], v[100:103]
	v_mfma_f32_16x16x32_bf16 v[50:53], v[124:127], v[144:147], v[50:53]
	v_mfma_f32_16x16x32_bf16 v[62:65], v[140:143], v[144:147], v[62:65]
	ds_read_b128 v[120:123], v20 offset:4096
	v_mfma_f32_16x16x32_bf16 v[74:77], v[156:159], v[144:147], v[74:77]
	ds_read_b128 v[180:183], v21 offset:20480
	v_mfma_f32_16x16x32_bf16 v[34:37], v[160:163], v[144:147], v[34:37]
	v_mfma_f32_16x16x32_bf16 v[54:57], v[124:127], v[152:155], v[54:57]
	v_mfma_f32_16x16x32_bf16 v[66:69], v[140:143], v[152:155], v[66:69]
	ds_read_b128 v[148:151], v20 offset:6144
	v_mfma_f32_16x16x32_bf16 v[70:73], v[156:159], v[152:155], v[70:73]
	ds_read_b128 v[184:187], v21 offset:22528
	v_mfma_f32_16x16x32_bf16 v[38:41], v[160:163], v[152:155], v[38:41]
	s_waitcnt lgkmcnt(6)
	v_mfma_f32_16x16x32_bf16 v[42:45], v[172:175], v[168:171], v[42:45]
	s_waitcnt lgkmcnt(0)
	v_mfma_f32_16x16x32_bf16 v[26:29], v[184:187], v[168:171], v[26:29]
	v_mfma_f32_16x16x32_bf16 v[96:99], v[176:179], v[168:171], v[96:99]
	v_mfma_f32_16x16x32_bf16 v[104:107], v[180:183], v[168:171], v[104:107]
	v_mfma_f32_16x16x32_bf16 v[46:49], v[172:175], v[108:111], v[46:49]
	v_mfma_f32_16x16x32_bf16 v[58:61], v[176:179], v[108:111], v[58:61]
	v_mfma_f32_16x16x32_bf16 v[30:33], v[184:187], v[108:111], v[30:33]
	v_mfma_f32_16x16x32_bf16 v[100:103], v[180:183], v[108:111], v[100:103]
	v_mfma_f32_16x16x32_bf16 v[50:53], v[172:175], v[120:123], v[50:53]
	v_mfma_f32_16x16x32_bf16 v[62:65], v[176:179], v[120:123], v[62:65]
	v_mfma_f32_16x16x32_bf16 v[74:77], v[180:183], v[120:123], v[74:77]
	v_mfma_f32_16x16x32_bf16 v[34:37], v[184:187], v[120:123], v[34:37]
	v_mfma_f32_16x16x32_bf16 v[54:57], v[172:175], v[148:151], v[54:57]
	v_mfma_f32_16x16x32_bf16 v[66:69], v[176:179], v[148:151], v[66:69]
	v_mfma_f32_16x16x32_bf16 v[70:73], v[180:183], v[148:151], v[70:73]
	v_mfma_f32_16x16x32_bf16 v[38:41], v[184:187], v[148:151], v[38:41]
	s_setprio 0
	s_waitcnt vmcnt(0) lgkmcnt(0)
	s_barrier
; template <int MODE>
; __device__ __forceinline__ void gemm_tile(const Params& P, int tm, int tn, unsigned char* smem) {
;     ...
; #pragma unroll
;         for (int i = 0; i < 4; ++i) { fa[i] = *(const bf16x8*)(sA + arow_off + i * 2048 + ch0); fb[i] = *(const bf16x8*)(sB + brow_off + i * 2048 + ch0); }
;         __builtin_amdgcn_sched_barrier(0);
;         __builtin_amdgcn_s_setprio(2);
;         if (wr_ok) *(uint4*)(nA + soff0) = ra0;
;         if (ld_ok) ra0 = *(const uint4*)(Ab + (aoff + 0u * LDA + koa));
;         ga[0] = *(const bf16x8*)(sA + arow_off + 0 * 2048 + ch1); gb[0] = *(const bf16x8*)(sB + brow_off + 0 * 2048 + ch1);
;         __builtin_amdgcn_sched_barrier(0);
; #pragma unroll
;         for (int j = 0; j < 4; ++j) acc[0][j] = __builtin_amdgcn_mfma_f32_16x16x32_bf16(fb[j], fa[0], acc[0][j], 0, 0, 0);
;         __builtin_amdgcn_sched_barrier(0);
;         if (wr_ok) *(uint4*)(nA + soff0 + 4096) = ra1;
;         if (ld_ok) ra1 = *(const uint4*)(Ab + (aoff + 32u * LDA + koa));
;         ga[1] = *(const bf16x8*)(sA + arow_off + 1 * 2048 + ch1); gb[1] = *(const bf16x8*)(sB + brow_off + 1 * 2048 + ch1);
;         __builtin_amdgcn_sched_barrier(0);
; #pragma unroll
;         for (int j = 0; j < 4; ++j) acc[1][j] = __builtin_amdgcn_mfma_f32_16x16x32_bf16(fb[j], fa[1], acc[1][j], 0, 0, 0);
;         __builtin_amdgcn_sched_barrier(0);
;         if (wr_ok) *(uint4*)(nA + soff0 + 8192) = ra2;
;         if (ld_ok) ra2 = *(const uint4*)(Ab + (aoff + 64u * LDA + koa));
;         ga[2] = *(const bf16x8*)(sA + arow_off + 2 * 2048 + ch1); gb[2] = *(const bf16x8*)(sB + brow_off + 2 * 2048 + ch1);
;         __builtin_amdgcn_sched_barrier(0);
; #pragma unroll
;         for (int j = 0; j < 4; ++j) acc[2][j] = __builtin_amdgcn_mfma_f32_16x16x32_bf16(fb[j], fa[2], acc[2][j], 0, 0, 0);
;         __builtin_amdgcn_sched_barrier(0);
;         if (wr_ok) *(uint4*)(nA + soff0 + 12288) = ra3;
;         if (ld_ok) ra3 = *(const uint4*)(Ab + (aoff + 96u * LDA + koa));
;         ga[3] = *(const bf16x8*)(sA + arow_off + 3 * 2048 + ch1); gb[3] = *(const bf16x8*)(sB + brow_off + 3 * 2048 + ch1);
;         __builtin_amdgcn_sched_barrier(0);
; #pragma unroll
;         for (int j = 0; j < 4; ++j) acc[3][j] = __builtin_amdgcn_mfma_f32_16x16x32_bf16(fb[j], fa[3], acc[3][j], 0, 0, 0);
;         __builtin_amdgcn_sched_barrier(0);
;         if (wr_ok) *(uint4*)(nB + soff0) = rb0;
	ds_read_b128 v[112:115], v22 offset:32768
	ds_read_b128 v[120:123], v22 offset:34816
	ds_read_b128 v[132:135], v23 offset:49152
	ds_read_b128 v[140:143], v23 offset:51200
	ds_read_b128 v[148:151], v22 offset:36864
	ds_read_b128 v[152:155], v22 offset:38912
	ds_read_b128 v[156:159], v23 offset:53248
	ds_read_b128 v[160:163], v23 offset:55296
	s_setprio 2
	s_add_u32 s92, s92, 0x80
	s_addc_u32 s93, s93, 0
	s_add_u32 s94, s94, 0x80
	s_addc_u32 s95, s95, 0
	s_mov_b32 m0, s96
	ds_read_b128 v[164:167], v20 offset:32768
	global_load_lds_dwordx4 v240, s[92:93]
	s_add_u32 m0, s96, 0x1000
	ds_read_b128 v[172:175], v21 offset:49152
	global_load_lds_dwordx4 v241, s[92:93]
	s_add_u32 m0, s96, 0x2000
	s_waitcnt lgkmcnt(7)
	global_load_lds_dwordx4 v242, s[92:93]
	s_add_u32 m0, s96, 0x3000
	v_mfma_f32_16x16x32_bf16 v[42:45], v[132:135], v[112:115], v[42:45]
	global_load_lds_dwordx4 v243, s[92:93]
	s_add_u32 m0, s96, 0x4000
	s_waitcnt lgkmcnt(2)
	global_load_lds_dwordx4 v244, s[94:95]
	s_add_u32 m0, s96, 0x5000
	v_mfma_f32_16x16x32_bf16 v[26:29], v[160:163], v[112:115], v[26:29]
	global_load_lds_dwordx4 v245, s[94:95]
	s_add_u32 m0, s96, 0x6000
	v_mfma_f32_16x16x32_bf16 v[96:99], v[140:143], v[112:115], v[96:99]
	global_load_lds_dwordx4 v246, s[94:95]
	s_add_u32 m0, s96, 0x7000
	v_mfma_f32_16x16x32_bf16 v[104:107], v[156:159], v[112:115], v[104:107]
	global_load_lds_dwordx4 v247, s[94:95]
	v_mfma_f32_16x16x32_bf16 v[46:49], v[132:135], v[120:123], v[46:49]
	v_mfma_f32_16x16x32_bf16 v[58:61], v[140:143], v[120:123], v[58:61]
	ds_read_b128 v[78:81], v20 offset:34816
	v_mfma_f32_16x16x32_bf16 v[30:33], v[160:163], v[120:123], v[30:33]
	ds_read_b128 v[176:179], v21 offset:51200
	v_mfma_f32_16x16x32_bf16 v[100:103], v[156:159], v[120:123], v[100:103]
	v_mfma_f32_16x16x32_bf16 v[50:53], v[132:135], v[148:151], v[50:53]
	v_mfma_f32_16x16x32_bf16 v[62:65], v[140:143], v[148:151], v[62:65]
	ds_read_b128 v[116:119], v20 offset:36864
	v_mfma_f32_16x16x32_bf16 v[74:77], v[156:159], v[148:151], v[74:77]
	ds_read_b128 v[180:183], v21 offset:53248
	v_mfma_f32_16x16x32_bf16 v[34:37], v[160:163], v[148:151], v[34:37]
	v_mfma_f32_16x16x32_bf16 v[54:57], v[132:135], v[152:155], v[54:57]
	v_mfma_f32_16x16x32_bf16 v[66:69], v[140:143], v[152:155], v[66:69]
	ds_read_b128 v[144:147], v20 offset:38912
	v_mfma_f32_16x16x32_bf16 v[70:73], v[156:159], v[152:155], v[70:73]
	ds_read_b128 v[184:187], v21 offset:55296
	v_mfma_f32_16x16x32_bf16 v[38:41], v[160:163], v[152:155], v[38:41]
	s_waitcnt lgkmcnt(6)
	v_mfma_f32_16x16x32_bf16 v[42:45], v[172:175], v[164:167], v[42:45]
	s_waitcnt lgkmcnt(0)
	v_mfma_f32_16x16x32_bf16 v[26:29], v[184:187], v[164:167], v[26:29]
	v_mfma_f32_16x16x32_bf16 v[96:99], v[176:179], v[164:167], v[96:99]
	v_mfma_f32_16x16x32_bf16 v[104:107], v[180:183], v[164:167], v[104:107]
	v_mfma_f32_16x16x32_bf16 v[46:49], v[172:175], v[78:81], v[46:49]
	v_mfma_f32_16x16x32_bf16 v[58:61], v[176:179], v[78:81], v[58:61]
	v_mfma_f32_16x16x32_bf16 v[30:33], v[184:187], v[78:81], v[30:33]
	v_mfma_f32_16x16x32_bf16 v[100:103], v[180:183], v[78:81], v[100:103]
	v_mfma_f32_16x16x32_bf16 v[50:53], v[172:175], v[116:119], v[50:53]
	v_mfma_f32_16x16x32_bf16 v[62:65], v[176:179], v[116:119], v[62:65]
	v_mfma_f32_16x16x32_bf16 v[74:77], v[180:183], v[116:119], v[74:77]
	v_mfma_f32_16x16x32_bf16 v[34:37], v[184:187], v[116:119], v[34:37]
	v_mfma_f32_16x16x32_bf16 v[54:57], v[172:175], v[144:147], v[54:57]
	v_mfma_f32_16x16x32_bf16 v[66:69], v[176:179], v[144:147], v[66:69]
	v_mfma_f32_16x16x32_bf16 v[70:73], v[180:183], v[144:147], v[70:73]
	v_mfma_f32_16x16x32_bf16 v[38:41], v[184:187], v[144:147], v[38:41]
	s_setprio 0
	s_waitcnt vmcnt(0) lgkmcnt(0)
	s_barrier
	ds_read_b128 v[92:95], v22
	ds_read_b128 v[116:119], v22 offset:2048
	ds_read_b128 v[136:139], v23 offset:16384
	ds_read_b128 v[140:143], v23 offset:18432
	ds_read_b128 v[144:147], v22 offset:4096
	ds_read_b128 v[152:155], v22 offset:6144
	ds_read_b128 v[156:159], v23 offset:20480
	ds_read_b128 v[160:163], v23 offset:22528
	s_setprio 2
	s_add_u32 s92, s92, 0x80
	s_addc_u32 s93, s93, 0
	s_add_u32 s94, s94, 0x80
	s_addc_u32 s95, s95, 0
	s_add_u32 m0, s96, 0x8000
	ds_read_b128 v[168:171], v20
	global_load_lds_dwordx4 v240, s[92:93]
	s_add_u32 m0, s96, 0x9000
	ds_read_b128 v[172:175], v21 offset:16384
	global_load_lds_dwordx4 v241, s[92:93]
	s_add_u32 m0, s96, 0xa000
	s_waitcnt lgkmcnt(7)
	global_load_lds_dwordx4 v242, s[92:93]
	s_add_u32 m0, s96, 0xb000
	v_mfma_f32_16x16x32_bf16 v[42:45], v[136:139], v[92:95], v[42:45]
	global_load_lds_dwordx4 v243, s[92:93]
	s_add_u32 m0, s96, 0xc000
	s_waitcnt lgkmcnt(2)
	global_load_lds_dwordx4 v244, s[94:95]
	s_add_u32 m0, s96, 0xd000
	v_mfma_f32_16x16x32_bf16 v[26:29], v[160:163], v[92:95], v[26:29]
	global_load_lds_dwordx4 v245, s[94:95]
	s_add_u32 m0, s96, 0xe000
	v_mfma_f32_16x16x32_bf16 v[96:99], v[140:143], v[92:95], v[96:99]
	global_load_lds_dwordx4 v246, s[94:95]
	s_add_u32 m0, s96, 0xf000
	v_mfma_f32_16x16x32_bf16 v[104:107], v[156:159], v[92:95], v[104:107]
	global_load_lds_dwordx4 v247, s[94:95]
	v_mfma_f32_16x16x32_bf16 v[46:49], v[136:139], v[116:119], v[46:49]
	v_mfma_f32_16x16x32_bf16 v[58:61], v[140:143], v[116:119], v[58:61]
	ds_read_b128 v[112:115], v20 offset:2048
	v_mfma_f32_16x16x32_bf16 v[30:33], v[160:163], v[116:119], v[30:33]
	ds_read_b128 v[176:179], v21 offset:18432
	v_mfma_f32_16x16x32_bf16 v[100:103], v[156:159], v[116:119], v[100:103]
	v_mfma_f32_16x16x32_bf16 v[50:53], v[136:139], v[144:147], v[50:53]
	v_mfma_f32_16x16x32_bf16 v[62:65], v[140:143], v[144:147], v[62:65]
	ds_read_b128 v[120:123], v20 offset:4096
	v_mfma_f32_16x16x32_bf16 v[74:77], v[156:159], v[144:147], v[74:77]
	ds_read_b128 v[180:183], v21 offset:20480
	v_mfma_f32_16x16x32_bf16 v[34:37], v[160:163], v[144:147], v[34:37]
	v_mfma_f32_16x16x32_bf16 v[54:57], v[136:139], v[152:155], v[54:57]
	v_mfma_f32_16x16x32_bf16 v[66:69], v[140:143], v[152:155], v[66:69]
	ds_read_b128 v[148:151], v20 offset:6144
	v_mfma_f32_16x16x32_bf16 v[70:73], v[156:159], v[152:155], v[70:73]
	ds_read_b128 v[184:187], v21 offset:22528
	v_mfma_f32_16x16x32_bf16 v[38:41], v[160:163], v[152:155], v[38:41]
	s_waitcnt lgkmcnt(6)
; template <int MODE>
; __device__ __forceinline__ void gemm_tile(const Params& P, int tm, int tn, unsigned char* smem) {
;     ...
; #pragma unroll
;         for (int i = 0; i < 4; ++i) { fa[i] = *(const bf16x8*)(sA + arow_off + i * 2048 + ch0); fb[i] = *(const bf16x8*)(sB + brow_off + i * 2048 + ch0); }
;         __builtin_amdgcn_sched_barrier(0);
;         __builtin_amdgcn_s_setprio(2);
;         if (wr_ok) *(uint4*)(nA + soff0) = ra0;
;         if (ld_ok) ra0 = *(const uint4*)(Ab + (aoff + 0u * LDA + koa));
;         ga[0] = *(const bf16x8*)(sA + arow_off + 0 * 2048 + ch1); gb[0] = *(const bf16x8*)(sB + brow_off + 0 * 2048 + ch1);
;         __builtin_amdgcn_sched_barrier(0);
; #pragma unroll
;         for (int j = 0; j < 4; ++j) acc[0][j] = __builtin_amdgcn_mfma_f32_16x16x32_bf16(fb[j], fa[0], acc[0][j], 0, 0, 0);
;         __builtin_amdgcn_sched_barrier(0);
;         if (wr_ok) *(uint4*)(nA + soff0 + 4096) = ra1;
;         if (ld_ok) ra1 = *(const uint4*)(Ab + (aoff + 32u * LDA + koa));
;         ga[1] = *(const bf16x8*)(sA + arow_off + 1 * 2048 + ch1); gb[1] = *(const bf16x8*)(sB + brow_off + 1 * 2048 + ch1);
;         __builtin_amdgcn_sched_barrier(0);
; #pragma unroll
;         for (int j = 0; j < 4; ++j) acc[1][j] = __builtin_amdgcn_mfma_f32_16x16x32_bf16(fb[j], fa[1], acc[1][j], 0, 0, 0);
;         __builtin_amdgcn_sched_barrier(0);
;         if (wr_ok) *(uint4*)(nA + soff0 + 8192) = ra2;
;         if (ld_ok) ra2 = *(const uint4*)(Ab + (aoff + 64u * LDA + koa));
;         ga[2] = *(const bf16x8*)(sA + arow_off + 2 * 2048 + ch1); gb[2] = *(const bf16x8*)(sB + brow_off + 2 * 2048 + ch1);
;         __builtin_amdgcn_sched_barrier(0);
; #pragma unroll
;         for (int j = 0; j < 4; ++j) acc[2][j] = __builtin_amdgcn_mfma_f32_16x16x32_bf16(fb[j], fa[2], acc[2][j], 0, 0, 0);
;         __builtin_amdgcn_sched_barrier(0);
;         if (wr_ok) *(uint4*)(nA + soff0 + 12288) = ra3;
;         if (ld_ok) ra3 = *(const uint4*)(Ab + (aoff + 96u * LDA + koa));
;         ga[3] = *(const bf16x8*)(sA + arow_off + 3 * 2048 + ch1); gb[3] = *(const bf16x8*)(sB + brow_off + 3 * 2048 + ch1);
;         __builtin_amdgcn_sched_barrier(0);
; #pragma unroll
;         for (int j = 0; j < 4; ++j) acc[3][j] = __builtin_amdgcn_mfma_f32_16x16x32_bf16(fb[j], fa[3], acc[3][j], 0, 0, 0);
;         __builtin_amdgcn_sched_barrier(0);
;         if (wr_ok) *(uint4*)(nB + soff0) = rb0;
	v_mfma_f32_16x16x32_bf16 v[42:45], v[172:175], v[168:171], v[42:45]
	s_waitcnt lgkmcnt(0)
	v_mfma_f32_16x16x32_bf16 v[26:29], v[184:187], v[168:171], v[26:29]
	v_mfma_f32_16x16x32_bf16 v[96:99], v[176:179], v[168:171], v[96:99]
	v_mfma_f32_16x16x32_bf16 v[104:107], v[180:183], v[168:171], v[104:107]
	v_mfma_f32_16x16x32_bf16 v[46:49], v[172:175], v[112:115], v[46:49]
	v_mfma_f32_16x16x32_bf16 v[58:61], v[176:179], v[112:115], v[58:61]
	v_mfma_f32_16x16x32_bf16 v[30:33], v[184:187], v[112:115], v[30:33]
	v_mfma_f32_16x16x32_bf16 v[100:103], v[180:183], v[112:115], v[100:103]
	v_mfma_f32_16x16x32_bf16 v[50:53], v[172:175], v[120:123], v[50:53]
	v_mfma_f32_16x16x32_bf16 v[62:65], v[176:179], v[120:123], v[62:65]
	v_mfma_f32_16x16x32_bf16 v[74:77], v[180:183], v[120:123], v[74:77]
	v_mfma_f32_16x16x32_bf16 v[34:37], v[184:187], v[120:123], v[34:37]
	v_mfma_f32_16x16x32_bf16 v[54:57], v[172:175], v[148:151], v[54:57]
	v_mfma_f32_16x16x32_bf16 v[66:69], v[176:179], v[148:151], v[66:69]
	v_mfma_f32_16x16x32_bf16 v[70:73], v[180:183], v[148:151], v[70:73]
	v_mfma_f32_16x16x32_bf16 v[38:41], v[184:187], v[148:151], v[38:41]
	s_setprio 0
	s_waitcnt vmcnt(0) lgkmcnt(0)
	s_barrier
	ds_read_b128 v[108:111], v22 offset:32768
	ds_read_b128 v[120:123], v22 offset:34816
	ds_read_b128 v[124:127], v23 offset:49152
	ds_read_b128 v[140:143], v23 offset:51200
	ds_read_b128 v[148:151], v22 offset:36864
	ds_read_b128 v[152:155], v22 offset:38912
	ds_read_b128 v[156:159], v23 offset:53248
	ds_read_b128 v[160:163], v23 offset:55296
	s_setprio 2
	s_add_u32 s92, s92, 0x80
	s_addc_u32 s93, s93, 0
	s_add_u32 s94, s94, 0x80
	s_addc_u32 s95, s95, 0
	s_mov_b32 m0, s96
	ds_read_b128 v[164:167], v20 offset:32768
	global_load_lds_dwordx4 v240, s[92:93]
	s_add_u32 m0, s96, 0x1000
	ds_read_b128 v[172:175], v21 offset:49152
	global_load_lds_dwordx4 v241, s[92:93]
	s_add_u32 m0, s96, 0x2000
	s_waitcnt lgkmcnt(7)
	global_load_lds_dwordx4 v242, s[92:93]
	s_add_u32 m0, s96, 0x3000
	v_mfma_f32_16x16x32_bf16 v[42:45], v[124:127], v[108:111], v[42:45]
	global_load_lds_dwordx4 v243, s[92:93]
	s_add_u32 m0, s96, 0x4000
	s_waitcnt lgkmcnt(2)
	global_load_lds_dwordx4 v244, s[94:95]
	s_add_u32 m0, s96, 0x5000
	v_mfma_f32_16x16x32_bf16 v[26:29], v[160:163], v[108:111], v[26:29]
	global_load_lds_dwordx4 v245, s[94:95]
	s_add_u32 m0, s96, 0x6000
	v_mfma_f32_16x16x32_bf16 v[96:99], v[140:143], v[108:111], v[96:99]
	global_load_lds_dwordx4 v246, s[94:95]
	s_add_u32 m0, s96, 0x7000
	v_mfma_f32_16x16x32_bf16 v[104:107], v[156:159], v[108:111], v[104:107]
	global_load_lds_dwordx4 v247, s[94:95]
	v_mfma_f32_16x16x32_bf16 v[46:49], v[124:127], v[120:123], v[46:49]
	v_mfma_f32_16x16x32_bf16 v[58:61], v[140:143], v[120:123], v[58:61]
	ds_read_b128 v[92:95], v20 offset:34816
	v_mfma_f32_16x16x32_bf16 v[30:33], v[160:163], v[120:123], v[30:33]
	ds_read_b128 v[176:179], v21 offset:51200
	v_mfma_f32_16x16x32_bf16 v[100:103], v[156:159], v[120:123], v[100:103]
	v_mfma_f32_16x16x32_bf16 v[50:53], v[124:127], v[148:151], v[50:53]
	v_mfma_f32_16x16x32_bf16 v[62:65], v[140:143], v[148:151], v[62:65]
	ds_read_b128 v[116:119], v20 offset:36864
	v_mfma_f32_16x16x32_bf16 v[74:77], v[156:159], v[148:151], v[74:77]
	ds_read_b128 v[180:183], v21 offset:53248
	v_mfma_f32_16x16x32_bf16 v[34:37], v[160:163], v[148:151], v[34:37]
	v_mfma_f32_16x16x32_bf16 v[54:57], v[124:127], v[152:155], v[54:57]
	v_mfma_f32_16x16x32_bf16 v[66:69], v[140:143], v[152:155], v[66:69]
	ds_read_b128 v[144:147], v20 offset:38912
	v_mfma_f32_16x16x32_bf16 v[70:73], v[156:159], v[152:155], v[70:73]
	ds_read_b128 v[184:187], v21 offset:55296
	v_mfma_f32_16x16x32_bf16 v[38:41], v[160:163], v[152:155], v[38:41]
	s_waitcnt lgkmcnt(6)
	v_mfma_f32_16x16x32_bf16 v[42:45], v[172:175], v[164:167], v[42:45]
	s_waitcnt lgkmcnt(0)
	v_mfma_f32_16x16x32_bf16 v[26:29], v[184:187], v[164:167], v[26:29]
	v_mfma_f32_16x16x32_bf16 v[96:99], v[176:179], v[164:167], v[96:99]
	v_mfma_f32_16x16x32_bf16 v[104:107], v[180:183], v[164:167], v[104:107]
	v_mfma_f32_16x16x32_bf16 v[46:49], v[172:175], v[92:95], v[46:49]
	v_mfma_f32_16x16x32_bf16 v[58:61], v[176:179], v[92:95], v[58:61]
	v_mfma_f32_16x16x32_bf16 v[30:33], v[184:187], v[92:95], v[30:33]
	v_mfma_f32_16x16x32_bf16 v[100:103], v[180:183], v[92:95], v[100:103]
	v_mfma_f32_16x16x32_bf16 v[50:53], v[172:175], v[116:119], v[50:53]
	v_mfma_f32_16x16x32_bf16 v[62:65], v[176:179], v[116:119], v[62:65]
	v_mfma_f32_16x16x32_bf16 v[74:77], v[180:183], v[116:119], v[74:77]
	v_mfma_f32_16x16x32_bf16 v[34:37], v[184:187], v[116:119], v[34:37]
	v_mfma_f32_16x16x32_bf16 v[54:57], v[172:175], v[144:147], v[54:57]
	v_mfma_f32_16x16x32_bf16 v[66:69], v[176:179], v[144:147], v[66:69]
	v_mfma_f32_16x16x32_bf16 v[70:73], v[180:183], v[144:147], v[70:73]
	v_mfma_f32_16x16x32_bf16 v[38:41], v[184:187], v[144:147], v[38:41]
	s_setprio 0
	s_waitcnt vmcnt(0) lgkmcnt(0)
	s_barrier
; template <int MODE>
; __device__ __forceinline__ void gemm_tile(const Params& P, int tm, int tn, unsigned char* smem) {
;     ...
; #pragma unroll
;         for (int i = 0; i < 4; ++i) { fa[i] = *(const bf16x8*)(sA + arow_off + i * 2048 + ch0); fb[i] = *(const bf16x8*)(sB + brow_off + i * 2048 + ch0); }
;         __builtin_amdgcn_sched_barrier(0);
;         __builtin_amdgcn_s_setprio(2);
;         if (wr_ok) *(uint4*)(nA + soff0) = ra0;
;         if (ld_ok) ra0 = *(const uint4*)(Ab + (aoff + 0u * LDA + koa));
;         ga[0] = *(const bf16x8*)(sA + arow_off + 0 * 2048 + ch1); gb[0] = *(const bf16x8*)(sB + brow_off + 0 * 2048 + ch1);
;         __builtin_amdgcn_sched_barrier(0);
; #pragma unroll
;         for (int j = 0; j < 4; ++j) acc[0][j] = __builtin_amdgcn_mfma_f32_16x16x32_bf16(fb[j], fa[0], acc[0][j], 0, 0, 0);
;         __builtin_amdgcn_sched_barrier(0);
;         if (wr_ok) *(uint4*)(nA + soff0 + 4096) = ra1;
;         if (ld_ok) ra1 = *(const uint4*)(Ab + (aoff + 32u * LDA + koa));
;         ga[1] = *(const bf16x8*)(sA + arow_off + 1 * 2048 + ch1); gb[1] = *(const bf16x8*)(sB + brow_off + 1 * 2048 + ch1);
;         __builtin_amdgcn_sched_barrier(0);
; #pragma unroll
;         for (int j = 0; j < 4; ++j) acc[1][j] = __builtin_amdgcn_mfma_f32_16x16x32_bf16(fb[j], fa[1], acc[1][j], 0, 0, 0);
;         __builtin_amdgcn_sched_barrier(0);
;         if (wr_ok) *(uint4*)(nA + soff0 + 8192) = ra2;
;         if (ld_ok) ra2 = *(const uint4*)(Ab + (aoff + 64u * LDA + koa));
;         ga[2] = *(const bf16x8*)(sA + arow_off + 2 * 2048 + ch1); gb[2] = *(const bf16x8*)(sB + brow_off + 2 * 2048 + ch1);
;         __builtin_amdgcn_sched_barrier(0);
; #pragma unroll
;         for (int j = 0; j < 4; ++j) acc[2][j] = __builtin_amdgcn_mfma_f32_16x16x32_bf16(fb[j], fa[2], acc[2][j], 0, 0, 0);
;         __builtin_amdgcn_sched_barrier(0);
;         if (wr_ok) *(uint4*)(nA + soff0 + 12288) = ra3;
;         if (ld_ok) ra3 = *(const uint4*)(Ab + (aoff + 96u * LDA + koa));
;         ga[3] = *(const bf16x8*)(sA + arow_off + 3 * 2048 + ch1); gb[3] = *(const bf16x8*)(sB + brow_off + 3 * 2048 + ch1);
;         __builtin_amdgcn_sched_barrier(0);
; #pragma unroll
;         for (int j = 0; j < 4; ++j) acc[3][j] = __builtin_amdgcn_mfma_f32_16x16x32_bf16(fb[j], fa[3], acc[3][j], 0, 0, 0);
;         __builtin_amdgcn_sched_barrier(0);
;         if (wr_ok) *(uint4*)(nB + soff0) = rb0;
	ds_read_b128 v[78:81], v22
	ds_read_b128 v[116:119], v22 offset:2048
	ds_read_b128 v[132:135], v23 offset:16384
	ds_read_b128 v[140:143], v23 offset:18432
	ds_read_b128 v[144:147], v22 offset:4096
	ds_read_b128 v[152:155], v22 offset:6144
	ds_read_b128 v[156:159], v23 offset:20480
	ds_read_b128 v[160:163], v23 offset:22528
	s_setprio 2
	s_add_u32 s92, s92, 0x80
	s_addc_u32 s93, s93, 0
	s_add_u32 s94, s94, 0x80
	s_addc_u32 s95, s95, 0
	s_add_u32 m0, s96, 0x8000
	ds_read_b128 v[168:171], v20
	global_load_lds_dwordx4 v240, s[92:93]
	s_add_u32 m0, s96, 0x9000
	ds_read_b128 v[172:175], v21 offset:16384
	global_load_lds_dwordx4 v241, s[92:93]
	s_add_u32 m0, s96, 0xa000
	s_waitcnt lgkmcnt(7)
	global_load_lds_dwordx4 v242, s[92:93]
	s_add_u32 m0, s96, 0xb000
	v_mfma_f32_16x16x32_bf16 v[42:45], v[132:135], v[78:81], v[42:45]
	global_load_lds_dwordx4 v243, s[92:93]
	s_add_u32 m0, s96, 0xc000
	s_waitcnt lgkmcnt(2)
	global_load_lds_dwordx4 v244, s[94:95]
	s_add_u32 m0, s96, 0xd000
	v_mfma_f32_16x16x32_bf16 v[26:29], v[160:163], v[78:81], v[26:29]
	global_load_lds_dwordx4 v245, s[94:95]
	s_add_u32 m0, s96, 0xe000
	v_mfma_f32_16x16x32_bf16 v[96:99], v[140:143], v[78:81], v[96:99]
	global_load_lds_dwordx4 v246, s[94:95]
	s_add_u32 m0, s96, 0xf000
	v_mfma_f32_16x16x32_bf16 v[104:107], v[156:159], v[78:81], v[104:107]
	global_load_lds_dwordx4 v247, s[94:95]
	v_mfma_f32_16x16x32_bf16 v[46:49], v[132:135], v[116:119], v[46:49]
	v_mfma_f32_16x16x32_bf16 v[58:61], v[140:143], v[116:119], v[58:61]
	ds_read_b128 v[108:111], v20 offset:2048
	v_mfma_f32_16x16x32_bf16 v[30:33], v[160:163], v[116:119], v[30:33]
	ds_read_b128 v[176:179], v21 offset:18432
	v_mfma_f32_16x16x32_bf16 v[100:103], v[156:159], v[116:119], v[100:103]
	v_mfma_f32_16x16x32_bf16 v[50:53], v[132:135], v[144:147], v[50:53]
	v_mfma_f32_16x16x32_bf16 v[62:65], v[140:143], v[144:147], v[62:65]
	ds_read_b128 v[120:123], v20 offset:4096
	v_mfma_f32_16x16x32_bf16 v[74:77], v[156:159], v[144:147], v[74:77]
	ds_read_b128 v[180:183], v21 offset:20480
	v_mfma_f32_16x16x32_bf16 v[34:37], v[160:163], v[144:147], v[34:37]
	v_mfma_f32_16x16x32_bf16 v[54:57], v[132:135], v[152:155], v[54:57]
	v_mfma_f32_16x16x32_bf16 v[66:69], v[140:143], v[152:155], v[66:69]
	ds_read_b128 v[148:151], v20 offset:6144
	v_mfma_f32_16x16x32_bf16 v[70:73], v[156:159], v[152:155], v[70:73]
	ds_read_b128 v[184:187], v21 offset:22528
	v_mfma_f32_16x16x32_bf16 v[38:41], v[160:163], v[152:155], v[38:41]
	s_waitcnt lgkmcnt(6)
	v_mfma_f32_16x16x32_bf16 v[42:45], v[172:175], v[168:171], v[42:45]
	s_waitcnt lgkmcnt(0)
	v_mfma_f32_16x16x32_bf16 v[26:29], v[184:187], v[168:171], v[26:29]
	v_mfma_f32_16x16x32_bf16 v[96:99], v[176:179], v[168:171], v[96:99]
	v_mfma_f32_16x16x32_bf16 v[104:107], v[180:183], v[168:171], v[104:107]
	v_mfma_f32_16x16x32_bf16 v[46:49], v[172:175], v[108:111], v[46:49]
	v_mfma_f32_16x16x32_bf16 v[58:61], v[176:179], v[108:111], v[58:61]
	v_mfma_f32_16x16x32_bf16 v[30:33], v[184:187], v[108:111], v[30:33]
	v_mfma_f32_16x16x32_bf16 v[100:103], v[180:183], v[108:111], v[100:103]
	v_mfma_f32_16x16x32_bf16 v[50:53], v[172:175], v[120:123], v[50:53]
	v_mfma_f32_16x16x32_bf16 v[62:65], v[176:179], v[120:123], v[62:65]
	v_mfma_f32_16x16x32_bf16 v[74:77], v[180:183], v[120:123], v[74:77]
	v_mfma_f32_16x16x32_bf16 v[34:37], v[184:187], v[120:123], v[34:37]
	v_mfma_f32_16x16x32_bf16 v[54:57], v[172:175], v[148:151], v[54:57]
	v_mfma_f32_16x16x32_bf16 v[66:69], v[176:179], v[148:151], v[66:69]
	v_mfma_f32_16x16x32_bf16 v[70:73], v[180:183], v[148:151], v[70:73]
	v_mfma_f32_16x16x32_bf16 v[38:41], v[184:187], v[148:151], v[38:41]
	s_setprio 0
	s_waitcnt vmcnt(0) lgkmcnt(0)
	s_barrier
	ds_read_b128 v[112:115], v22 offset:32768
	ds_read_b128 v[120:123], v22 offset:34816
	ds_read_b128 v[136:139], v23 offset:49152
	ds_read_b128 v[140:143], v23 offset:51200
	ds_read_b128 v[148:151], v22 offset:36864
	ds_read_b128 v[152:155], v22 offset:38912
	ds_read_b128 v[156:159], v23 offset:53248
	ds_read_b128 v[160:163], v23 offset:55296
	s_setprio 2
	s_add_u32 s92, s92, 0x80
	s_addc_u32 s93, s93, 0
	s_add_u32 s94, s94, 0x80
	s_addc_u32 s95, s95, 0
	s_mov_b32 m0, s96
	ds_read_b128 v[164:167], v20 offset:32768
	global_load_lds_dwordx4 v240, s[92:93]
	s_add_u32 m0, s96, 0x1000
	ds_read_b128 v[172:175], v21 offset:49152
	global_load_lds_dwordx4 v241, s[92:93]
	s_add_u32 m0, s96, 0x2000
	s_waitcnt lgkmcnt(7)
	global_load_lds_dwordx4 v242, s[92:93]
	s_add_u32 m0, s96, 0x3000
	v_mfma_f32_16x16x32_bf16 v[42:45], v[136:139], v[112:115], v[42:45]
	global_load_lds_dwordx4 v243, s[92:93]
	s_add_u32 m0, s96, 0x4000
	s_waitcnt lgkmcnt(2)
	global_load_lds_dwordx4 v244, s[94:95]
	s_add_u32 m0, s96, 0x5000
	v_mfma_f32_16x16x32_bf16 v[26:29], v[160:163], v[112:115], v[26:29]
	global_load_lds_dwordx4 v245, s[94:95]
	s_add_u32 m0, s96, 0x6000
	v_mfma_f32_16x16x32_bf16 v[96:99], v[140:143], v[112:115], v[96:99]
	global_load_lds_dwordx4 v246, s[94:95]
	s_add_u32 m0, s96, 0x7000
	v_mfma_f32_16x16x32_bf16 v[104:107], v[156:159], v[112:115], v[104:107]
	global_load_lds_dwordx4 v247, s[94:95]
	v_mfma_f32_16x16x32_bf16 v[46:49], v[136:139], v[120:123], v[46:49]
	v_mfma_f32_16x16x32_bf16 v[58:61], v[140:143], v[120:123], v[58:61]
	ds_read_b128 v[78:81], v20 offset:34816
	v_mfma_f32_16x16x32_bf16 v[30:33], v[160:163], v[120:123], v[30:33]
	ds_read_b128 v[176:179], v21 offset:51200
	v_mfma_f32_16x16x32_bf16 v[100:103], v[156:159], v[120:123], v[100:103]
	v_mfma_f32_16x16x32_bf16 v[50:53], v[136:139], v[148:151], v[50:53]
	v_mfma_f32_16x16x32_bf16 v[62:65], v[140:143], v[148:151], v[62:65]
	ds_read_b128 v[116:119], v20 offset:36864
	v_mfma_f32_16x16x32_bf16 v[74:77], v[156:159], v[148:151], v[74:77]
	ds_read_b128 v[180:183], v21 offset:53248
	v_mfma_f32_16x16x32_bf16 v[34:37], v[160:163], v[148:151], v[34:37]
	v_mfma_f32_16x16x32_bf16 v[54:57], v[136:139], v[152:155], v[54:57]
	v_mfma_f32_16x16x32_bf16 v[66:69], v[140:143], v[152:155], v[66:69]
	ds_read_b128 v[144:147], v20 offset:38912
	v_mfma_f32_16x16x32_bf16 v[70:73], v[156:159], v[152:155], v[70:73]
	ds_read_b128 v[184:187], v21 offset:55296
	v_mfma_f32_16x16x32_bf16 v[38:41], v[160:163], v[152:155], v[38:41]
	s_waitcnt lgkmcnt(6)
; template <int MODE>
; __device__ __forceinline__ void gemm_tile(const Params& P, int tm, int tn, unsigned char* smem) {
;     ...
; #pragma unroll
;         for (int i = 0; i < 4; ++i) { fa[i] = *(const bf16x8*)(sA + arow_off + i * 2048 + ch0); fb[i] = *(const bf16x8*)(sB + brow_off + i * 2048 + ch0); }
;         __builtin_amdgcn_sched_barrier(0);
;         __builtin_amdgcn_s_setprio(2);
;         if (wr_ok) *(uint4*)(nA + soff0) = ra0;
;         if (ld_ok) ra0 = *(const uint4*)(Ab + (aoff + 0u * LDA + koa));
;         ga[0] = *(const bf16x8*)(sA + arow_off + 0 * 2048 + ch1); gb[0] = *(const bf16x8*)(sB + brow_off + 0 * 2048 + ch1);
;         __builtin_amdgcn_sched_barrier(0);
; #pragma unroll
;         for (int j = 0; j < 4; ++j) acc[0][j] = __builtin_amdgcn_mfma_f32_16x16x32_bf16(fb[j], fa[0], acc[0][j], 0, 0, 0);
;         __builtin_amdgcn_sched_barrier(0);
;         if (wr_ok) *(uint4*)(nA + soff0 + 4096) = ra1;
;         if (ld_ok) ra1 = *(const uint4*)(Ab + (aoff + 32u * LDA + koa));
;         ga[1] = *(const bf16x8*)(sA + arow_off + 1 * 2048 + ch1); gb[1] = *(const bf16x8*)(sB + brow_off + 1 * 2048 + ch1);
;         __builtin_amdgcn_sched_barrier(0);
; #pragma unroll
;         for (int j = 0; j < 4; ++j) acc[1][j] = __builtin_amdgcn_mfma_f32_16x16x32_bf16(fb[j], fa[1], acc[1][j], 0, 0, 0);
;         __builtin_amdgcn_sched_barrier(0);
;         if (wr_ok) *(uint4*)(nA + soff0 + 8192) = ra2;
;         if (ld_ok) ra2 = *(const uint4*)(Ab + (aoff + 64u * LDA + koa));
;         ga[2] = *(const bf16x8*)(sA + arow_off + 2 * 2048 + ch1); gb[2] = *(const bf16x8*)(sB + brow_off + 2 * 2048 + ch1);
;         __builtin_amdgcn_sched_barrier(0);
; #pragma unroll
;         for (int j = 0; j < 4; ++j) acc[2][j] = __builtin_amdgcn_mfma_f32_16x16x32_bf16(fb[j], fa[2], acc[2][j], 0, 0, 0);
;         __builtin_amdgcn_sched_barrier(0);
;         if (wr_ok) *(uint4*)(nA + soff0 + 12288) = ra3;
;         if (ld_ok) ra3 = *(const uint4*)(Ab + (aoff + 96u * LDA + koa));
;         ga[3] = *(const bf16x8*)(sA + arow_off + 3 * 2048 + ch1); gb[3] = *(const bf16x8*)(sB + brow_off + 3 * 2048 + ch1);
;         __builtin_amdgcn_sched_barrier(0);
; #pragma unroll
;         for (int j = 0; j < 4; ++j) acc[3][j] = __builtin_amdgcn_mfma_f32_16x16x32_bf16(fb[j], fa[3], acc[3][j], 0, 0, 0);
;         __builtin_amdgcn_sched_barrier(0);
;         if (wr_ok) *(uint4*)(nB + soff0) = rb0;
	v_mfma_f32_16x16x32_bf16 v[42:45], v[172:175], v[164:167], v[42:45]
	s_waitcnt lgkmcnt(0)
	v_mfma_f32_16x16x32_bf16 v[26:29], v[184:187], v[164:167], v[26:29]
	v_mfma_f32_16x16x32_bf16 v[96:99], v[176:179], v[164:167], v[96:99]
	v_mfma_f32_16x16x32_bf16 v[104:107], v[180:183], v[164:167], v[104:107]
	v_mfma_f32_16x16x32_bf16 v[46:49], v[172:175], v[78:81], v[46:49]
	v_mfma_f32_16x16x32_bf16 v[58:61], v[176:179], v[78:81], v[58:61]
	v_mfma_f32_16x16x32_bf16 v[30:33], v[184:187], v[78:81], v[30:33]
	v_mfma_f32_16x16x32_bf16 v[100:103], v[180:183], v[78:81], v[100:103]
	v_mfma_f32_16x16x32_bf16 v[50:53], v[172:175], v[116:119], v[50:53]
	v_mfma_f32_16x16x32_bf16 v[62:65], v[176:179], v[116:119], v[62:65]
	v_mfma_f32_16x16x32_bf16 v[74:77], v[180:183], v[116:119], v[74:77]
	v_mfma_f32_16x16x32_bf16 v[34:37], v[184:187], v[116:119], v[34:37]
	v_mfma_f32_16x16x32_bf16 v[54:57], v[172:175], v[144:147], v[54:57]
	v_mfma_f32_16x16x32_bf16 v[66:69], v[176:179], v[144:147], v[66:69]
	v_mfma_f32_16x16x32_bf16 v[70:73], v[180:183], v[144:147], v[70:73]
	v_mfma_f32_16x16x32_bf16 v[38:41], v[184:187], v[144:147], v[38:41]
	s_setprio 0
	s_waitcnt vmcnt(0) lgkmcnt(0)
	s_barrier
	ds_read_b128 v[92:95], v22
	ds_read_b128 v[116:119], v22 offset:2048
	ds_read_b128 v[124:127], v23 offset:16384
	ds_read_b128 v[140:143], v23 offset:18432
	ds_read_b128 v[144:147], v22 offset:4096
	ds_read_b128 v[152:155], v22 offset:6144
	ds_read_b128 v[156:159], v23 offset:20480
	ds_read_b128 v[160:163], v23 offset:22528
	s_setprio 2
	s_add_u32 s92, s92, 0x80
	s_addc_u32 s93, s93, 0
	s_add_u32 s94, s94, 0x80
	s_addc_u32 s95, s95, 0
	s_add_u32 m0, s96, 0x8000
	ds_read_b128 v[168:171], v20
	global_load_lds_dwordx4 v240, s[92:93]
	s_add_u32 m0, s96, 0x9000
	ds_read_b128 v[172:175], v21 offset:16384
	global_load_lds_dwordx4 v241, s[92:93]
	s_add_u32 m0, s96, 0xa000
	s_waitcnt lgkmcnt(7)
	global_load_lds_dwordx4 v242, s[92:93]
	s_add_u32 m0, s96, 0xb000
	v_mfma_f32_16x16x32_bf16 v[42:45], v[124:127], v[92:95], v[42:45]
	global_load_lds_dwordx4 v243, s[92:93]
	s_add_u32 m0, s96, 0xc000
	s_waitcnt lgkmcnt(2)
	global_load_lds_dwordx4 v244, s[94:95]
	s_add_u32 m0, s96, 0xd000
	v_mfma_f32_16x16x32_bf16 v[26:29], v[160:163], v[92:95], v[26:29]
	global_load_lds_dwordx4 v245, s[94:95]
	s_add_u32 m0, s96, 0xe000
	v_mfma_f32_16x16x32_bf16 v[96:99], v[140:143], v[92:95], v[96:99]
	global_load_lds_dwordx4 v246, s[94:95]
	s_add_u32 m0, s96, 0xf000
	v_mfma_f32_16x16x32_bf16 v[104:107], v[156:159], v[92:95], v[104:107]
	global_load_lds_dwordx4 v247, s[94:95]
	v_mfma_f32_16x16x32_bf16 v[46:49], v[124:127], v[116:119], v[46:49]
	v_mfma_f32_16x16x32_bf16 v[58:61], v[140:143], v[116:119], v[58:61]
	ds_read_b128 v[112:115], v20 offset:2048
	v_mfma_f32_16x16x32_bf16 v[30:33], v[160:163], v[116:119], v[30:33]
	ds_read_b128 v[176:179], v21 offset:18432
	v_mfma_f32_16x16x32_bf16 v[100:103], v[156:159], v[116:119], v[100:103]
	v_mfma_f32_16x16x32_bf16 v[50:53], v[124:127], v[144:147], v[50:53]
	v_mfma_f32_16x16x32_bf16 v[62:65], v[140:143], v[144:147], v[62:65]
	ds_read_b128 v[120:123], v20 offset:4096
	v_mfma_f32_16x16x32_bf16 v[74:77], v[156:159], v[144:147], v[74:77]
	ds_read_b128 v[180:183], v21 offset:20480
	v_mfma_f32_16x16x32_bf16 v[34:37], v[160:163], v[144:147], v[34:37]
	v_mfma_f32_16x16x32_bf16 v[54:57], v[124:127], v[152:155], v[54:57]
	v_mfma_f32_16x16x32_bf16 v[66:69], v[140:143], v[152:155], v[66:69]
	ds_read_b128 v[148:151], v20 offset:6144
	v_mfma_f32_16x16x32_bf16 v[70:73], v[156:159], v[152:155], v[70:73]
	ds_read_b128 v[184:187], v21 offset:22528
	v_mfma_f32_16x16x32_bf16 v[38:41], v[160:163], v[152:155], v[38:41]
	s_waitcnt lgkmcnt(6)
	v_mfma_f32_16x16x32_bf16 v[42:45], v[172:175], v[168:171], v[42:45]
	s_waitcnt lgkmcnt(0)
	v_mfma_f32_16x16x32_bf16 v[26:29], v[184:187], v[168:171], v[26:29]
	v_mfma_f32_16x16x32_bf16 v[96:99], v[176:179], v[168:171], v[96:99]
	v_mfma_f32_16x16x32_bf16 v[104:107], v[180:183], v[168:171], v[104:107]
	v_mfma_f32_16x16x32_bf16 v[46:49], v[172:175], v[112:115], v[46:49]
	v_mfma_f32_16x16x32_bf16 v[58:61], v[176:179], v[112:115], v[58:61]
	v_mfma_f32_16x16x32_bf16 v[30:33], v[184:187], v[112:115], v[30:33]
	v_mfma_f32_16x16x32_bf16 v[100:103], v[180:183], v[112:115], v[100:103]
	v_mfma_f32_16x16x32_bf16 v[50:53], v[172:175], v[120:123], v[50:53]
	v_mfma_f32_16x16x32_bf16 v[62:65], v[176:179], v[120:123], v[62:65]
	v_mfma_f32_16x16x32_bf16 v[74:77], v[180:183], v[120:123], v[74:77]
	v_mfma_f32_16x16x32_bf16 v[34:37], v[184:187], v[120:123], v[34:37]
	v_mfma_f32_16x16x32_bf16 v[54:57], v[172:175], v[148:151], v[54:57]
	v_mfma_f32_16x16x32_bf16 v[66:69], v[176:179], v[148:151], v[66:69]
	v_mfma_f32_16x16x32_bf16 v[70:73], v[180:183], v[148:151], v[70:73]
	v_mfma_f32_16x16x32_bf16 v[38:41], v[184:187], v[148:151], v[38:41]
	s_setprio 0
	s_waitcnt vmcnt(0) lgkmcnt(0)
	s_barrier
; template <int MODE>
; __device__ __forceinline__ void gemm_tile(const Params& P, int tm, int tn, unsigned char* smem) {
;     ...
;     for (int kt = 0; kt < 16; ++kt) {
;         unsigned char* sA = (kt & 1) ? sA1 : sA0; unsigned char* sB = (kt & 1) ? sB1 : sB0;
;         unsigned char* nA = (kt & 1) ? sA0 : sA1; unsigned char* nB = (kt & 1) ? sB0 : sB1;
;         bf16x8 fa[4], fb[4], ga[4], gb[4];
;         const int ch0 = ((g ^ sw) << 4), ch1 = (((4 + g) ^ sw) << 4);
;         const unsigned ko = (unsigned)(kt + 2) * 128u;
;         const unsigned koa = ko + ((MODE == 2 && kt + 2 >= 8) ? (unsigned)(ZC_FQ - 512) * 2u : 0u);
;         const bool wr_ok = kt < 15, ld_ok = kt < 14;
; #pragma unroll
;         for (int i = 0; i < 4; ++i) { fa[i] = *(const bf16x8*)(sA + arow_off + i * 2048 + ch0); fb[i] = *(const bf16x8*)(sB + brow_off + i * 2048 + ch0); }
;         __builtin_amdgcn_sched_barrier(0);
;         __builtin_amdgcn_s_setprio(2);
;         if (wr_ok) *(uint4*)(nA + soff0) = ra0;
;         if (ld_ok) ra0 = *(const uint4*)(Ab + (aoff + 0u * LDA + koa));
;         ga[0] = *(const bf16x8*)(sA + arow_off + 0 * 2048 + ch1); gb[0] = *(const bf16x8*)(sB + brow_off + 0 * 2048 + ch1);
;         __builtin_amdgcn_sched_barrier(0);
; #pragma unroll
;         for (int j = 0; j < 4; ++j) acc[0][j] = __builtin_amdgcn_mfma_f32_16x16x32_bf16(fb[j], fa[0], acc[0][j], 0, 0, 0);
;         __builtin_amdgcn_sched_barrier(0);
;         if (wr_ok) *(uint4*)(nA + soff0 + 4096) = ra1;
;         if (ld_ok) ra1 = *(const uint4*)(Ab + (aoff + 32u * LDA + koa));
;         ga[1] = *(const bf16x8*)(sA + arow_off + 1 * 2048 + ch1); gb[1] = *(const bf16x8*)(sB + brow_off + 1 * 2048 + ch1);
;         __builtin_amdgcn_sched_barrier(0);
; #pragma unroll
;         for (int j = 0; j < 4; ++j) acc[1][j] = __builtin_amdgcn_mfma_f32_16x16x32_bf16(fb[j], fa[1], acc[1][j], 0, 0, 0);
;         __builtin_amdgcn_sched_barrier(0);
;         if (wr_ok) *(uint4*)(nA + soff0 + 8192) = ra2;
;         if (ld_ok) ra2 = *(const uint4*)(Ab + (aoff + 64u * LDA + koa));
;         ga[2] = *(const bf16x8*)(sA + arow_off + 2 * 2048 + ch1); gb[2] = *(const bf16x8*)(sB + brow_off + 2 * 2048 + ch1);
;         __builtin_amdgcn_sched_barrier(0);
; #pragma unroll
;         for (int j = 0; j < 4; ++j) acc[2][j] = __builtin_amdgcn_mfma_f32_16x16x32_bf16(fb[j], fa[2], acc[2][j], 0, 0, 0);
	ds_read_b128 v[108:111], v22 offset:32768
	ds_read_b128 v[120:123], v22 offset:34816
	ds_read_b128 v[132:135], v23 offset:49152
	ds_read_b128 v[140:143], v23 offset:51200
	ds_read_b128 v[148:151], v22 offset:36864
	ds_read_b128 v[152:155], v22 offset:38912
	ds_read_b128 v[156:159], v23 offset:53248
	ds_read_b128 v[160:163], v23 offset:55296
	s_setprio 2
	s_add_u32 s92, s92, 0x80
	s_addc_u32 s93, s93, 0
	s_add_u32 s94, s94, 0x80
	s_addc_u32 s95, s95, 0
	s_mov_b32 m0, s96
	ds_read_b128 v[164:167], v20 offset:32768
	global_load_lds_dwordx4 v240, s[92:93]
	s_add_u32 m0, s96, 0x1000
	ds_read_b128 v[172:175], v21 offset:49152
	global_load_lds_dwordx4 v241, s[92:93]
	s_add_u32 m0, s96, 0x2000
	s_waitcnt lgkmcnt(7)
	global_load_lds_dwordx4 v242, s[92:93]
	s_add_u32 m0, s96, 0x3000
	v_mfma_f32_16x16x32_bf16 v[42:45], v[132:135], v[108:111], v[42:45]
	global_load_lds_dwordx4 v243, s[92:93]
	s_add_u32 m0, s96, 0x4000
	s_waitcnt lgkmcnt(2)
	global_load_lds_dwordx4 v244, s[94:95]
	s_add_u32 m0, s96, 0x5000
	v_mfma_f32_16x16x32_bf16 v[26:29], v[160:163], v[108:111], v[26:29]
	global_load_lds_dwordx4 v245, s[94:95]
	s_add_u32 m0, s96, 0x6000
	v_mfma_f32_16x16x32_bf16 v[96:99], v[140:143], v[108:111], v[96:99]
	global_load_lds_dwordx4 v246, s[94:95]
	s_add_u32 m0, s96, 0x7000
	v_mfma_f32_16x16x32_bf16 v[104:107], v[156:159], v[108:111], v[104:107]
	global_load_lds_dwordx4 v247, s[94:95]
	v_mfma_f32_16x16x32_bf16 v[46:49], v[132:135], v[120:123], v[46:49]
	v_mfma_f32_16x16x32_bf16 v[58:61], v[140:143], v[120:123], v[58:61]
	ds_read_b128 v[92:95], v20 offset:34816
	v_mfma_f32_16x16x32_bf16 v[30:33], v[160:163], v[120:123], v[30:33]
	ds_read_b128 v[176:179], v21 offset:51200
	v_mfma_f32_16x16x32_bf16 v[100:103], v[156:159], v[120:123], v[100:103]
	v_mfma_f32_16x16x32_bf16 v[50:53], v[132:135], v[148:151], v[50:53]
	v_mfma_f32_16x16x32_bf16 v[62:65], v[140:143], v[148:151], v[62:65]
	ds_read_b128 v[116:119], v20 offset:36864
	v_mfma_f32_16x16x32_bf16 v[74:77], v[156:159], v[148:151], v[74:77]
	ds_read_b128 v[180:183], v21 offset:53248
	v_mfma_f32_16x16x32_bf16 v[34:37], v[160:163], v[148:151], v[34:37]
	v_add_u32_e32 v24, 0x30780, v24
	ds_read_b128 v[144:147], v20 offset:38912
	ds_read_b128 v[184:187], v21 offset:55296
	v_mfma_f32_16x16x32_bf16 v[54:57], v[132:135], v[152:155], v[54:57]
	v_mfma_f32_16x16x32_bf16 v[66:69], v[140:143], v[152:155], v[66:69]
	v_mfma_f32_16x16x32_bf16 v[70:73], v[156:159], v[152:155], v[70:73]
	v_mfma_f32_16x16x32_bf16 v[38:41], v[160:163], v[152:155], v[38:41]
	s_waitcnt lgkmcnt(6)
	v_mfma_f32_16x16x32_bf16 v[42:45], v[172:175], v[164:167], v[42:45]
	s_waitcnt lgkmcnt(0)
	v_mfma_f32_16x16x32_bf16 v[24:27], v[184:187], v[164:167], v[26:29]
	v_mfma_f32_16x16x32_bf16 v[96:99], v[176:179], v[164:167], v[96:99]
	v_mfma_f32_16x16x32_bf16 v[104:107], v[180:183], v[164:167], v[104:107]
	s_nop 0
	v_mfma_f32_16x16x32_bf16 v[46:49], v[172:175], v[92:95], v[46:49]
	v_mfma_f32_16x16x32_bf16 v[58:61], v[176:179], v[92:95], v[58:61]
	v_mfma_f32_16x16x32_bf16 v[28:31], v[184:187], v[92:95], v[30:33]
	v_mfma_f32_16x16x32_bf16 v[100:103], v[180:183], v[92:95], v[100:103]
	s_nop 1
	v_mfma_f32_16x16x32_bf16 v[50:53], v[172:175], v[116:119], v[50:53]
	v_mfma_f32_16x16x32_bf16 v[62:65], v[176:179], v[116:119], v[62:65]
	v_mfma_f32_16x16x32_bf16 v[74:77], v[180:183], v[116:119], v[74:77]
	v_mfma_f32_16x16x32_bf16 v[32:35], v[184:187], v[116:119], v[34:37]
	v_add_u32_e32 v18, 0x30780, v18
	v_mfma_f32_16x16x32_bf16 v[54:57], v[172:175], v[144:147], v[54:57]
	v_mfma_f32_16x16x32_bf16 v[66:69], v[176:179], v[144:147], v[66:69]
	v_mfma_f32_16x16x32_bf16 v[70:73], v[180:183], v[144:147], v[70:73]
	v_mfma_f32_16x16x32_bf16 v[36:39], v[184:187], v[144:147], v[38:41]
	s_setprio 0
	s_waitcnt vmcnt(0) lgkmcnt(0)
	s_barrier
	ds_read_b128 v[78:81], v22
	ds_read_b128 v[116:119], v22 offset:2048
	ds_read_b128 v[136:139], v23 offset:16384
	ds_read_b128 v[140:143], v23 offset:18432
	ds_read_b128 v[144:147], v22 offset:4096
	ds_read_b128 v[152:155], v22 offset:6144
	ds_read_b128 v[156:159], v23 offset:20480
	ds_read_b128 v[160:163], v23 offset:22528
	s_setprio 2
	s_add_u32 s92, s92, 0x80
	s_addc_u32 s93, s93, 0
	s_add_u32 s94, s94, 0x80
	s_addc_u32 s95, s95, 0
	s_add_u32 m0, s96, 0x8000
	ds_read_b128 v[164:167], v20
	global_load_lds_dwordx4 v240, s[92:93]
	s_add_u32 m0, s96, 0x9000
	ds_read_b128 v[168:171], v21 offset:16384
	global_load_lds_dwordx4 v241, s[92:93]
	s_add_u32 m0, s96, 0xa000
	s_waitcnt lgkmcnt(7)
	global_load_lds_dwordx4 v242, s[92:93]
	s_add_u32 m0, s96, 0xb000
	v_mfma_f32_16x16x32_bf16 v[40:43], v[136:139], v[78:81], v[42:45]
	global_load_lds_dwordx4 v243, s[92:93]
	s_add_u32 m0, s96, 0xc000
	s_waitcnt lgkmcnt(2)
	global_load_lds_dwordx4 v244, s[94:95]
	s_add_u32 m0, s96, 0xd000
	v_mfma_f32_16x16x32_bf16 v[24:27], v[160:163], v[78:81], v[24:27]
	global_load_lds_dwordx4 v245, s[94:95]
	s_add_u32 m0, s96, 0xe000
	v_mfma_f32_16x16x32_bf16 v[96:99], v[140:143], v[78:81], v[96:99]
	global_load_lds_dwordx4 v246, s[94:95]
	s_add_u32 m0, s96, 0xf000
	v_mfma_f32_16x16x32_bf16 v[104:107], v[156:159], v[78:81], v[104:107]
	global_load_lds_dwordx4 v247, s[94:95]
	v_mfma_f32_16x16x32_bf16 v[44:47], v[136:139], v[116:119], v[46:49]
	v_mfma_f32_16x16x32_bf16 v[58:61], v[140:143], v[116:119], v[58:61]
	ds_read_b128 v[78:81], v20 offset:2048
	v_mfma_f32_16x16x32_bf16 v[28:31], v[160:163], v[116:119], v[28:31]
	ds_read_b128 v[108:111], v21 offset:18432
	v_mfma_f32_16x16x32_bf16 v[100:103], v[156:159], v[116:119], v[100:103]
	v_mfma_f32_16x16x32_bf16 v[48:51], v[136:139], v[144:147], v[50:53]
	v_mfma_f32_16x16x32_bf16 v[62:65], v[140:143], v[144:147], v[62:65]
	ds_read_b128 v[116:119], v20 offset:4096
	v_mfma_f32_16x16x32_bf16 v[74:77], v[156:159], v[144:147], v[74:77]
	ds_read_b128 v[120:123], v21 offset:20480
	v_mfma_f32_16x16x32_bf16 v[32:35], v[160:163], v[144:147], v[32:35]
	v_mfma_f32_16x16x32_bf16 v[52:55], v[136:139], v[152:155], v[54:57]
	v_mfma_f32_16x16x32_bf16 v[66:69], v[140:143], v[152:155], v[66:69]
	ds_read_b128 v[144:147], v20 offset:6144
	v_mfma_f32_16x16x32_bf16 v[70:73], v[156:159], v[152:155], v[70:73]
	ds_read_b128 v[148:151], v21 offset:22528
	v_mfma_f32_16x16x32_bf16 v[36:39], v[160:163], v[152:155], v[36:39]
	s_waitcnt lgkmcnt(6)
; template <int MODE>
; __device__ __forceinline__ void gemm_tile(const Params& P, int tm, int tn, unsigned char* smem) {
;     ...
;     for (int kt = 0; kt < 16; ++kt) {
;         unsigned char* sA = (kt & 1) ? sA1 : sA0; unsigned char* sB = (kt & 1) ? sB1 : sB0;
;         unsigned char* nA = (kt & 1) ? sA0 : sA1; unsigned char* nB = (kt & 1) ? sB0 : sB1;
;         bf16x8 fa[4], fb[4], ga[4], gb[4];
;         const int ch0 = ((g ^ sw) << 4), ch1 = (((4 + g) ^ sw) << 4);
;         const unsigned ko = (unsigned)(kt + 2) * 128u;
;         const unsigned koa = ko + ((MODE == 2 && kt + 2 >= 8) ? (unsigned)(ZC_FQ - 512) * 2u : 0u);
;         const bool wr_ok = kt < 15, ld_ok = kt < 14;
; #pragma unroll
;         for (int i = 0; i < 4; ++i) { fa[i] = *(const bf16x8*)(sA + arow_off + i * 2048 + ch0); fb[i] = *(const bf16x8*)(sB + brow_off + i * 2048 + ch0); }
;         __builtin_amdgcn_sched_barrier(0);
;         __builtin_amdgcn_s_setprio(2);
;         if (wr_ok) *(uint4*)(nA + soff0) = ra0;
;         if (ld_ok) ra0 = *(const uint4*)(Ab + (aoff + 0u * LDA + koa));
;         ga[0] = *(const bf16x8*)(sA + arow_off + 0 * 2048 + ch1); gb[0] = *(const bf16x8*)(sB + brow_off + 0 * 2048 + ch1);
;         __builtin_amdgcn_sched_barrier(0);
; #pragma unroll
;         for (int j = 0; j < 4; ++j) acc[0][j] = __builtin_amdgcn_mfma_f32_16x16x32_bf16(fb[j], fa[0], acc[0][j], 0, 0, 0);
;         __builtin_amdgcn_sched_barrier(0);
;         if (wr_ok) *(uint4*)(nA + soff0 + 4096) = ra1;
;         if (ld_ok) ra1 = *(const uint4*)(Ab + (aoff + 32u * LDA + koa));
;         ga[1] = *(const bf16x8*)(sA + arow_off + 1 * 2048 + ch1); gb[1] = *(const bf16x8*)(sB + brow_off + 1 * 2048 + ch1);
;         __builtin_amdgcn_sched_barrier(0);
; #pragma unroll
;         for (int j = 0; j < 4; ++j) acc[1][j] = __builtin_amdgcn_mfma_f32_16x16x32_bf16(fb[j], fa[1], acc[1][j], 0, 0, 0);
;         __builtin_amdgcn_sched_barrier(0);
;         if (wr_ok) *(uint4*)(nA + soff0 + 8192) = ra2;
;         if (ld_ok) ra2 = *(const uint4*)(Ab + (aoff + 64u * LDA + koa));
;         ga[2] = *(const bf16x8*)(sA + arow_off + 2 * 2048 + ch1); gb[2] = *(const bf16x8*)(sB + brow_off + 2 * 2048 + ch1);
;         __builtin_amdgcn_sched_barrier(0);
; #pragma unroll
;         for (int j = 0; j < 4; ++j) acc[2][j] = __builtin_amdgcn_mfma_f32_16x16x32_bf16(fb[j], fa[2], acc[2][j], 0, 0, 0);
	v_mfma_f32_16x16x32_bf16 v[40:43], v[168:171], v[164:167], v[40:43]
	s_waitcnt lgkmcnt(0)
	v_mfma_f32_16x16x32_bf16 v[24:27], v[148:151], v[164:167], v[24:27]
	v_mfma_f32_16x16x32_bf16 v[96:99], v[108:111], v[164:167], v[96:99]
	v_mfma_f32_16x16x32_bf16 v[104:107], v[120:123], v[164:167], v[104:107]
	v_mfma_f32_16x16x32_bf16 v[44:47], v[168:171], v[78:81], v[44:47]
	v_mfma_f32_16x16x32_bf16 v[56:59], v[108:111], v[78:81], v[58:61]
	v_mfma_f32_16x16x32_bf16 v[28:31], v[148:151], v[78:81], v[28:31]
	v_mfma_f32_16x16x32_bf16 v[100:103], v[120:123], v[78:81], v[100:103]
	v_mfma_f32_16x16x32_bf16 v[48:51], v[168:171], v[116:119], v[48:51]
	v_mfma_f32_16x16x32_bf16 v[60:63], v[108:111], v[116:119], v[62:65]
	v_mfma_f32_16x16x32_bf16 v[74:77], v[120:123], v[116:119], v[74:77]
	v_mfma_f32_16x16x32_bf16 v[32:35], v[148:151], v[116:119], v[32:35]
	v_mfma_f32_16x16x32_bf16 v[52:55], v[168:171], v[144:147], v[52:55]
	v_mfma_f32_16x16x32_bf16 v[64:67], v[108:111], v[144:147], v[66:69]
	v_mfma_f32_16x16x32_bf16 v[68:71], v[120:123], v[144:147], v[70:73]
	v_mfma_f32_16x16x32_bf16 v[36:39], v[148:151], v[144:147], v[36:39]
	s_setprio 0
	s_waitcnt vmcnt(0) lgkmcnt(0)
	s_barrier
	ds_read_b128 v[78:81], v22 offset:32768
	ds_read_b128 v[92:95], v22 offset:34816
	ds_read_b128 v[108:111], v23 offset:49152
	ds_read_b128 v[112:115], v23 offset:51200
	ds_read_b128 v[116:119], v22 offset:36864
	ds_read_b128 v[120:123], v22 offset:38912
	ds_read_b128 v[124:127], v23 offset:53248
	ds_read_b128 v[132:135], v23 offset:55296
	s_setprio 2
	ds_read_b128 v[136:139], v20 offset:32768
	ds_read_b128 v[140:143], v21 offset:49152
	s_waitcnt lgkmcnt(7)
	v_mfma_f32_16x16x32_bf16 v[40:43], v[108:111], v[78:81], v[40:43]
	s_waitcnt lgkmcnt(2)
	v_mfma_f32_16x16x32_bf16 v[22:25], v[132:135], v[78:81], v[24:27]
	v_mfma_f32_16x16x32_bf16 v[96:99], v[112:115], v[78:81], v[96:99]
	v_mfma_f32_16x16x32_bf16 v[104:107], v[124:127], v[78:81], v[104:107]
	v_mfma_f32_16x16x32_bf16 v[44:47], v[108:111], v[92:95], v[44:47]
	ds_read_b128 v[144:147], v20 offset:34816
	v_mfma_f32_16x16x32_bf16 v[56:59], v[112:115], v[92:95], v[56:59]
	ds_read_b128 v[148:151], v21 offset:51200
	v_mfma_f32_16x16x32_bf16 v[26:29], v[132:135], v[92:95], v[28:31]
	v_mfma_f32_16x16x32_bf16 v[100:103], v[124:127], v[92:95], v[100:103]
	v_mfma_f32_16x16x32_bf16 v[30:33], v[132:135], v[116:119], v[32:35]
	ds_read_b128 v[92:95], v20 offset:36864
	v_mfma_f32_16x16x32_bf16 v[156:159], v[108:111], v[116:119], v[48:51]
	ds_read_b128 v[152:155], v21 offset:53248
	v_mfma_f32_16x16x32_bf16 v[160:163], v[112:115], v[116:119], v[60:63]
	v_mfma_f32_16x16x32_bf16 v[164:167], v[124:127], v[116:119], v[74:77]
	v_mfma_f32_16x16x32_bf16 v[108:111], v[108:111], v[120:123], v[52:55]
	ds_read_b128 v[116:119], v20 offset:38912
	v_mfma_f32_16x16x32_bf16 v[112:115], v[112:115], v[120:123], v[64:67]
	ds_read_b128 v[18:21], v21 offset:55296
	v_mfma_f32_16x16x32_bf16 v[124:127], v[124:127], v[120:123], v[68:71]
	v_mfma_f32_16x16x32_bf16 v[120:123], v[132:135], v[120:123], v[36:39]
	s_waitcnt lgkmcnt(6)
	v_mfma_f32_16x16x32_bf16 v[78:81], v[140:143], v[136:139], v[40:43]
	s_waitcnt lgkmcnt(4)
	v_mfma_f32_16x16x32_bf16 v[74:77], v[148:151], v[136:139], v[96:99]
	s_waitcnt lgkmcnt(2)
	v_mfma_f32_16x16x32_bf16 v[70:73], v[152:155], v[136:139], v[104:107]
	s_waitcnt lgkmcnt(0)
	v_mfma_f32_16x16x32_bf16 v[66:69], v[18:21], v[136:139], v[22:25]
	v_mfma_f32_16x16x32_bf16 v[62:65], v[140:143], v[144:147], v[44:47]
	v_mfma_f32_16x16x32_bf16 v[58:61], v[148:151], v[144:147], v[56:59]
	v_mfma_f32_16x16x32_bf16 v[54:57], v[152:155], v[144:147], v[100:103]
	v_mfma_f32_16x16x32_bf16 v[50:53], v[18:21], v[144:147], v[26:29]
	v_mfma_f32_16x16x32_bf16 v[46:49], v[140:143], v[92:95], v[156:159]
	v_mfma_f32_16x16x32_bf16 v[42:45], v[148:151], v[92:95], v[160:163]
	v_mfma_f32_16x16x32_bf16 v[38:41], v[152:155], v[92:95], v[164:167]
	v_mfma_f32_16x16x32_bf16 v[34:37], v[18:21], v[92:95], v[30:33]
	v_mfma_f32_16x16x32_bf16 v[30:33], v[140:143], v[116:119], v[108:111]
	v_mfma_f32_16x16x32_bf16 v[26:29], v[148:151], v[116:119], v[112:115]
	v_mfma_f32_16x16x32_bf16 v[22:25], v[152:155], v[116:119], v[124:127]
	v_mfma_f32_16x16x32_bf16 v[18:21], v[18:21], v[116:119], v[120:123]
	s_setprio 0
	v_add_f32_e32 v10, v10, v11
	v_add_f32_e32 v11, v12, v13
	v_add_f32_e32 v10, v10, v11
	v_mov_b32_e32 v11, v10
	s_nop 1
	v_permlane32_swap_b32_e32 v10, v11
	v_add_f32_e32 v10, v10, v11
	v_mov_b32_e32 v11, v10
	s_nop 1
	v_permlane16_swap_b32_e32 v10, v11
	v_add_f32_e32 v10, v10, v11
	v_fmamk_f32 v10, v10, 0x3a800000, v86
	v_mul_f32_e32 v11, 0x4b800000, v10
	v_cmp_gt_f32_e64 s[0:1], s19, v10
	v_lshl_add_u64 v[84:85], v[84:85], 2, s[8:9]
	s_nop 0
	v_cndmask_b32_e64 v10, v10, v11, s[0:1]
	v_rsq_f32_e32 v10, v10
	v_or3_b32 v11, v91, s2, v89
	v_cmp_eq_u32_e32 vcc, 0, v11
	s_barrier
	v_mul_f32_e32 v11, 0x45800000, v10
	v_cndmask_b32_e64 v12, v10, v11, s[0:1]
	s_and_saveexec_b64 s[0:1], vcc
	s_cbranch_execz .LBB0_1265
	global_store_dword v[84:85], v12, off
